# v20: v19 + remaining K-loop LDS-DMA pieces converted (next-K-tile pieces via saved scalar base + offset:kstep with M0 compensation; vcc bases): no per-piece 64-bit VALU address adds left in 10 K-loops
# speedup vs baseline: 1.0061x; 1.0010x over previous
; #define PG8_STAGE(bufoff, gbase, voff) do { _Pragma("unroll") for (int _i = 0; _i < 2; ++_i) \
;         __builtin_amdgcn_global_load_lds((const unsigned*)((const char*)(gbase) + (voff)[_i]), (PG8_LAS unsigned*)(lds + (bufoff) + ldsw + _i * 8192), 16, 0, 0); } while (0)
; #define PG8_LDA(dst, b, h) do { _Pragma("unroll") for (int m = 0; m < 4; ++m) _Pragma("unroll") for (int k = 0; k < 2; ++k) dst[m][k] = *(const PG8_LAS bf16x8*)(lds + PG8_SA(b, h) + aoff + m * 2048 + k * 1024); } while (0)
; #define PG8_LDB(dst, b, h) do { _Pragma("unroll") for (int n = 0; n < 2; ++n) _Pragma("unroll") for (int k = 0; k < 2; ++k) dst[n][k] = *(const PG8_LAS bf16x8*)(lds + PG8_SB(b, h) + boff + n * 2048 + k * 1024); } while (0)
; #define PG8_MMA(ai, bj, At, Bt) do { __builtin_amdgcn_s_setprio(1); _Pragma("unroll") for (int m = 0; m < 4; ++m) _Pragma("unroll") for (int n = 0; n < 2; ++n) _Pragma("unroll") for (int k = 0; k < 2; ++k) \
;         acc[ai][bj][m][n] = mma_<I8>(Bt[n][k], At[m][k], acc[ai][bj][m][n]); __builtin_amdgcn_s_setprio(0); } while (0)
; #define PG8_WAIT_V(n) asm volatile("s_waitcnt vmcnt(" #n ")" ::: "memory")
; #define PG8_WAIT_L(n) asm volatile("s_waitcnt lgkmcnt(" #n ")" ::: "memory")
; #define PG8_BAR __builtin_amdgcn_s_barrier()
; #define PG8_SCHED __builtin_amdgcn_sched_barrier(0)
; template <class Epi, class Sched, bool ALIGN_EPI = false, bool SP2 = false, bool I8 = false>
; __device__ __forceinline__ void gemm_phase(PG8_LAS unsigned char* lds, const Gemm g, const Sched& S, const Epi& E) {
;     ...
;             const char* a1 = cA + (size_t)(t + 1) * kstep;
;             const char* a2 = last ? nA : cA + (size_t)(t + 2) * kstep; const char* b2 = last ? nB : cB + (size_t)(t + 2) * kstep;
;             const char* a3 = a2 + kstep; const char* b3 = b2 + kstep;
;             if (last && has_next) S.a_ready(nxt);
;             if constexpr (SP2) {
;             PG8_LDB(B0, 0, 0); PG8_LDB(B1, 0, 1); PG8_SCHED; PG8_LDA(At, 0, 0); PG8_STAGE(PG8_SA(1, 1), a1 + hstepA, voffA);
;             PG8_WAIT_V(8); PG8_WAIT_L(0); PG8_BAR; PG8_MMA(0, 0, At, B0); PG8_MMA(0, 1, At, B1); PG8_BAR; PG8_SCHED;
;             PG8_LDA(At, 0, 1); PG8_STAGE(PG8_SB(0, 0), b2, voffB); PG8_STAGE(PG8_SB(0, 1), b2 + hstepB, voffB); PG8_STAGE(PG8_SA(0, 0), a2, voffA);
;             PG8_WAIT_V(8); PG8_WAIT_L(0); PG8_BAR; PG8_MMA(1, 0, At, B0); PG8_MMA(1, 1, At, B1); PG8_BAR; PG8_SCHED;
.LBB0_483:
	ds_read_b128 v[58:61], v187
	ds_read_b128 v[62:65], v187 offset:1024
	ds_read_b128 v[74:77], v187 offset:2048
	ds_read_b128 v[78:81], v187 offset:3072
	ds_read_b128 v[162:165], v188
	ds_read_b128 v[166:169], v188 offset:1024
	ds_read_b128 v[170:173], v188 offset:2048
	ds_read_b128 v[190:193], v188 offset:3072
	s_add_u32 s34, s2, 0xfff80080
	s_addc_u32 s35, s3, -1
	s_cmp_eq_u32 s40, 28
	s_cselect_b32 s37, s7, s35
	s_cselect_b32 s36, s25, s34
	s_cselect_b32 s35, s23, s39
	s_cselect_b32 s34, s33, s38
	s_add_i32 m0, s31, 0xc000
	ds_read_b128 v[194:197], v189
	ds_read_b128 v[198:201], v189 offset:1024
	ds_read_b128 v[202:205], v189 offset:2048
	ds_read_b128 v[206:209], v189 offset:3072
	ds_read_b128 v[210:213], v189 offset:4096
	ds_read_b128 v[214:217], v189 offset:5120
	ds_read_b128 v[218:221], v189 offset:6144
	ds_read_b128 v[222:225], v189 offset:7168
	global_load_lds_dwordx4 v154, s[2:3]
	s_add_i32 m0, s31, 0xe000
	s_nop 0
	global_load_lds_dwordx4 v156, s[2:3]
	s_waitcnt vmcnt(8)
	s_waitcnt lgkmcnt(0)
	s_barrier
	s_waitcnt lgkmcnt(0)
	v_mfma_i32_16x16x64_i8 v[142:145], v[58:61], v[194:197], v[142:145]
	v_mfma_i32_16x16x64_i8 v[138:141], v[74:77], v[194:197], v[138:141]
	v_mfma_i32_16x16x64_i8 v[126:129], v[58:61], v[202:205], v[126:129]
	v_mfma_i32_16x16x64_i8 v[122:125], v[74:77], v[202:205], v[122:125]
	v_mfma_i32_16x16x64_i8 v[110:113], v[58:61], v[210:213], v[110:113]
	v_mfma_i32_16x16x64_i8 v[106:109], v[74:77], v[210:213], v[106:109]
	v_mfma_i32_16x16x64_i8 v[94:97], v[58:61], v[218:221], v[94:97]
	v_mfma_i32_16x16x64_i8 v[90:93], v[74:77], v[218:221], v[90:93]
	v_mfma_i32_16x16x64_i8 v[142:145], v[62:65], v[198:201], v[142:145]
	v_mfma_i32_16x16x64_i8 v[138:141], v[78:81], v[198:201], v[138:141]
	v_mfma_i32_16x16x64_i8 v[126:129], v[62:65], v[206:209], v[126:129]
	v_mfma_i32_16x16x64_i8 v[122:125], v[78:81], v[206:209], v[122:125]
	v_mfma_i32_16x16x64_i8 v[110:113], v[62:65], v[214:217], v[110:113]
	v_mfma_i32_16x16x64_i8 v[106:109], v[78:81], v[214:217], v[106:109]
	v_mfma_i32_16x16x64_i8 v[94:97], v[62:65], v[222:225], v[94:97]
	v_mfma_i32_16x16x64_i8 v[90:93], v[78:81], v[222:225], v[90:93]
	v_mfma_i32_16x16x64_i8 v[134:137], v[162:165], v[194:197], v[134:137]
	v_mfma_i32_16x16x64_i8 v[130:133], v[170:173], v[194:197], v[130:133]
	v_mfma_i32_16x16x64_i8 v[118:121], v[162:165], v[202:205], v[118:121]
	v_mfma_i32_16x16x64_i8 v[114:117], v[170:173], v[202:205], v[114:117]
	v_mfma_i32_16x16x64_i8 v[102:105], v[162:165], v[210:213], v[102:105]
	v_mfma_i32_16x16x64_i8 v[98:101], v[170:173], v[210:213], v[98:101]
	v_mfma_i32_16x16x64_i8 v[86:89], v[162:165], v[218:221], v[86:89]
	v_mfma_i32_16x16x64_i8 v[82:85], v[170:173], v[218:221], v[82:85]
	v_mfma_i32_16x16x64_i8 v[134:137], v[166:169], v[198:201], v[134:137]
	v_mfma_i32_16x16x64_i8 v[130:133], v[190:193], v[198:201], v[130:133]
	v_mfma_i32_16x16x64_i8 v[118:121], v[166:169], v[206:209], v[118:121]
	v_mfma_i32_16x16x64_i8 v[114:117], v[190:193], v[206:209], v[114:117]
	v_mfma_i32_16x16x64_i8 v[102:105], v[166:169], v[214:217], v[102:105]
	v_mfma_i32_16x16x64_i8 v[98:101], v[190:193], v[214:217], v[98:101]
	v_mfma_i32_16x16x64_i8 v[86:89], v[166:169], v[222:225], v[86:89]
	v_mfma_i32_16x16x64_i8 v[82:85], v[190:193], v[222:225], v[82:85]
	s_barrier
	s_add_i32 s41, s8, s68
	s_mov_b64 s[98:99], s[34:35]
	s_mov_b32 m0, s41
	ds_read_b128 v[194:197], v189 offset:16384
	ds_read_b128 v[198:201], v189 offset:17408
	ds_read_b128 v[202:205], v189 offset:18432
	ds_read_b128 v[206:209], v189 offset:19456
	ds_read_b128 v[210:213], v189 offset:20480
	ds_read_b128 v[214:217], v189 offset:21504
	ds_read_b128 v[218:221], v189 offset:22528
	ds_read_b128 v[222:225], v189 offset:23552
	global_load_lds_dwordx4 v148, s[34:35]
	s_add_i32 m0, s41, 0x2000
	s_add_u32 vcc_lo, s34, 0x80000
	s_mov_b64 s[98:99], s[34:35]
	s_addc_u32 vcc_hi, s35, 0
	s_add_i32 s41, s9, s68
	global_load_lds_dwordx4 v152, s[34:35]
	s_mov_b32 m0, s41
	s_mov_b64 s[100:101], s[36:37]
	global_load_lds_dwordx4 v148, vcc
	s_add_i32 m0, s41, 0x2000
	s_nop 0
	global_load_lds_dwordx4 v152, vcc
	s_mov_b64 s[100:101], s[36:37]
	s_mov_b32 m0, s31
	s_nop 0
	global_load_lds_dwordx4 v146, s[36:37]
	s_mov_b32 m0, s69
	s_nop 0
	global_load_lds_dwordx4 v150, s[36:37]
	s_waitcnt vmcnt(8)
	s_waitcnt lgkmcnt(0)
	s_barrier
	s_waitcnt lgkmcnt(0)
	v_mfma_i32_16x16x64_i8 v[70:73], v[58:61], v[194:197], v[70:73]
	v_mfma_i32_16x16x64_i8 v[66:69], v[74:77], v[194:197], v[66:69]
	v_mfma_i32_16x16x64_i8 v[46:49], v[58:61], v[202:205], v[46:49]
	v_mfma_i32_16x16x64_i8 v[42:45], v[74:77], v[202:205], v[42:45]
	v_mfma_i32_16x16x64_i8 v[30:33], v[58:61], v[210:213], v[30:33]
	v_mfma_i32_16x16x64_i8 v[26:29], v[74:77], v[210:213], v[26:29]
	v_mfma_i32_16x16x64_i8 v[14:17], v[58:61], v[218:221], v[14:17]
	v_mfma_i32_16x16x64_i8 v[10:13], v[74:77], v[218:221], v[10:13]
	v_mfma_i32_16x16x64_i8 v[70:73], v[62:65], v[198:201], v[70:73]
	v_mfma_i32_16x16x64_i8 v[66:69], v[78:81], v[198:201], v[66:69]
	v_mfma_i32_16x16x64_i8 v[46:49], v[62:65], v[206:209], v[46:49]
	v_mfma_i32_16x16x64_i8 v[42:45], v[78:81], v[206:209], v[42:45]
	v_mfma_i32_16x16x64_i8 v[30:33], v[62:65], v[214:217], v[30:33]
	v_mfma_i32_16x16x64_i8 v[26:29], v[78:81], v[214:217], v[26:29]
	v_mfma_i32_16x16x64_i8 v[14:17], v[62:65], v[222:225], v[14:17]
	v_mfma_i32_16x16x64_i8 v[10:13], v[78:81], v[222:225], v[10:13]
	v_mfma_i32_16x16x64_i8 v[54:57], v[162:165], v[194:197], v[54:57]
	v_mfma_i32_16x16x64_i8 v[50:53], v[170:173], v[194:197], v[50:53]
	v_mfma_i32_16x16x64_i8 v[38:41], v[162:165], v[202:205], v[38:41]
	v_mfma_i32_16x16x64_i8 v[34:37], v[170:173], v[202:205], v[34:37]
	v_mfma_i32_16x16x64_i8 v[22:25], v[162:165], v[210:213], v[22:25]
	v_mfma_i32_16x16x64_i8 v[18:21], v[170:173], v[210:213], v[18:21]
	v_mfma_i32_16x16x64_i8 v[6:9], v[162:165], v[218:221], v[6:9]
	v_mfma_i32_16x16x64_i8 v[2:5], v[170:173], v[218:221], v[2:5]
	v_mfma_i32_16x16x64_i8 v[54:57], v[166:169], v[198:201], v[54:57]
	v_mfma_i32_16x16x64_i8 v[50:53], v[190:193], v[198:201], v[50:53]
	v_mfma_i32_16x16x64_i8 v[38:41], v[166:169], v[206:209], v[38:41]
	v_mfma_i32_16x16x64_i8 v[34:37], v[190:193], v[206:209], v[34:37]
	v_mfma_i32_16x16x64_i8 v[22:25], v[166:169], v[214:217], v[22:25]
	v_mfma_i32_16x16x64_i8 v[18:21], v[190:193], v[214:217], v[18:21]
	v_mfma_i32_16x16x64_i8 v[6:9], v[166:169], v[222:225], v[6:9]
	v_mfma_i32_16x16x64_i8 v[2:5], v[190:193], v[222:225], v[2:5]
	s_barrier
; #define PG8_STAGE(bufoff, gbase, voff) do { _Pragma("unroll") for (int _i = 0; _i < 2; ++_i) \
;         __builtin_amdgcn_global_load_lds((const unsigned*)((const char*)(gbase) + (voff)[_i]), (PG8_LAS unsigned*)(lds + (bufoff) + ldsw + _i * 8192), 16, 0, 0); } while (0)
; #define PG8_LDA(dst, b, h) do { _Pragma("unroll") for (int m = 0; m < 4; ++m) _Pragma("unroll") for (int k = 0; k < 2; ++k) dst[m][k] = *(const PG8_LAS bf16x8*)(lds + PG8_SA(b, h) + aoff + m * 2048 + k * 1024); } while (0)
; #define PG8_LDB(dst, b, h) do { _Pragma("unroll") for (int n = 0; n < 2; ++n) _Pragma("unroll") for (int k = 0; k < 2; ++k) dst[n][k] = *(const PG8_LAS bf16x8*)(lds + PG8_SB(b, h) + boff + n * 2048 + k * 1024); } while (0)
; #define PG8_MMA(ai, bj, At, Bt) do { __builtin_amdgcn_s_setprio(1); _Pragma("unroll") for (int m = 0; m < 4; ++m) _Pragma("unroll") for (int n = 0; n < 2; ++n) _Pragma("unroll") for (int k = 0; k < 2; ++k) \
;         acc[ai][bj][m][n] = mma_<I8>(Bt[n][k], At[m][k], acc[ai][bj][m][n]); __builtin_amdgcn_s_setprio(0); } while (0)
; #define PG8_WAIT_V(n) asm volatile("s_waitcnt vmcnt(" #n ")" ::: "memory")
; #define PG8_WAIT_L(n) asm volatile("s_waitcnt lgkmcnt(" #n ")" ::: "memory")
; #define PG8_BAR __builtin_amdgcn_s_barrier()
; #define PG8_SCHED __builtin_amdgcn_sched_barrier(0)
; template <class Epi, class Sched, bool ALIGN_EPI = false, bool SP2 = false, bool I8 = false>
; __device__ __forceinline__ void gemm_phase(PG8_LAS unsigned char* lds, const Gemm g, const Sched& S, const Epi& E) {
;     ...
;         for (int t = 0; t < nt; t += 2) {
;             const bool last = (t == nt - 2);
;     ...
;             PG8_LDB(B0, 1, 0); PG8_LDB(B1, 1, 1); PG8_SCHED; PG8_LDA(At, 1, 0); PG8_STAGE(PG8_SA(0, 1), a2 + hstepA, voffA);
;             PG8_WAIT_V(8); PG8_WAIT_L(0); PG8_BAR; PG8_MMA(0, 0, At, B0); PG8_MMA(0, 1, At, B1); PG8_BAR; PG8_SCHED;
;             PG8_LDA(At, 1, 1); PG8_STAGE(PG8_SB(1, 0), b3, voffB); PG8_STAGE(PG8_SB(1, 1), b3 + hstepB, voffB); PG8_STAGE(PG8_SA(1, 0), a3, voffA);
;             PG8_WAIT_V(8); PG8_WAIT_L(0); PG8_BAR; PG8_MMA(1, 0, At, B0); PG8_MMA(1, 1, At, B1); PG8_BAR; PG8_SCHED;
	s_add_i32 s41, 0, 0x18000
	s_add_i32 s95, 0, 0x1c000
	v_add_u32_e32 v78, s41, v181
	v_add_u32_e32 v190, s95, v181
	ds_read_b128 v[58:61], v78
	ds_read_b128 v[62:65], v78 offset:1024
	ds_read_b128 v[74:77], v78 offset:2048
	ds_read_b128 v[78:81], v78 offset:3072
	ds_read_b128 v[162:165], v190
	ds_read_b128 v[166:169], v190 offset:1024
	ds_read_b128 v[170:173], v190 offset:2048
	ds_read_b128 v[190:193], v190 offset:3072
	s_add_u32 s36, s36, 0x80000
	s_addc_u32 s37, s37, 0
	s_mov_b32 m0, s70
	ds_read_b128 v[194:197], v189 offset:32768
	ds_read_b128 v[198:201], v189 offset:33792
	ds_read_b128 v[202:205], v189 offset:34816
	ds_read_b128 v[206:209], v189 offset:35840
	ds_read_b128 v[210:213], v189 offset:36864
	ds_read_b128 v[214:217], v189 offset:37888
	ds_read_b128 v[218:221], v189 offset:38912
	ds_read_b128 v[222:225], v189 offset:39936
	global_load_lds_dwordx4 v146, s[36:37]
	s_mov_b32 m0, s71
	s_nop 0
	global_load_lds_dwordx4 v150, s[36:37]
	s_waitcnt vmcnt(8)
	s_waitcnt lgkmcnt(0)
	s_barrier
	s_waitcnt lgkmcnt(0)
	v_mfma_i32_16x16x64_i8 v[142:145], v[58:61], v[194:197], v[142:145]
	v_mfma_i32_16x16x64_i8 v[138:141], v[74:77], v[194:197], v[138:141]
	v_mfma_i32_16x16x64_i8 v[126:129], v[58:61], v[202:205], v[126:129]
	v_mfma_i32_16x16x64_i8 v[122:125], v[74:77], v[202:205], v[122:125]
	v_mfma_i32_16x16x64_i8 v[110:113], v[58:61], v[210:213], v[110:113]
	v_mfma_i32_16x16x64_i8 v[106:109], v[74:77], v[210:213], v[106:109]
	v_mfma_i32_16x16x64_i8 v[94:97], v[58:61], v[218:221], v[94:97]
	v_mfma_i32_16x16x64_i8 v[90:93], v[74:77], v[218:221], v[90:93]
	v_mfma_i32_16x16x64_i8 v[142:145], v[62:65], v[198:201], v[142:145]
	v_mfma_i32_16x16x64_i8 v[138:141], v[78:81], v[198:201], v[138:141]
	v_mfma_i32_16x16x64_i8 v[126:129], v[62:65], v[206:209], v[126:129]
	v_mfma_i32_16x16x64_i8 v[122:125], v[78:81], v[206:209], v[122:125]
	v_mfma_i32_16x16x64_i8 v[110:113], v[62:65], v[214:217], v[110:113]
	v_mfma_i32_16x16x64_i8 v[106:109], v[78:81], v[214:217], v[106:109]
	v_mfma_i32_16x16x64_i8 v[94:97], v[62:65], v[222:225], v[94:97]
	v_mfma_i32_16x16x64_i8 v[90:93], v[78:81], v[222:225], v[90:93]
	v_mfma_i32_16x16x64_i8 v[134:137], v[162:165], v[194:197], v[134:137]
	v_mfma_i32_16x16x64_i8 v[130:133], v[170:173], v[194:197], v[130:133]
	v_mfma_i32_16x16x64_i8 v[118:121], v[162:165], v[202:205], v[118:121]
	v_mfma_i32_16x16x64_i8 v[114:117], v[170:173], v[202:205], v[114:117]
	v_mfma_i32_16x16x64_i8 v[102:105], v[162:165], v[210:213], v[102:105]
	v_mfma_i32_16x16x64_i8 v[98:101], v[170:173], v[210:213], v[98:101]
	v_mfma_i32_16x16x64_i8 v[86:89], v[162:165], v[218:221], v[86:89]
	v_mfma_i32_16x16x64_i8 v[82:85], v[170:173], v[218:221], v[82:85]
	v_mfma_i32_16x16x64_i8 v[134:137], v[166:169], v[198:201], v[134:137]
	v_mfma_i32_16x16x64_i8 v[130:133], v[190:193], v[198:201], v[130:133]
	v_mfma_i32_16x16x64_i8 v[118:121], v[166:169], v[206:209], v[118:121]
	v_mfma_i32_16x16x64_i8 v[114:117], v[190:193], v[206:209], v[114:117]
	v_mfma_i32_16x16x64_i8 v[102:105], v[166:169], v[214:217], v[102:105]
	v_mfma_i32_16x16x64_i8 v[98:101], v[190:193], v[214:217], v[98:101]
	v_mfma_i32_16x16x64_i8 v[86:89], v[166:169], v[222:225], v[86:89]
	v_mfma_i32_16x16x64_i8 v[82:85], v[190:193], v[222:225], v[82:85]
	s_barrier
	s_add_i32 s36, s41, s68
	s_add_i32 m0, s36, 0xffffff80
	ds_read_b128 v[194:197], v189 offset:49152
	ds_read_b128 v[198:201], v189 offset:50176
	ds_read_b128 v[202:205], v189 offset:51200
	ds_read_b128 v[206:209], v189 offset:52224
	ds_read_b128 v[210:213], v189 offset:53248
	ds_read_b128 v[214:217], v189 offset:54272
	ds_read_b128 v[218:221], v189 offset:55296
	ds_read_b128 v[222:225], v189 offset:56320
	global_load_lds_dwordx4 v148, s[98:99] offset:128
	s_add_i32 m0, s36, 0x1f80
	s_add_u32 s34, s34, 0x80080
	s_addc_u32 s35, s35, 0
	s_add_i32 s36, s95, s68
	global_load_lds_dwordx4 v152, s[98:99] offset:128
	s_mov_b32 m0, s36
	s_nop 0
	global_load_lds_dwordx4 v148, s[34:35]
	s_add_i32 m0, s36, 0x2000
	s_nop 0
	global_load_lds_dwordx4 v152, s[34:35]
	s_add_i32 m0, s89, 0xffffff80
	s_nop 0
	global_load_lds_dwordx4 v146, s[100:101] offset:128
	s_add_i32 m0, s92, 0xffffff80
	s_nop 0
	global_load_lds_dwordx4 v150, s[100:101] offset:128
	s_waitcnt vmcnt(8)
	s_waitcnt lgkmcnt(0)
	s_barrier
	s_waitcnt lgkmcnt(0)
	v_mfma_i32_16x16x64_i8 v[70:73], v[58:61], v[194:197], v[70:73]
	v_mfma_i32_16x16x64_i8 v[66:69], v[74:77], v[194:197], v[66:69]
	v_mfma_i32_16x16x64_i8 v[46:49], v[58:61], v[202:205], v[46:49]
	v_mfma_i32_16x16x64_i8 v[42:45], v[74:77], v[202:205], v[42:45]
	v_mfma_i32_16x16x64_i8 v[30:33], v[58:61], v[210:213], v[30:33]
	v_mfma_i32_16x16x64_i8 v[26:29], v[74:77], v[210:213], v[26:29]
	v_mfma_i32_16x16x64_i8 v[14:17], v[58:61], v[218:221], v[14:17]
	v_mfma_i32_16x16x64_i8 v[10:13], v[74:77], v[218:221], v[10:13]
	v_mfma_i32_16x16x64_i8 v[70:73], v[62:65], v[198:201], v[70:73]
	v_mfma_i32_16x16x64_i8 v[66:69], v[78:81], v[198:201], v[66:69]
	v_mfma_i32_16x16x64_i8 v[46:49], v[62:65], v[206:209], v[46:49]
	v_mfma_i32_16x16x64_i8 v[42:45], v[78:81], v[206:209], v[42:45]
	v_mfma_i32_16x16x64_i8 v[30:33], v[62:65], v[214:217], v[30:33]
	v_mfma_i32_16x16x64_i8 v[26:29], v[78:81], v[214:217], v[26:29]
	v_mfma_i32_16x16x64_i8 v[14:17], v[62:65], v[222:225], v[14:17]
	v_mfma_i32_16x16x64_i8 v[10:13], v[78:81], v[222:225], v[10:13]
	v_mfma_i32_16x16x64_i8 v[54:57], v[162:165], v[194:197], v[54:57]
	v_mfma_i32_16x16x64_i8 v[50:53], v[170:173], v[194:197], v[50:53]
	v_mfma_i32_16x16x64_i8 v[38:41], v[162:165], v[202:205], v[38:41]
	v_mfma_i32_16x16x64_i8 v[34:37], v[170:173], v[202:205], v[34:37]
	v_mfma_i32_16x16x64_i8 v[22:25], v[162:165], v[210:213], v[22:25]
	v_mfma_i32_16x16x64_i8 v[18:21], v[170:173], v[210:213], v[18:21]
	v_mfma_i32_16x16x64_i8 v[6:9], v[162:165], v[218:221], v[6:9]
	v_mfma_i32_16x16x64_i8 v[2:5], v[170:173], v[218:221], v[2:5]
	v_mfma_i32_16x16x64_i8 v[54:57], v[166:169], v[198:201], v[54:57]
	v_mfma_i32_16x16x64_i8 v[50:53], v[190:193], v[198:201], v[50:53]
	v_mfma_i32_16x16x64_i8 v[38:41], v[166:169], v[206:209], v[38:41]
	v_mfma_i32_16x16x64_i8 v[34:37], v[190:193], v[206:209], v[34:37]
	v_mfma_i32_16x16x64_i8 v[22:25], v[166:169], v[214:217], v[22:25]
	v_mfma_i32_16x16x64_i8 v[18:21], v[190:193], v[214:217], v[18:21]
	v_mfma_i32_16x16x64_i8 v[6:9], v[166:169], v[222:225], v[6:9]
	v_mfma_i32_16x16x64_i8 v[2:5], v[190:193], v[222:225], v[2:5]
	s_barrier
	s_add_i32 s40, s40, 2
	s_add_u32 s2, s2, 0x100
	s_addc_u32 s3, s3, 0
	s_add_u32 s38, s38, 0x100
	s_addc_u32 s39, s39, 0
	s_cmp_gt_u32 s40, 29
	s_cbranch_scc0 .LBB0_483
	s_and_b64 vcc, exec, s[20:21]
	s_cbranch_vccz .LBB0_486
	s_barrier

; #define PG8_STAGE(bufoff, gbase, voff) do { _Pragma("unroll") for (int _i = 0; _i < 2; ++_i) \
;         __builtin_amdgcn_global_load_lds((const unsigned*)((const char*)(gbase) + (voff)[_i]), (PG8_LAS unsigned*)(lds + (bufoff) + ldsw + _i * 8192), 16, 0, 0); } while (0)
; #define PG8_LDA(dst, b, h) do { _Pragma("unroll") for (int m = 0; m < 4; ++m) _Pragma("unroll") for (int k = 0; k < 2; ++k) dst[m][k] = *(const PG8_LAS bf16x8*)(lds + PG8_SA(b, h) + aoff + m * 2048 + k * 1024); } while (0)
; #define PG8_LDB(dst, b, h) do { _Pragma("unroll") for (int n = 0; n < 2; ++n) _Pragma("unroll") for (int k = 0; k < 2; ++k) dst[n][k] = *(const PG8_LAS bf16x8*)(lds + PG8_SB(b, h) + boff + n * 2048 + k * 1024); } while (0)
; #define PG8_MMA(ai, bj, At, Bt) do { __builtin_amdgcn_s_setprio(1); _Pragma("unroll") for (int m = 0; m < 4; ++m) _Pragma("unroll") for (int n = 0; n < 2; ++n) _Pragma("unroll") for (int k = 0; k < 2; ++k) \
;         acc[ai][bj][m][n] = mma_<I8>(Bt[n][k], At[m][k], acc[ai][bj][m][n]); __builtin_amdgcn_s_setprio(0); } while (0)
; #define PG8_WAIT_V(n) asm volatile("s_waitcnt vmcnt(" #n ")" ::: "memory")
; #define PG8_WAIT_L(n) asm volatile("s_waitcnt lgkmcnt(" #n ")" ::: "memory")
; #define PG8_BAR __builtin_amdgcn_s_barrier()
; #define PG8_SCHED __builtin_amdgcn_sched_barrier(0)
; template <class Epi, class Sched, bool ALIGN_EPI = false, bool SP2 = false, bool I8 = false>
; __device__ __forceinline__ void gemm_phase(PG8_LAS unsigned char* lds, const Gemm g, const Sched& S, const Epi& E) {
;     ...
;             const char* a1 = cA + (size_t)(t + 1) * kstep;
;             const char* a2 = last ? nA : cA + (size_t)(t + 2) * kstep; const char* b2 = last ? nB : cB + (size_t)(t + 2) * kstep;
;             const char* a3 = a2 + kstep; const char* b3 = b2 + kstep;
;             if (last && has_next) S.a_ready(nxt);
;             if constexpr (SP2) {
;             PG8_LDB(B0, 0, 0); PG8_LDB(B1, 0, 1); PG8_SCHED; PG8_LDA(At, 0, 0); PG8_STAGE(PG8_SA(1, 1), a1 + hstepA, voffA);
;             PG8_WAIT_V(8); PG8_WAIT_L(0); PG8_BAR; PG8_MMA(0, 0, At, B0); PG8_MMA(0, 1, At, B1); PG8_BAR; PG8_SCHED;
;             PG8_LDA(At, 0, 1); PG8_STAGE(PG8_SB(0, 0), b2, voffB); PG8_STAGE(PG8_SB(0, 1), b2 + hstepB, voffB); PG8_STAGE(PG8_SA(0, 0), a2, voffA);
;             PG8_WAIT_V(8); PG8_WAIT_L(0); PG8_BAR; PG8_MMA(1, 0, At, B0); PG8_MMA(1, 1, At, B1); PG8_BAR; PG8_SCHED;
.LBB0_541:
	ds_read_b128 v[154:157], v149
	ds_read_b128 v[158:161], v149 offset:1024
	ds_read_b128 v[162:165], v149 offset:2048
	ds_read_b128 v[166:169], v149 offset:3072
	ds_read_b128 v[170:173], v151
	ds_read_b128 v[174:177], v151 offset:1024
	ds_read_b128 v[178:181], v151 offset:2048
	ds_read_b128 v[188:191], v151 offset:3072
	s_add_u32 s34, s30, 0xfff00080
	s_addc_u32 s35, s31, -1
	s_cmp_eq_u32 s94, 60
	s_cselect_b32 s37, s7, s35
	s_cselect_b32 s36, s25, s34
	s_cselect_b32 s35, s23, s93
	s_cselect_b32 s34, s29, s92
	s_add_i32 m0, s39, 0xc000
	ds_read_b128 v[192:195], v153
	ds_read_b128 v[196:199], v153 offset:1024
	ds_read_b128 v[200:203], v153 offset:2048
	ds_read_b128 v[204:207], v153 offset:3072
	ds_read_b128 v[208:211], v153 offset:4096
	ds_read_b128 v[212:215], v153 offset:5120
	ds_read_b128 v[216:219], v153 offset:6144
	ds_read_b128 v[220:223], v153 offset:7168
	global_load_lds_dwordx4 v138, s[30:31]
	s_add_i32 m0, s39, 0xe000
	s_nop 0
	global_load_lds_dwordx4 v140, s[30:31]
	s_waitcnt vmcnt(8)
	s_waitcnt lgkmcnt(0)
	s_barrier
	s_waitcnt lgkmcnt(0)
	v_mfma_f32_16x16x32_bf16 v[126:129], v[154:157], v[192:195], v[126:129]
	v_mfma_f32_16x16x32_bf16 v[122:125], v[162:165], v[192:195], v[122:125]
	v_mfma_f32_16x16x32_bf16 v[110:113], v[154:157], v[200:203], v[110:113]
	v_mfma_f32_16x16x32_bf16 v[106:109], v[162:165], v[200:203], v[106:109]
	v_mfma_f32_16x16x32_bf16 v[94:97], v[154:157], v[208:211], v[94:97]
	v_mfma_f32_16x16x32_bf16 v[90:93], v[162:165], v[208:211], v[90:93]
	v_mfma_f32_16x16x32_bf16 v[78:81], v[154:157], v[216:219], v[78:81]
	v_mfma_f32_16x16x32_bf16 v[74:77], v[162:165], v[216:219], v[74:77]
	v_mfma_f32_16x16x32_bf16 v[126:129], v[158:161], v[196:199], v[126:129]
	v_mfma_f32_16x16x32_bf16 v[122:125], v[166:169], v[196:199], v[122:125]
	v_mfma_f32_16x16x32_bf16 v[110:113], v[158:161], v[204:207], v[110:113]
	v_mfma_f32_16x16x32_bf16 v[106:109], v[166:169], v[204:207], v[106:109]
	v_mfma_f32_16x16x32_bf16 v[94:97], v[158:161], v[212:215], v[94:97]
	v_mfma_f32_16x16x32_bf16 v[90:93], v[166:169], v[212:215], v[90:93]
	v_mfma_f32_16x16x32_bf16 v[78:81], v[158:161], v[220:223], v[78:81]
	v_mfma_f32_16x16x32_bf16 v[74:77], v[166:169], v[220:223], v[74:77]
	v_mfma_f32_16x16x32_bf16 v[118:121], v[170:173], v[192:195], v[118:121]
	v_mfma_f32_16x16x32_bf16 v[114:117], v[178:181], v[192:195], v[114:117]
	v_mfma_f32_16x16x32_bf16 v[102:105], v[170:173], v[200:203], v[102:105]
	v_mfma_f32_16x16x32_bf16 v[98:101], v[178:181], v[200:203], v[98:101]
	v_mfma_f32_16x16x32_bf16 v[86:89], v[170:173], v[208:211], v[86:89]
	v_mfma_f32_16x16x32_bf16 v[82:85], v[178:181], v[208:211], v[82:85]
	v_mfma_f32_16x16x32_bf16 v[70:73], v[170:173], v[216:219], v[70:73]
	v_mfma_f32_16x16x32_bf16 v[66:69], v[178:181], v[216:219], v[66:69]
	v_mfma_f32_16x16x32_bf16 v[118:121], v[174:177], v[196:199], v[118:121]
	v_mfma_f32_16x16x32_bf16 v[114:117], v[188:191], v[196:199], v[114:117]
	v_mfma_f32_16x16x32_bf16 v[102:105], v[174:177], v[204:207], v[102:105]
	v_mfma_f32_16x16x32_bf16 v[98:101], v[188:191], v[204:207], v[98:101]
	v_mfma_f32_16x16x32_bf16 v[86:89], v[174:177], v[212:215], v[86:89]
	v_mfma_f32_16x16x32_bf16 v[82:85], v[188:191], v[212:215], v[82:85]
	v_mfma_f32_16x16x32_bf16 v[70:73], v[174:177], v[220:223], v[70:73]
	v_mfma_f32_16x16x32_bf16 v[66:69], v[188:191], v[220:223], v[66:69]
	s_barrier
	s_add_i32 s95, s88, s38
	s_mov_b64 s[98:99], s[34:35]
	s_mov_b32 m0, s95
	ds_read_b128 v[192:195], v153 offset:16384
	ds_read_b128 v[196:199], v153 offset:17408
	ds_read_b128 v[200:203], v153 offset:18432
	ds_read_b128 v[204:207], v153 offset:19456
	ds_read_b128 v[208:211], v153 offset:20480
	ds_read_b128 v[212:215], v153 offset:21504
	ds_read_b128 v[216:219], v153 offset:22528
	ds_read_b128 v[220:223], v153 offset:23552
	global_load_lds_dwordx4 v132, s[34:35]
	s_add_i32 m0, s95, 0x2000
	s_add_u32 vcc_lo, s34, 0x100000
	s_mov_b64 s[98:99], s[34:35]
	s_addc_u32 vcc_hi, s35, 0
	s_add_i32 s95, s89, s38
	global_load_lds_dwordx4 v136, s[34:35]
	s_mov_b32 m0, s95
	s_mov_b64 s[100:101], s[36:37]
	global_load_lds_dwordx4 v132, vcc
	s_add_i32 m0, s95, 0x2000
	s_nop 0
	global_load_lds_dwordx4 v136, vcc
	s_mov_b64 s[100:101], s[36:37]
	s_mov_b32 m0, s39
	s_nop 0
	global_load_lds_dwordx4 v130, s[36:37]
	s_mov_b32 m0, s40
	s_nop 0
	global_load_lds_dwordx4 v134, s[36:37]
	s_waitcnt vmcnt(8)
	s_waitcnt lgkmcnt(0)
	s_barrier
	s_waitcnt lgkmcnt(0)
	v_mfma_f32_16x16x32_bf16 v[62:65], v[154:157], v[192:195], v[62:65]
	v_mfma_f32_16x16x32_bf16 v[58:61], v[162:165], v[192:195], v[58:61]
	v_mfma_f32_16x16x32_bf16 v[46:49], v[154:157], v[200:203], v[46:49]
	v_mfma_f32_16x16x32_bf16 v[42:45], v[162:165], v[200:203], v[42:45]
	v_mfma_f32_16x16x32_bf16 v[30:33], v[154:157], v[208:211], v[30:33]
	v_mfma_f32_16x16x32_bf16 v[26:29], v[162:165], v[208:211], v[26:29]
	v_mfma_f32_16x16x32_bf16 v[14:17], v[154:157], v[216:219], v[14:17]
	v_mfma_f32_16x16x32_bf16 v[10:13], v[162:165], v[216:219], v[10:13]
	v_mfma_f32_16x16x32_bf16 v[62:65], v[158:161], v[196:199], v[62:65]
	v_mfma_f32_16x16x32_bf16 v[58:61], v[166:169], v[196:199], v[58:61]
	v_mfma_f32_16x16x32_bf16 v[46:49], v[158:161], v[204:207], v[46:49]
	v_mfma_f32_16x16x32_bf16 v[42:45], v[166:169], v[204:207], v[42:45]
	v_mfma_f32_16x16x32_bf16 v[30:33], v[158:161], v[212:215], v[30:33]
	v_mfma_f32_16x16x32_bf16 v[26:29], v[166:169], v[212:215], v[26:29]
	v_mfma_f32_16x16x32_bf16 v[14:17], v[158:161], v[220:223], v[14:17]
	v_mfma_f32_16x16x32_bf16 v[10:13], v[166:169], v[220:223], v[10:13]
	v_mfma_f32_16x16x32_bf16 v[54:57], v[170:173], v[192:195], v[54:57]
	v_mfma_f32_16x16x32_bf16 v[50:53], v[178:181], v[192:195], v[50:53]
	v_mfma_f32_16x16x32_bf16 v[38:41], v[170:173], v[200:203], v[38:41]
	v_mfma_f32_16x16x32_bf16 v[34:37], v[178:181], v[200:203], v[34:37]
	v_mfma_f32_16x16x32_bf16 v[22:25], v[170:173], v[208:211], v[22:25]
	v_mfma_f32_16x16x32_bf16 v[18:21], v[178:181], v[208:211], v[18:21]
	v_mfma_f32_16x16x32_bf16 v[6:9], v[170:173], v[216:219], v[6:9]
	v_mfma_f32_16x16x32_bf16 v[2:5], v[178:181], v[216:219], v[2:5]
	v_mfma_f32_16x16x32_bf16 v[54:57], v[174:177], v[196:199], v[54:57]
	v_mfma_f32_16x16x32_bf16 v[50:53], v[188:191], v[196:199], v[50:53]
	v_mfma_f32_16x16x32_bf16 v[38:41], v[174:177], v[204:207], v[38:41]
	v_mfma_f32_16x16x32_bf16 v[34:37], v[188:191], v[204:207], v[34:37]
	v_mfma_f32_16x16x32_bf16 v[22:25], v[174:177], v[212:215], v[22:25]
	v_mfma_f32_16x16x32_bf16 v[18:21], v[188:191], v[212:215], v[18:21]
	v_mfma_f32_16x16x32_bf16 v[6:9], v[174:177], v[220:223], v[6:9]
	v_mfma_f32_16x16x32_bf16 v[2:5], v[188:191], v[220:223], v[2:5]
	s_barrier
; #define PG8_STAGE(bufoff, gbase, voff) do { _Pragma("unroll") for (int _i = 0; _i < 2; ++_i) \
;         __builtin_amdgcn_global_load_lds((const unsigned*)((const char*)(gbase) + (voff)[_i]), (PG8_LAS unsigned*)(lds + (bufoff) + ldsw + _i * 8192), 16, 0, 0); } while (0)
; #define PG8_LDA(dst, b, h) do { _Pragma("unroll") for (int m = 0; m < 4; ++m) _Pragma("unroll") for (int k = 0; k < 2; ++k) dst[m][k] = *(const PG8_LAS bf16x8*)(lds + PG8_SA(b, h) + aoff + m * 2048 + k * 1024); } while (0)
; #define PG8_LDB(dst, b, h) do { _Pragma("unroll") for (int n = 0; n < 2; ++n) _Pragma("unroll") for (int k = 0; k < 2; ++k) dst[n][k] = *(const PG8_LAS bf16x8*)(lds + PG8_SB(b, h) + boff + n * 2048 + k * 1024); } while (0)
; #define PG8_MMA(ai, bj, At, Bt) do { __builtin_amdgcn_s_setprio(1); _Pragma("unroll") for (int m = 0; m < 4; ++m) _Pragma("unroll") for (int n = 0; n < 2; ++n) _Pragma("unroll") for (int k = 0; k < 2; ++k) \
;         acc[ai][bj][m][n] = mma_<I8>(Bt[n][k], At[m][k], acc[ai][bj][m][n]); __builtin_amdgcn_s_setprio(0); } while (0)
; #define PG8_WAIT_V(n) asm volatile("s_waitcnt vmcnt(" #n ")" ::: "memory")
; #define PG8_WAIT_L(n) asm volatile("s_waitcnt lgkmcnt(" #n ")" ::: "memory")
; #define PG8_BAR __builtin_amdgcn_s_barrier()
; #define PG8_SCHED __builtin_amdgcn_sched_barrier(0)
; template <class Epi, class Sched, bool ALIGN_EPI = false, bool SP2 = false, bool I8 = false>
; __device__ __forceinline__ void gemm_phase(PG8_LAS unsigned char* lds, const Gemm g, const Sched& S, const Epi& E) {
;     ...
;         for (int t = 0; t < nt; t += 2) {
;             const bool last = (t == nt - 2);
;     ...
;             PG8_LDB(B0, 1, 0); PG8_LDB(B1, 1, 1); PG8_SCHED; PG8_LDA(At, 1, 0); PG8_STAGE(PG8_SA(0, 1), a2 + hstepA, voffA);
;             PG8_WAIT_V(8); PG8_WAIT_L(0); PG8_BAR; PG8_MMA(0, 0, At, B0); PG8_MMA(0, 1, At, B1); PG8_BAR; PG8_SCHED;
;             PG8_LDA(At, 1, 1); PG8_STAGE(PG8_SB(1, 0), b3, voffB); PG8_STAGE(PG8_SB(1, 1), b3 + hstepB, voffB); PG8_STAGE(PG8_SA(1, 0), a3, voffA);
;             PG8_WAIT_V(8); PG8_WAIT_L(0); PG8_BAR; PG8_MMA(1, 0, At, B0); PG8_MMA(1, 1, At, B1); PG8_BAR; PG8_SCHED;
	s_add_i32 s95, 0, 0x18000
	s_add_i32 vcc_lo, 0, 0x1c000
	v_add_u32_e32 v166, s95, v147
	v_add_u32_e32 v187, vcc_lo, v147
	ds_read_b128 v[154:157], v166
	ds_read_b128 v[158:161], v166 offset:1024
	ds_read_b128 v[162:165], v166 offset:2048
	ds_read_b128 v[166:169], v166 offset:3072
	ds_read_b128 v[170:173], v187
	ds_read_b128 v[174:177], v187 offset:1024
	ds_read_b128 v[178:181], v187 offset:2048
	ds_read_b128 v[188:191], v187 offset:3072
	s_add_u32 s36, s36, 0x100000
	s_addc_u32 s37, s37, 0
	s_mov_b32 m0, s41
	ds_read_b128 v[192:195], v153 offset:32768
	ds_read_b128 v[196:199], v153 offset:33792
	ds_read_b128 v[200:203], v153 offset:34816
	ds_read_b128 v[204:207], v153 offset:35840
	ds_read_b128 v[208:211], v153 offset:36864
	ds_read_b128 v[212:215], v153 offset:37888
	ds_read_b128 v[216:219], v153 offset:38912
	ds_read_b128 v[220:223], v153 offset:39936
	global_load_lds_dwordx4 v130, s[36:37]
	s_mov_b32 m0, s46
	s_nop 0
	global_load_lds_dwordx4 v134, s[36:37]
	s_waitcnt vmcnt(8)
	s_waitcnt lgkmcnt(0)
	s_barrier
	s_waitcnt lgkmcnt(0)
	v_mfma_f32_16x16x32_bf16 v[126:129], v[154:157], v[192:195], v[126:129]
	v_mfma_f32_16x16x32_bf16 v[122:125], v[162:165], v[192:195], v[122:125]
	v_mfma_f32_16x16x32_bf16 v[110:113], v[154:157], v[200:203], v[110:113]
	v_mfma_f32_16x16x32_bf16 v[106:109], v[162:165], v[200:203], v[106:109]
	v_mfma_f32_16x16x32_bf16 v[94:97], v[154:157], v[208:211], v[94:97]
	v_mfma_f32_16x16x32_bf16 v[90:93], v[162:165], v[208:211], v[90:93]
	v_mfma_f32_16x16x32_bf16 v[78:81], v[154:157], v[216:219], v[78:81]
	v_mfma_f32_16x16x32_bf16 v[74:77], v[162:165], v[216:219], v[74:77]
	v_mfma_f32_16x16x32_bf16 v[126:129], v[158:161], v[196:199], v[126:129]
	v_mfma_f32_16x16x32_bf16 v[122:125], v[166:169], v[196:199], v[122:125]
	v_mfma_f32_16x16x32_bf16 v[110:113], v[158:161], v[204:207], v[110:113]
	v_mfma_f32_16x16x32_bf16 v[106:109], v[166:169], v[204:207], v[106:109]
	v_mfma_f32_16x16x32_bf16 v[94:97], v[158:161], v[212:215], v[94:97]
	v_mfma_f32_16x16x32_bf16 v[90:93], v[166:169], v[212:215], v[90:93]
	v_mfma_f32_16x16x32_bf16 v[78:81], v[158:161], v[220:223], v[78:81]
	v_mfma_f32_16x16x32_bf16 v[74:77], v[166:169], v[220:223], v[74:77]
	v_mfma_f32_16x16x32_bf16 v[118:121], v[170:173], v[192:195], v[118:121]
	v_mfma_f32_16x16x32_bf16 v[114:117], v[178:181], v[192:195], v[114:117]
	v_mfma_f32_16x16x32_bf16 v[102:105], v[170:173], v[200:203], v[102:105]
	v_mfma_f32_16x16x32_bf16 v[98:101], v[178:181], v[200:203], v[98:101]
	v_mfma_f32_16x16x32_bf16 v[86:89], v[170:173], v[208:211], v[86:89]
	v_mfma_f32_16x16x32_bf16 v[82:85], v[178:181], v[208:211], v[82:85]
	v_mfma_f32_16x16x32_bf16 v[70:73], v[170:173], v[216:219], v[70:73]
	v_mfma_f32_16x16x32_bf16 v[66:69], v[178:181], v[216:219], v[66:69]
	v_mfma_f32_16x16x32_bf16 v[118:121], v[174:177], v[196:199], v[118:121]
	v_mfma_f32_16x16x32_bf16 v[114:117], v[188:191], v[196:199], v[114:117]
	v_mfma_f32_16x16x32_bf16 v[102:105], v[174:177], v[204:207], v[102:105]
	v_mfma_f32_16x16x32_bf16 v[98:101], v[188:191], v[204:207], v[98:101]
	v_mfma_f32_16x16x32_bf16 v[86:89], v[174:177], v[212:215], v[86:89]
	v_mfma_f32_16x16x32_bf16 v[82:85], v[188:191], v[212:215], v[82:85]
	v_mfma_f32_16x16x32_bf16 v[70:73], v[174:177], v[220:223], v[70:73]
	v_mfma_f32_16x16x32_bf16 v[66:69], v[188:191], v[220:223], v[66:69]
	s_barrier
	s_add_i32 s36, s95, s38
	s_add_i32 m0, s36, 0xffffff80
	ds_read_b128 v[192:195], v153 offset:49152
	ds_read_b128 v[196:199], v153 offset:50176
	ds_read_b128 v[200:203], v153 offset:51200
	ds_read_b128 v[204:207], v153 offset:52224
	ds_read_b128 v[208:211], v153 offset:53248
	ds_read_b128 v[212:215], v153 offset:54272
	ds_read_b128 v[216:219], v153 offset:55296
	ds_read_b128 v[220:223], v153 offset:56320
	global_load_lds_dwordx4 v132, s[98:99] offset:128
	s_add_i32 m0, s36, 0x1f80
	s_add_u32 s34, s34, 0x100080
	s_addc_u32 s35, s35, 0
	s_add_i32 s36, vcc_lo, s38
	global_load_lds_dwordx4 v136, s[98:99] offset:128
	s_mov_b32 m0, s36
	s_nop 0
	global_load_lds_dwordx4 v132, s[34:35]
	s_add_i32 m0, s36, 0x2000
	s_nop 0
	global_load_lds_dwordx4 v136, s[34:35]
	s_add_i32 m0, s68, 0xffffff80
	s_nop 0
	global_load_lds_dwordx4 v130, s[100:101] offset:128
	s_add_i32 m0, s69, 0xffffff80
	s_nop 0
	global_load_lds_dwordx4 v134, s[100:101] offset:128
	s_waitcnt vmcnt(8)
	s_waitcnt lgkmcnt(0)
	s_barrier
	s_waitcnt lgkmcnt(0)
	v_mfma_f32_16x16x32_bf16 v[62:65], v[154:157], v[192:195], v[62:65]
	v_mfma_f32_16x16x32_bf16 v[58:61], v[162:165], v[192:195], v[58:61]
	v_mfma_f32_16x16x32_bf16 v[46:49], v[154:157], v[200:203], v[46:49]
	v_mfma_f32_16x16x32_bf16 v[42:45], v[162:165], v[200:203], v[42:45]
	v_mfma_f32_16x16x32_bf16 v[30:33], v[154:157], v[208:211], v[30:33]
	v_mfma_f32_16x16x32_bf16 v[26:29], v[162:165], v[208:211], v[26:29]
	v_mfma_f32_16x16x32_bf16 v[14:17], v[154:157], v[216:219], v[14:17]
	v_mfma_f32_16x16x32_bf16 v[10:13], v[162:165], v[216:219], v[10:13]
	v_mfma_f32_16x16x32_bf16 v[62:65], v[158:161], v[196:199], v[62:65]
	v_mfma_f32_16x16x32_bf16 v[58:61], v[166:169], v[196:199], v[58:61]
	v_mfma_f32_16x16x32_bf16 v[46:49], v[158:161], v[204:207], v[46:49]
	v_mfma_f32_16x16x32_bf16 v[42:45], v[166:169], v[204:207], v[42:45]
	v_mfma_f32_16x16x32_bf16 v[30:33], v[158:161], v[212:215], v[30:33]
	v_mfma_f32_16x16x32_bf16 v[26:29], v[166:169], v[212:215], v[26:29]
	v_mfma_f32_16x16x32_bf16 v[14:17], v[158:161], v[220:223], v[14:17]
	v_mfma_f32_16x16x32_bf16 v[10:13], v[166:169], v[220:223], v[10:13]
	v_mfma_f32_16x16x32_bf16 v[54:57], v[170:173], v[192:195], v[54:57]
	v_mfma_f32_16x16x32_bf16 v[50:53], v[178:181], v[192:195], v[50:53]
	v_mfma_f32_16x16x32_bf16 v[38:41], v[170:173], v[200:203], v[38:41]
	v_mfma_f32_16x16x32_bf16 v[34:37], v[178:181], v[200:203], v[34:37]
	v_mfma_f32_16x16x32_bf16 v[22:25], v[170:173], v[208:211], v[22:25]
	v_mfma_f32_16x16x32_bf16 v[18:21], v[178:181], v[208:211], v[18:21]
	v_mfma_f32_16x16x32_bf16 v[6:9], v[170:173], v[216:219], v[6:9]
	v_mfma_f32_16x16x32_bf16 v[2:5], v[178:181], v[216:219], v[2:5]
	v_mfma_f32_16x16x32_bf16 v[54:57], v[174:177], v[196:199], v[54:57]
	v_mfma_f32_16x16x32_bf16 v[50:53], v[188:191], v[196:199], v[50:53]
	v_mfma_f32_16x16x32_bf16 v[38:41], v[174:177], v[204:207], v[38:41]
	v_mfma_f32_16x16x32_bf16 v[34:37], v[188:191], v[204:207], v[34:37]
	v_mfma_f32_16x16x32_bf16 v[22:25], v[174:177], v[212:215], v[22:25]
	v_mfma_f32_16x16x32_bf16 v[18:21], v[188:191], v[212:215], v[18:21]
	v_mfma_f32_16x16x32_bf16 v[6:9], v[174:177], v[220:223], v[6:9]
	v_mfma_f32_16x16x32_bf16 v[2:5], v[188:191], v[220:223], v[2:5]
	s_barrier
	s_add_i32 s94, s94, 2
	s_add_u32 s30, s30, 0x100
	s_addc_u32 s31, s31, 0
	s_add_u32 s92, s92, 0x100
	s_addc_u32 s93, s93, 0
	s_cmp_gt_u32 s94, 61
	s_cbranch_scc0 .LBB0_541
	s_and_b64 vcc, exec, s[20:21]
	s_cbranch_vccz .LBB0_544
	s_barrier

; #define PG8_STAGE(bufoff, gbase, voff) do { _Pragma("unroll") for (int _i = 0; _i < 2; ++_i) \
;         __builtin_amdgcn_global_load_lds((const unsigned*)((const char*)(gbase) + (voff)[_i]), (PG8_LAS unsigned*)(lds + (bufoff) + ldsw + _i * 8192), 16, 0, 0); } while (0)
; #define PG8_LDA(dst, b, h) do { _Pragma("unroll") for (int m = 0; m < 4; ++m) _Pragma("unroll") for (int k = 0; k < 2; ++k) dst[m][k] = *(const PG8_LAS bf16x8*)(lds + PG8_SA(b, h) + aoff + m * 2048 + k * 1024); } while (0)
; #define PG8_LDB(dst, b, h) do { _Pragma("unroll") for (int n = 0; n < 2; ++n) _Pragma("unroll") for (int k = 0; k < 2; ++k) dst[n][k] = *(const PG8_LAS bf16x8*)(lds + PG8_SB(b, h) + boff + n * 2048 + k * 1024); } while (0)
; #define PG8_MMA(ai, bj, At, Bt) do { __builtin_amdgcn_s_setprio(1); _Pragma("unroll") for (int m = 0; m < 4; ++m) _Pragma("unroll") for (int n = 0; n < 2; ++n) _Pragma("unroll") for (int k = 0; k < 2; ++k) \
;         acc[ai][bj][m][n] = mma_<I8>(Bt[n][k], At[m][k], acc[ai][bj][m][n]); __builtin_amdgcn_s_setprio(0); } while (0)
; #define PG8_WAIT_V(n) asm volatile("s_waitcnt vmcnt(" #n ")" ::: "memory")
; #define PG8_WAIT_L(n) asm volatile("s_waitcnt lgkmcnt(" #n ")" ::: "memory")
; #define PG8_BAR __builtin_amdgcn_s_barrier()
; #define PG8_SCHED __builtin_amdgcn_sched_barrier(0)
; template <class Epi, class Sched, bool ALIGN_EPI = false, bool SP2 = false, bool I8 = false>
; __device__ __forceinline__ void gemm_phase(PG8_LAS unsigned char* lds, const Gemm g, const Sched& S, const Epi& E) {
;     ...
;             const char* a1 = cA + (size_t)(t + 1) * kstep;
;             const char* a2 = last ? nA : cA + (size_t)(t + 2) * kstep; const char* b2 = last ? nB : cB + (size_t)(t + 2) * kstep;
;             const char* a3 = a2 + kstep; const char* b3 = b2 + kstep;
;             if (last && has_next) S.a_ready(nxt);
;             if constexpr (SP2) {
;             PG8_LDB(B0, 0, 0); PG8_LDB(B1, 0, 1); PG8_SCHED; PG8_LDA(At, 0, 0); PG8_STAGE(PG8_SA(1, 1), a1 + hstepA, voffA);
;             PG8_WAIT_V(8); PG8_WAIT_L(0); PG8_BAR; PG8_MMA(0, 0, At, B0); PG8_MMA(0, 1, At, B1); PG8_BAR; PG8_SCHED;
;             PG8_LDA(At, 0, 1); PG8_STAGE(PG8_SB(0, 0), b2, voffB); PG8_STAGE(PG8_SB(0, 1), b2 + hstepB, voffB); PG8_STAGE(PG8_SA(0, 0), a2, voffA);
;             PG8_WAIT_V(8); PG8_WAIT_L(0); PG8_BAR; PG8_MMA(1, 0, At, B0); PG8_MMA(1, 1, At, B1); PG8_BAR; PG8_SCHED;
.LBB0_607:
	ds_read_b128 v[58:61], v177
	ds_read_b128 v[62:65], v177 offset:1024
	ds_read_b128 v[74:77], v177 offset:2048
	ds_read_b128 v[78:81], v177 offset:3072
	ds_read_b128 v[162:165], v178
	ds_read_b128 v[166:169], v178 offset:1024
	ds_read_b128 v[170:173], v178 offset:2048
	ds_read_b128 v[180:183], v178 offset:3072
	s_add_u32 s34, s2, 0xfff80080
	s_addc_u32 s35, s3, -1
	s_cmp_eq_u32 s39, 28
	s_cselect_b32 s37, s7, s35
	s_cselect_b32 s36, s9, s34
	s_cselect_b32 s35, s23, s38
	s_cselect_b32 s34, s25, s31
	s_add_i32 m0, s69, 0xc000
	ds_read_b128 v[184:187], v179
	ds_read_b128 v[188:191], v179 offset:1024
	ds_read_b128 v[192:195], v179 offset:2048
	ds_read_b128 v[196:199], v179 offset:3072
	ds_read_b128 v[200:203], v179 offset:4096
	ds_read_b128 v[204:207], v179 offset:5120
	ds_read_b128 v[208:211], v179 offset:6144
	ds_read_b128 v[212:215], v179 offset:7168
	global_load_lds_dwordx4 v154, s[2:3]
	s_add_i32 m0, s69, 0xe000
	s_nop 0
	global_load_lds_dwordx4 v156, s[2:3]
	s_waitcnt vmcnt(8)
	s_waitcnt lgkmcnt(0)
	s_barrier
	s_waitcnt lgkmcnt(0)
	v_mfma_i32_16x16x64_i8 v[142:145], v[58:61], v[184:187], v[142:145]
	v_mfma_i32_16x16x64_i8 v[138:141], v[74:77], v[184:187], v[138:141]
	v_mfma_i32_16x16x64_i8 v[126:129], v[58:61], v[192:195], v[126:129]
	v_mfma_i32_16x16x64_i8 v[122:125], v[74:77], v[192:195], v[122:125]
	v_mfma_i32_16x16x64_i8 v[110:113], v[58:61], v[200:203], v[110:113]
	v_mfma_i32_16x16x64_i8 v[106:109], v[74:77], v[200:203], v[106:109]
	v_mfma_i32_16x16x64_i8 v[94:97], v[58:61], v[208:211], v[94:97]
	v_mfma_i32_16x16x64_i8 v[90:93], v[74:77], v[208:211], v[90:93]
	v_mfma_i32_16x16x64_i8 v[142:145], v[62:65], v[188:191], v[142:145]
	v_mfma_i32_16x16x64_i8 v[138:141], v[78:81], v[188:191], v[138:141]
	v_mfma_i32_16x16x64_i8 v[126:129], v[62:65], v[196:199], v[126:129]
	v_mfma_i32_16x16x64_i8 v[122:125], v[78:81], v[196:199], v[122:125]
	v_mfma_i32_16x16x64_i8 v[110:113], v[62:65], v[204:207], v[110:113]
	v_mfma_i32_16x16x64_i8 v[106:109], v[78:81], v[204:207], v[106:109]
	v_mfma_i32_16x16x64_i8 v[94:97], v[62:65], v[212:215], v[94:97]
	v_mfma_i32_16x16x64_i8 v[90:93], v[78:81], v[212:215], v[90:93]
	v_mfma_i32_16x16x64_i8 v[134:137], v[162:165], v[184:187], v[134:137]
	v_mfma_i32_16x16x64_i8 v[130:133], v[170:173], v[184:187], v[130:133]
	v_mfma_i32_16x16x64_i8 v[118:121], v[162:165], v[192:195], v[118:121]
	v_mfma_i32_16x16x64_i8 v[114:117], v[170:173], v[192:195], v[114:117]
	v_mfma_i32_16x16x64_i8 v[102:105], v[162:165], v[200:203], v[102:105]
	v_mfma_i32_16x16x64_i8 v[98:101], v[170:173], v[200:203], v[98:101]
	v_mfma_i32_16x16x64_i8 v[86:89], v[162:165], v[208:211], v[86:89]
	v_mfma_i32_16x16x64_i8 v[82:85], v[170:173], v[208:211], v[82:85]
	v_mfma_i32_16x16x64_i8 v[134:137], v[166:169], v[188:191], v[134:137]
	v_mfma_i32_16x16x64_i8 v[130:133], v[180:183], v[188:191], v[130:133]
	v_mfma_i32_16x16x64_i8 v[118:121], v[166:169], v[196:199], v[118:121]
	v_mfma_i32_16x16x64_i8 v[114:117], v[180:183], v[196:199], v[114:117]
	v_mfma_i32_16x16x64_i8 v[102:105], v[166:169], v[204:207], v[102:105]
	v_mfma_i32_16x16x64_i8 v[98:101], v[180:183], v[204:207], v[98:101]
	v_mfma_i32_16x16x64_i8 v[86:89], v[166:169], v[212:215], v[86:89]
	v_mfma_i32_16x16x64_i8 v[82:85], v[180:183], v[212:215], v[82:85]
	s_barrier
	s_add_i32 s40, s33, s68
	s_mov_b64 s[98:99], s[34:35]
	s_mov_b32 m0, s40
	ds_read_b128 v[184:187], v179 offset:16384
	ds_read_b128 v[188:191], v179 offset:17408
	ds_read_b128 v[192:195], v179 offset:18432
	ds_read_b128 v[196:199], v179 offset:19456
	ds_read_b128 v[200:203], v179 offset:20480
	ds_read_b128 v[204:207], v179 offset:21504
	ds_read_b128 v[208:211], v179 offset:22528
	ds_read_b128 v[212:215], v179 offset:23552
	global_load_lds_dwordx4 v148, s[34:35]
	s_add_i32 m0, s40, 0x2000
	s_add_u32 s40, s34, 0x80000
	s_mov_b64 s[98:99], s[34:35]
	s_addc_u32 s41, s35, 0
	s_add_i32 vcc_lo, s8, s68
	global_load_lds_dwordx4 v152, s[34:35]
	s_mov_b32 m0, vcc_lo
	s_mov_b64 s[100:101], s[36:37]
	global_load_lds_dwordx4 v148, s[40:41]
	s_add_i32 m0, vcc_lo, 0x2000
	s_nop 0
	global_load_lds_dwordx4 v152, s[40:41]
	s_mov_b64 s[100:101], s[36:37]
	s_mov_b32 m0, s69
	s_nop 0
	global_load_lds_dwordx4 v146, s[36:37]
	s_mov_b32 m0, s70
	s_nop 0
	global_load_lds_dwordx4 v150, s[36:37]
	s_waitcnt vmcnt(8)
	s_waitcnt lgkmcnt(0)
	s_barrier
	s_waitcnt lgkmcnt(0)
	v_mfma_i32_16x16x64_i8 v[70:73], v[58:61], v[184:187], v[70:73]
	v_mfma_i32_16x16x64_i8 v[66:69], v[74:77], v[184:187], v[66:69]
	v_mfma_i32_16x16x64_i8 v[46:49], v[58:61], v[192:195], v[46:49]
	v_mfma_i32_16x16x64_i8 v[42:45], v[74:77], v[192:195], v[42:45]
	v_mfma_i32_16x16x64_i8 v[30:33], v[58:61], v[200:203], v[30:33]
	v_mfma_i32_16x16x64_i8 v[26:29], v[74:77], v[200:203], v[26:29]
	v_mfma_i32_16x16x64_i8 v[14:17], v[58:61], v[208:211], v[14:17]
	v_mfma_i32_16x16x64_i8 v[10:13], v[74:77], v[208:211], v[10:13]
	v_mfma_i32_16x16x64_i8 v[70:73], v[62:65], v[188:191], v[70:73]
	v_mfma_i32_16x16x64_i8 v[66:69], v[78:81], v[188:191], v[66:69]
	v_mfma_i32_16x16x64_i8 v[46:49], v[62:65], v[196:199], v[46:49]
	v_mfma_i32_16x16x64_i8 v[42:45], v[78:81], v[196:199], v[42:45]
	v_mfma_i32_16x16x64_i8 v[30:33], v[62:65], v[204:207], v[30:33]
	v_mfma_i32_16x16x64_i8 v[26:29], v[78:81], v[204:207], v[26:29]
	v_mfma_i32_16x16x64_i8 v[14:17], v[62:65], v[212:215], v[14:17]
	v_mfma_i32_16x16x64_i8 v[10:13], v[78:81], v[212:215], v[10:13]
	v_mfma_i32_16x16x64_i8 v[54:57], v[162:165], v[184:187], v[54:57]
	v_mfma_i32_16x16x64_i8 v[50:53], v[170:173], v[184:187], v[50:53]
	v_mfma_i32_16x16x64_i8 v[38:41], v[162:165], v[192:195], v[38:41]
	v_mfma_i32_16x16x64_i8 v[34:37], v[170:173], v[192:195], v[34:37]
	v_mfma_i32_16x16x64_i8 v[22:25], v[162:165], v[200:203], v[22:25]
	v_mfma_i32_16x16x64_i8 v[18:21], v[170:173], v[200:203], v[18:21]
	v_mfma_i32_16x16x64_i8 v[6:9], v[162:165], v[208:211], v[6:9]
	v_mfma_i32_16x16x64_i8 v[2:5], v[170:173], v[208:211], v[2:5]
	v_mfma_i32_16x16x64_i8 v[54:57], v[166:169], v[188:191], v[54:57]
	v_mfma_i32_16x16x64_i8 v[50:53], v[180:183], v[188:191], v[50:53]
	v_mfma_i32_16x16x64_i8 v[38:41], v[166:169], v[196:199], v[38:41]
	v_mfma_i32_16x16x64_i8 v[34:37], v[180:183], v[196:199], v[34:37]
	v_mfma_i32_16x16x64_i8 v[22:25], v[166:169], v[204:207], v[22:25]
	v_mfma_i32_16x16x64_i8 v[18:21], v[180:183], v[204:207], v[18:21]
	v_mfma_i32_16x16x64_i8 v[6:9], v[166:169], v[212:215], v[6:9]
	v_mfma_i32_16x16x64_i8 v[2:5], v[180:183], v[212:215], v[2:5]
	s_barrier
; #define PG8_STAGE(bufoff, gbase, voff) do { _Pragma("unroll") for (int _i = 0; _i < 2; ++_i) \
;         __builtin_amdgcn_global_load_lds((const unsigned*)((const char*)(gbase) + (voff)[_i]), (PG8_LAS unsigned*)(lds + (bufoff) + ldsw + _i * 8192), 16, 0, 0); } while (0)
; #define PG8_LDA(dst, b, h) do { _Pragma("unroll") for (int m = 0; m < 4; ++m) _Pragma("unroll") for (int k = 0; k < 2; ++k) dst[m][k] = *(const PG8_LAS bf16x8*)(lds + PG8_SA(b, h) + aoff + m * 2048 + k * 1024); } while (0)
; #define PG8_WAIT_V(n) asm volatile("s_waitcnt vmcnt(" #n ")" ::: "memory")
; #define PG8_WAIT_L(n) asm volatile("s_waitcnt lgkmcnt(" #n ")" ::: "memory")
; #define PG8_BAR __builtin_amdgcn_s_barrier()
; template <class Epi, class Sched, bool ALIGN_EPI = false, bool SP2 = false, bool I8 = false>
; __device__ __forceinline__ void gemm_phase(PG8_LAS unsigned char* lds, const Gemm g, const Sched& S, const Epi& E) {
;     ...
;         for (int t = 0; t < nt; t += 2) {
;             const bool last = (t == nt - 2);
;             const char* a1 = cA + (size_t)(t + 1) * kstep;
;             const char* a2 = last ? nA : cA + (size_t)(t + 2) * kstep; const char* b2 = last ? nB : cB + (size_t)(t + 2) * kstep;
;             const char* a3 = a2 + kstep; const char* b3 = b2 + kstep;
;             if (last && has_next) S.a_ready(nxt);
;             if constexpr (SP2) {
;             PG8_LDB(B0, 0, 0); PG8_LDB(B1, 0, 1); PG8_SCHED; PG8_LDA(At, 0, 0); PG8_STAGE(PG8_SA(1, 1), a1 + hstepA, voffA);
;             PG8_WAIT_V(8); PG8_WAIT_L(0); PG8_BAR; PG8_MMA(0, 0, At, B0); PG8_MMA(0, 1, At, B1); PG8_BAR; PG8_SCHED;
;             PG8_LDA(At, 0, 1); PG8_STAGE(PG8_SB(0, 0), b2, voffB); PG8_STAGE(PG8_SB(0, 1), b2 + hstepB, voffB); PG8_STAGE(PG8_SA(0, 0), a2, voffA);
;             PG8_WAIT_V(8); PG8_WAIT_L(0); PG8_BAR; PG8_MMA(1, 0, At, B0); PG8_MMA(1, 1, At, B1); PG8_BAR; PG8_SCHED;
;             PG8_LDB(B0, 1, 0); PG8_LDB(B1, 1, 1); PG8_SCHED; PG8_LDA(At, 1, 0); PG8_STAGE(PG8_SA(0, 1), a2 + hstepA, voffA);
;             PG8_WAIT_V(8); PG8_WAIT_L(0); PG8_BAR; PG8_MMA(0, 0, At, B0); PG8_MMA(0, 1, At, B1); PG8_BAR; PG8_SCHED;
;             PG8_LDA(At, 1, 1); PG8_STAGE(PG8_SB(1, 0), b3, voffB); PG8_STAGE(PG8_SB(1, 1), b3 + hstepB, voffB); PG8_STAGE(PG8_SA(1, 0), a3, voffA);
;             PG8_WAIT_V(8); PG8_WAIT_L(0); PG8_BAR; PG8_MMA(1, 0, At, B0); PG8_MMA(1, 1, At, B1); PG8_BAR; PG8_SCHED;
	s_add_i32 s40, 0, 0x18000
	s_add_i32 s41, 0, 0x1c000
	v_add_u32_e32 v78, s40, v176
	v_add_u32_e32 v180, s41, v176
	ds_read_b128 v[58:61], v78
	ds_read_b128 v[62:65], v78 offset:1024
	ds_read_b128 v[74:77], v78 offset:2048
	ds_read_b128 v[78:81], v78 offset:3072
	ds_read_b128 v[162:165], v180
	ds_read_b128 v[166:169], v180 offset:1024
	ds_read_b128 v[170:173], v180 offset:2048
	ds_read_b128 v[180:183], v180 offset:3072
	s_add_u32 s36, s36, 0x80000
	s_addc_u32 s37, s37, 0
	s_mov_b32 m0, s71
	ds_read_b128 v[184:187], v179 offset:32768
	ds_read_b128 v[188:191], v179 offset:33792
	ds_read_b128 v[192:195], v179 offset:34816
	ds_read_b128 v[196:199], v179 offset:35840
	ds_read_b128 v[200:203], v179 offset:36864
	ds_read_b128 v[204:207], v179 offset:37888
	ds_read_b128 v[208:211], v179 offset:38912
	ds_read_b128 v[212:215], v179 offset:39936
	global_load_lds_dwordx4 v146, s[36:37]
	s_mov_b32 m0, s88
	s_nop 0
	global_load_lds_dwordx4 v150, s[36:37]
	s_waitcnt vmcnt(8)
	s_waitcnt lgkmcnt(0)
	s_barrier
	s_waitcnt lgkmcnt(0)
	v_mfma_i32_16x16x64_i8 v[142:145], v[58:61], v[184:187], v[142:145]
	v_mfma_i32_16x16x64_i8 v[138:141], v[74:77], v[184:187], v[138:141]
	v_mfma_i32_16x16x64_i8 v[126:129], v[58:61], v[192:195], v[126:129]
	v_mfma_i32_16x16x64_i8 v[122:125], v[74:77], v[192:195], v[122:125]
	v_mfma_i32_16x16x64_i8 v[110:113], v[58:61], v[200:203], v[110:113]
	v_mfma_i32_16x16x64_i8 v[106:109], v[74:77], v[200:203], v[106:109]
	v_mfma_i32_16x16x64_i8 v[94:97], v[58:61], v[208:211], v[94:97]
	v_mfma_i32_16x16x64_i8 v[90:93], v[74:77], v[208:211], v[90:93]
	v_mfma_i32_16x16x64_i8 v[142:145], v[62:65], v[188:191], v[142:145]
	v_mfma_i32_16x16x64_i8 v[138:141], v[78:81], v[188:191], v[138:141]
	v_mfma_i32_16x16x64_i8 v[126:129], v[62:65], v[196:199], v[126:129]
	v_mfma_i32_16x16x64_i8 v[122:125], v[78:81], v[196:199], v[122:125]
	v_mfma_i32_16x16x64_i8 v[110:113], v[62:65], v[204:207], v[110:113]
	v_mfma_i32_16x16x64_i8 v[106:109], v[78:81], v[204:207], v[106:109]
	v_mfma_i32_16x16x64_i8 v[94:97], v[62:65], v[212:215], v[94:97]
	v_mfma_i32_16x16x64_i8 v[90:93], v[78:81], v[212:215], v[90:93]
	v_mfma_i32_16x16x64_i8 v[134:137], v[162:165], v[184:187], v[134:137]
	v_mfma_i32_16x16x64_i8 v[130:133], v[170:173], v[184:187], v[130:133]
	v_mfma_i32_16x16x64_i8 v[118:121], v[162:165], v[192:195], v[118:121]
	v_mfma_i32_16x16x64_i8 v[114:117], v[170:173], v[192:195], v[114:117]
	v_mfma_i32_16x16x64_i8 v[102:105], v[162:165], v[200:203], v[102:105]
	v_mfma_i32_16x16x64_i8 v[98:101], v[170:173], v[200:203], v[98:101]
	v_mfma_i32_16x16x64_i8 v[86:89], v[162:165], v[208:211], v[86:89]
	v_mfma_i32_16x16x64_i8 v[82:85], v[170:173], v[208:211], v[82:85]
	v_mfma_i32_16x16x64_i8 v[134:137], v[166:169], v[188:191], v[134:137]
	v_mfma_i32_16x16x64_i8 v[130:133], v[180:183], v[188:191], v[130:133]
	v_mfma_i32_16x16x64_i8 v[118:121], v[166:169], v[196:199], v[118:121]
	v_mfma_i32_16x16x64_i8 v[114:117], v[180:183], v[196:199], v[114:117]
	v_mfma_i32_16x16x64_i8 v[102:105], v[166:169], v[204:207], v[102:105]
	v_mfma_i32_16x16x64_i8 v[98:101], v[180:183], v[204:207], v[98:101]
	v_mfma_i32_16x16x64_i8 v[86:89], v[166:169], v[212:215], v[86:89]
	v_mfma_i32_16x16x64_i8 v[82:85], v[180:183], v[212:215], v[82:85]
	s_barrier
	s_add_i32 s36, s40, s68
	s_add_i32 m0, s36, 0xffffff80
	ds_read_b128 v[184:187], v179 offset:49152
	ds_read_b128 v[188:191], v179 offset:50176
	ds_read_b128 v[192:195], v179 offset:51200
	ds_read_b128 v[196:199], v179 offset:52224
	ds_read_b128 v[200:203], v179 offset:53248
	ds_read_b128 v[204:207], v179 offset:54272
	ds_read_b128 v[208:211], v179 offset:55296
	ds_read_b128 v[212:215], v179 offset:56320
	global_load_lds_dwordx4 v148, s[98:99] offset:128
	s_add_i32 m0, s36, 0x1f80
	s_add_u32 s34, s34, 0x80080
	s_addc_u32 s35, s35, 0
	s_add_i32 s36, s41, s68
	global_load_lds_dwordx4 v152, s[98:99] offset:128
	s_mov_b32 m0, s36
	s_nop 0
	global_load_lds_dwordx4 v148, s[34:35]
	s_add_i32 m0, s36, 0x2000
	s_nop 0
	global_load_lds_dwordx4 v152, s[34:35]
	s_add_i32 m0, s92, 0xffffff80
	s_nop 0
	global_load_lds_dwordx4 v146, s[100:101] offset:128
	s_add_i32 m0, s93, 0xffffff80
	s_nop 0
	global_load_lds_dwordx4 v150, s[100:101] offset:128
	s_waitcnt vmcnt(8)
	s_waitcnt lgkmcnt(0)
	s_barrier
	s_waitcnt lgkmcnt(0)
	v_mfma_i32_16x16x64_i8 v[70:73], v[58:61], v[184:187], v[70:73]
	v_mfma_i32_16x16x64_i8 v[66:69], v[74:77], v[184:187], v[66:69]
	v_mfma_i32_16x16x64_i8 v[46:49], v[58:61], v[192:195], v[46:49]
	v_mfma_i32_16x16x64_i8 v[42:45], v[74:77], v[192:195], v[42:45]
	v_mfma_i32_16x16x64_i8 v[30:33], v[58:61], v[200:203], v[30:33]
	v_mfma_i32_16x16x64_i8 v[26:29], v[74:77], v[200:203], v[26:29]
	v_mfma_i32_16x16x64_i8 v[14:17], v[58:61], v[208:211], v[14:17]
	v_mfma_i32_16x16x64_i8 v[10:13], v[74:77], v[208:211], v[10:13]
	v_mfma_i32_16x16x64_i8 v[70:73], v[62:65], v[188:191], v[70:73]
	v_mfma_i32_16x16x64_i8 v[66:69], v[78:81], v[188:191], v[66:69]
	v_mfma_i32_16x16x64_i8 v[46:49], v[62:65], v[196:199], v[46:49]
	v_mfma_i32_16x16x64_i8 v[42:45], v[78:81], v[196:199], v[42:45]
	v_mfma_i32_16x16x64_i8 v[30:33], v[62:65], v[204:207], v[30:33]
	v_mfma_i32_16x16x64_i8 v[26:29], v[78:81], v[204:207], v[26:29]
	v_mfma_i32_16x16x64_i8 v[14:17], v[62:65], v[212:215], v[14:17]
	v_mfma_i32_16x16x64_i8 v[10:13], v[78:81], v[212:215], v[10:13]
	v_mfma_i32_16x16x64_i8 v[54:57], v[162:165], v[184:187], v[54:57]
	v_mfma_i32_16x16x64_i8 v[50:53], v[170:173], v[184:187], v[50:53]
	v_mfma_i32_16x16x64_i8 v[38:41], v[162:165], v[192:195], v[38:41]
	v_mfma_i32_16x16x64_i8 v[34:37], v[170:173], v[192:195], v[34:37]
	v_mfma_i32_16x16x64_i8 v[22:25], v[162:165], v[200:203], v[22:25]
	v_mfma_i32_16x16x64_i8 v[18:21], v[170:173], v[200:203], v[18:21]
	v_mfma_i32_16x16x64_i8 v[6:9], v[162:165], v[208:211], v[6:9]
	v_mfma_i32_16x16x64_i8 v[2:5], v[170:173], v[208:211], v[2:5]
	v_mfma_i32_16x16x64_i8 v[54:57], v[166:169], v[188:191], v[54:57]
	v_mfma_i32_16x16x64_i8 v[50:53], v[180:183], v[188:191], v[50:53]
	v_mfma_i32_16x16x64_i8 v[38:41], v[166:169], v[196:199], v[38:41]
	v_mfma_i32_16x16x64_i8 v[34:37], v[180:183], v[196:199], v[34:37]
	v_mfma_i32_16x16x64_i8 v[22:25], v[166:169], v[204:207], v[22:25]
	v_mfma_i32_16x16x64_i8 v[18:21], v[180:183], v[204:207], v[18:21]
	v_mfma_i32_16x16x64_i8 v[6:9], v[166:169], v[212:215], v[6:9]
	v_mfma_i32_16x16x64_i8 v[2:5], v[180:183], v[212:215], v[2:5]
	s_barrier
	s_add_i32 s39, s39, 2
	s_add_u32 s2, s2, 0x100
	s_addc_u32 s3, s3, 0
	s_add_u32 s31, s31, 0x100
	s_addc_u32 s38, s38, 0
	s_cmp_gt_u32 s39, 29
	s_cbranch_scc0 .LBB0_607
	s_and_b64 vcc, exec, s[20:21]
	s_cbranch_vccz .LBB0_610
	s_barrier

; #define PG8_STAGE(bufoff, gbase, voff) do { _Pragma("unroll") for (int _i = 0; _i < 2; ++_i) \
;         __builtin_amdgcn_global_load_lds((const unsigned*)((const char*)(gbase) + (voff)[_i]), (PG8_LAS unsigned*)(lds + (bufoff) + ldsw + _i * 8192), 16, 0, 0); } while (0)
; #define PG8_LDA(dst, b, h) do { _Pragma("unroll") for (int m = 0; m < 4; ++m) _Pragma("unroll") for (int k = 0; k < 2; ++k) dst[m][k] = *(const PG8_LAS bf16x8*)(lds + PG8_SA(b, h) + aoff + m * 2048 + k * 1024); } while (0)
; #define PG8_LDB(dst, b, h) do { _Pragma("unroll") for (int n = 0; n < 2; ++n) _Pragma("unroll") for (int k = 0; k < 2; ++k) dst[n][k] = *(const PG8_LAS bf16x8*)(lds + PG8_SB(b, h) + boff + n * 2048 + k * 1024); } while (0)
; #define PG8_MMA(ai, bj, At, Bt) do { __builtin_amdgcn_s_setprio(1); _Pragma("unroll") for (int m = 0; m < 4; ++m) _Pragma("unroll") for (int n = 0; n < 2; ++n) _Pragma("unroll") for (int k = 0; k < 2; ++k) \
;         acc[ai][bj][m][n] = mma_<I8>(Bt[n][k], At[m][k], acc[ai][bj][m][n]); __builtin_amdgcn_s_setprio(0); } while (0)
; #define PG8_WAIT_V(n) asm volatile("s_waitcnt vmcnt(" #n ")" ::: "memory")
; #define PG8_WAIT_L(n) asm volatile("s_waitcnt lgkmcnt(" #n ")" ::: "memory")
; #define PG8_BAR __builtin_amdgcn_s_barrier()
; template <class Epi, class Sched, bool ALIGN_EPI = false, bool SP2 = false, bool I8 = false>
; __device__ __forceinline__ void gemm_phase(PG8_LAS unsigned char* lds, const Gemm g, const Sched& S, const Epi& E) {
;     ...
;             const bool last = (t == nt - 2);
;             const char* a1 = cA + (size_t)(t + 1) * kstep;
;             const char* a2 = last ? nA : cA + (size_t)(t + 2) * kstep; const char* b2 = last ? nB : cB + (size_t)(t + 2) * kstep;
;             const char* a3 = a2 + kstep; const char* b3 = b2 + kstep;
;             if (last && has_next) S.a_ready(nxt);
;             if constexpr (SP2) {
;             PG8_LDB(B0, 0, 0); PG8_LDB(B1, 0, 1); PG8_SCHED; PG8_LDA(At, 0, 0); PG8_STAGE(PG8_SA(1, 1), a1 + hstepA, voffA);
;             PG8_WAIT_V(8); PG8_WAIT_L(0); PG8_BAR; PG8_MMA(0, 0, At, B0); PG8_MMA(0, 1, At, B1); PG8_BAR; PG8_SCHED;
;             PG8_LDA(At, 0, 1); PG8_STAGE(PG8_SB(0, 0), b2, voffB); PG8_STAGE(PG8_SB(0, 1), b2 + hstepB, voffB); PG8_STAGE(PG8_SA(0, 0), a2, voffA);
;             PG8_WAIT_V(8); PG8_WAIT_L(0); PG8_BAR; PG8_MMA(1, 0, At, B0); PG8_MMA(1, 1, At, B1); PG8_BAR; PG8_SCHED;
.LBB0_1092:
	ds_read_b128 v[58:61], v172
	ds_read_b128 v[62:65], v172 offset:1024
	ds_read_b128 v[74:77], v172 offset:2048
	ds_read_b128 v[78:81], v172 offset:3072
	ds_read_b128 v[164:167], v173
	ds_read_b128 v[168:171], v173 offset:1024
	ds_read_b128 v[176:179], v173 offset:2048
	ds_read_b128 v[180:183], v173 offset:3072
	s_add_i32 s47, s22, 2
	s_add_u32 s23, s8, 0xfffe0080
	s_addc_u32 s24, s9, -1
	s_cmp_eq_u32 s3, s22
	s_cselect_b32 s22, s20, s17
	s_cselect_b32 s25, s1, s24
	s_cselect_b32 s24, s0, s23
	s_cselect_b32 s23, s21, s19
	s_add_i32 m0, s33, 0xc000
	ds_read_b128 v[184:187], v174
	ds_read_b128 v[188:191], v174 offset:1024
	ds_read_b128 v[192:195], v174 offset:2048
	ds_read_b128 v[196:199], v174 offset:3072
	ds_read_b128 v[200:203], v174 offset:4096
	ds_read_b128 v[204:207], v174 offset:5120
	ds_read_b128 v[208:211], v174 offset:6144
	ds_read_b128 v[212:215], v174 offset:7168
	global_load_lds_dwordx4 v156, s[8:9]
	s_add_i32 m0, s33, 0xe000
	s_nop 0
	global_load_lds_dwordx4 v158, s[8:9]
	s_waitcnt vmcnt(8)
	s_waitcnt lgkmcnt(0)
	s_barrier
	s_waitcnt lgkmcnt(0)
	v_mfma_f32_16x16x32_bf16 v[142:145], v[58:61], v[184:187], v[142:145]
	v_mfma_f32_16x16x32_bf16 v[138:141], v[74:77], v[184:187], v[138:141]
	v_mfma_f32_16x16x32_bf16 v[126:129], v[58:61], v[192:195], v[126:129]
	v_mfma_f32_16x16x32_bf16 v[122:125], v[74:77], v[192:195], v[122:125]
	v_mfma_f32_16x16x32_bf16 v[110:113], v[58:61], v[200:203], v[110:113]
	v_mfma_f32_16x16x32_bf16 v[106:109], v[74:77], v[200:203], v[106:109]
	v_mfma_f32_16x16x32_bf16 v[94:97], v[58:61], v[208:211], v[94:97]
	v_mfma_f32_16x16x32_bf16 v[90:93], v[74:77], v[208:211], v[90:93]
	v_mfma_f32_16x16x32_bf16 v[142:145], v[62:65], v[188:191], v[142:145]
	v_mfma_f32_16x16x32_bf16 v[138:141], v[78:81], v[188:191], v[138:141]
	v_mfma_f32_16x16x32_bf16 v[126:129], v[62:65], v[196:199], v[126:129]
	v_mfma_f32_16x16x32_bf16 v[122:125], v[78:81], v[196:199], v[122:125]
	v_mfma_f32_16x16x32_bf16 v[110:113], v[62:65], v[204:207], v[110:113]
	v_mfma_f32_16x16x32_bf16 v[106:109], v[78:81], v[204:207], v[106:109]
	v_mfma_f32_16x16x32_bf16 v[94:97], v[62:65], v[212:215], v[94:97]
	v_mfma_f32_16x16x32_bf16 v[90:93], v[78:81], v[212:215], v[90:93]
	v_mfma_f32_16x16x32_bf16 v[134:137], v[164:167], v[184:187], v[134:137]
	v_mfma_f32_16x16x32_bf16 v[130:133], v[176:179], v[184:187], v[130:133]
	v_mfma_f32_16x16x32_bf16 v[118:121], v[164:167], v[192:195], v[118:121]
	v_mfma_f32_16x16x32_bf16 v[114:117], v[176:179], v[192:195], v[114:117]
	v_mfma_f32_16x16x32_bf16 v[102:105], v[164:167], v[200:203], v[102:105]
	v_mfma_f32_16x16x32_bf16 v[98:101], v[176:179], v[200:203], v[98:101]
	v_mfma_f32_16x16x32_bf16 v[86:89], v[164:167], v[208:211], v[86:89]
	v_mfma_f32_16x16x32_bf16 v[82:85], v[176:179], v[208:211], v[82:85]
	v_mfma_f32_16x16x32_bf16 v[134:137], v[168:171], v[188:191], v[134:137]
	v_mfma_f32_16x16x32_bf16 v[130:133], v[180:183], v[188:191], v[130:133]
	v_mfma_f32_16x16x32_bf16 v[118:121], v[168:171], v[196:199], v[118:121]
	v_mfma_f32_16x16x32_bf16 v[114:117], v[180:183], v[196:199], v[114:117]
	v_mfma_f32_16x16x32_bf16 v[102:105], v[168:171], v[204:207], v[102:105]
	v_mfma_f32_16x16x32_bf16 v[98:101], v[180:183], v[204:207], v[98:101]
	v_mfma_f32_16x16x32_bf16 v[86:89], v[168:171], v[212:215], v[86:89]
	v_mfma_f32_16x16x32_bf16 v[82:85], v[180:183], v[212:215], v[82:85]
	s_barrier
	s_add_i32 s56, s44, s30
	s_mov_b64 s[98:99], s[22:23]
	s_mov_b32 m0, s56
	ds_read_b128 v[184:187], v174 offset:16384
	ds_read_b128 v[188:191], v174 offset:17408
	ds_read_b128 v[192:195], v174 offset:18432
	ds_read_b128 v[196:199], v174 offset:19456
	ds_read_b128 v[200:203], v174 offset:20480
	ds_read_b128 v[204:207], v174 offset:21504
	ds_read_b128 v[208:211], v174 offset:22528
	ds_read_b128 v[212:215], v174 offset:23552
	global_load_lds_dwordx4 v148, s[22:23]
	s_add_i32 m0, s56, 0x2000
	s_add_u32 s56, s22, 0x20000
	s_mov_b64 s[98:99], s[22:23]
	s_addc_u32 s57, s23, 0
	s_add_i32 s58, s45, s30
	global_load_lds_dwordx4 v152, s[22:23]
	s_mov_b32 m0, s58
	s_mov_b64 s[100:101], s[24:25]
	global_load_lds_dwordx4 v148, s[56:57]
	s_add_i32 m0, s58, 0x2000
	s_nop 0
	global_load_lds_dwordx4 v152, s[56:57]
	s_mov_b64 s[100:101], s[24:25]
	s_mov_b32 m0, s33
	s_nop 0
	global_load_lds_dwordx4 v146, s[24:25]
	s_mov_b32 m0, s34
	s_nop 0
	global_load_lds_dwordx4 v150, s[24:25]
	s_waitcnt vmcnt(8)
	s_waitcnt lgkmcnt(0)
	s_barrier
	s_waitcnt lgkmcnt(0)
	v_mfma_f32_16x16x32_bf16 v[70:73], v[58:61], v[184:187], v[70:73]
	v_mfma_f32_16x16x32_bf16 v[66:69], v[74:77], v[184:187], v[66:69]
	v_mfma_f32_16x16x32_bf16 v[46:49], v[58:61], v[192:195], v[46:49]
	v_mfma_f32_16x16x32_bf16 v[42:45], v[74:77], v[192:195], v[42:45]
	v_mfma_f32_16x16x32_bf16 v[30:33], v[58:61], v[200:203], v[30:33]
	v_mfma_f32_16x16x32_bf16 v[26:29], v[74:77], v[200:203], v[26:29]
	v_mfma_f32_16x16x32_bf16 v[14:17], v[58:61], v[208:211], v[14:17]
	v_mfma_f32_16x16x32_bf16 v[10:13], v[74:77], v[208:211], v[10:13]
	v_mfma_f32_16x16x32_bf16 v[70:73], v[62:65], v[188:191], v[70:73]
	v_mfma_f32_16x16x32_bf16 v[66:69], v[78:81], v[188:191], v[66:69]
	v_mfma_f32_16x16x32_bf16 v[46:49], v[62:65], v[196:199], v[46:49]
	v_mfma_f32_16x16x32_bf16 v[42:45], v[78:81], v[196:199], v[42:45]
	v_mfma_f32_16x16x32_bf16 v[30:33], v[62:65], v[204:207], v[30:33]
	v_mfma_f32_16x16x32_bf16 v[26:29], v[78:81], v[204:207], v[26:29]
	v_mfma_f32_16x16x32_bf16 v[14:17], v[62:65], v[212:215], v[14:17]
	v_mfma_f32_16x16x32_bf16 v[10:13], v[78:81], v[212:215], v[10:13]
	v_mfma_f32_16x16x32_bf16 v[54:57], v[164:167], v[184:187], v[54:57]
	v_mfma_f32_16x16x32_bf16 v[50:53], v[176:179], v[184:187], v[50:53]
	v_mfma_f32_16x16x32_bf16 v[38:41], v[164:167], v[192:195], v[38:41]
	v_mfma_f32_16x16x32_bf16 v[34:37], v[176:179], v[192:195], v[34:37]
	v_mfma_f32_16x16x32_bf16 v[22:25], v[164:167], v[200:203], v[22:25]
	v_mfma_f32_16x16x32_bf16 v[18:21], v[176:179], v[200:203], v[18:21]
	v_mfma_f32_16x16x32_bf16 v[6:9], v[164:167], v[208:211], v[6:9]
	v_mfma_f32_16x16x32_bf16 v[2:5], v[176:179], v[208:211], v[2:5]
	v_mfma_f32_16x16x32_bf16 v[54:57], v[168:171], v[188:191], v[54:57]
	v_mfma_f32_16x16x32_bf16 v[50:53], v[180:183], v[188:191], v[50:53]
	v_mfma_f32_16x16x32_bf16 v[38:41], v[168:171], v[196:199], v[38:41]
	v_mfma_f32_16x16x32_bf16 v[34:37], v[180:183], v[196:199], v[34:37]
	v_mfma_f32_16x16x32_bf16 v[22:25], v[168:171], v[204:207], v[22:25]
	v_mfma_f32_16x16x32_bf16 v[18:21], v[180:183], v[204:207], v[18:21]
	v_mfma_f32_16x16x32_bf16 v[6:9], v[168:171], v[212:215], v[6:9]
	v_mfma_f32_16x16x32_bf16 v[2:5], v[180:183], v[212:215], v[2:5]
	s_barrier
; #define PG8_STAGE(bufoff, gbase, voff) do { _Pragma("unroll") for (int _i = 0; _i < 2; ++_i) \
;         __builtin_amdgcn_global_load_lds((const unsigned*)((const char*)(gbase) + (voff)[_i]), (PG8_LAS unsigned*)(lds + (bufoff) + ldsw + _i * 8192), 16, 0, 0); } while (0)
; #define PG8_LDA(dst, b, h) do { _Pragma("unroll") for (int m = 0; m < 4; ++m) _Pragma("unroll") for (int k = 0; k < 2; ++k) dst[m][k] = *(const PG8_LAS bf16x8*)(lds + PG8_SA(b, h) + aoff + m * 2048 + k * 1024); } while (0)
; #define PG8_WAIT_V(n) asm volatile("s_waitcnt vmcnt(" #n ")" ::: "memory")
; #define PG8_WAIT_L(n) asm volatile("s_waitcnt lgkmcnt(" #n ")" ::: "memory")
; #define PG8_BAR __builtin_amdgcn_s_barrier()
; template <class Epi, class Sched, bool ALIGN_EPI = false, bool SP2 = false, bool I8 = false>
; __device__ __forceinline__ void gemm_phase(PG8_LAS unsigned char* lds, const Gemm g, const Sched& S, const Epi& E) {
;     ...
;         for (int t = 0; t < nt; t += 2) {
;             const bool last = (t == nt - 2);
;             const char* a1 = cA + (size_t)(t + 1) * kstep;
;             const char* a2 = last ? nA : cA + (size_t)(t + 2) * kstep; const char* b2 = last ? nB : cB + (size_t)(t + 2) * kstep;
;             const char* a3 = a2 + kstep; const char* b3 = b2 + kstep;
;             if (last && has_next) S.a_ready(nxt);
;             if constexpr (SP2) {
;             PG8_LDB(B0, 0, 0); PG8_LDB(B1, 0, 1); PG8_SCHED; PG8_LDA(At, 0, 0); PG8_STAGE(PG8_SA(1, 1), a1 + hstepA, voffA);
;             PG8_WAIT_V(8); PG8_WAIT_L(0); PG8_BAR; PG8_MMA(0, 0, At, B0); PG8_MMA(0, 1, At, B1); PG8_BAR; PG8_SCHED;
;             PG8_LDA(At, 0, 1); PG8_STAGE(PG8_SB(0, 0), b2, voffB); PG8_STAGE(PG8_SB(0, 1), b2 + hstepB, voffB); PG8_STAGE(PG8_SA(0, 0), a2, voffA);
;             PG8_WAIT_V(8); PG8_WAIT_L(0); PG8_BAR; PG8_MMA(1, 0, At, B0); PG8_MMA(1, 1, At, B1); PG8_BAR; PG8_SCHED;
;             PG8_LDB(B0, 1, 0); PG8_LDB(B1, 1, 1); PG8_SCHED; PG8_LDA(At, 1, 0); PG8_STAGE(PG8_SA(0, 1), a2 + hstepA, voffA);
;             PG8_WAIT_V(8); PG8_WAIT_L(0); PG8_BAR; PG8_MMA(0, 0, At, B0); PG8_MMA(0, 1, At, B1); PG8_BAR; PG8_SCHED;
;             PG8_LDA(At, 1, 1); PG8_STAGE(PG8_SB(1, 0), b3, voffB); PG8_STAGE(PG8_SB(1, 1), b3 + hstepB, voffB); PG8_STAGE(PG8_SA(1, 0), a3, voffA);
;             PG8_WAIT_V(8); PG8_WAIT_L(0); PG8_BAR; PG8_MMA(1, 0, At, B0); PG8_MMA(1, 1, At, B1); PG8_BAR; PG8_SCHED;
	s_add_i32 s56, 0, 0x18000
	s_add_i32 s57, 0, 0x1c000
	v_add_u32_e32 v78, s56, v1
	v_add_u32_e32 v154, s57, v1
	ds_read_b128 v[58:61], v78
	ds_read_b128 v[62:65], v78 offset:1024
	ds_read_b128 v[74:77], v78 offset:2048
	ds_read_b128 v[78:81], v78 offset:3072
	ds_read_b128 v[164:167], v154
	ds_read_b128 v[168:171], v154 offset:1024
	ds_read_b128 v[176:179], v154 offset:2048
	ds_read_b128 v[180:183], v154 offset:3072
	s_add_u32 s24, s24, 0x20000
	s_addc_u32 s25, s25, 0
	s_mov_b32 m0, s35
	ds_read_b128 v[184:187], v174 offset:32768
	ds_read_b128 v[188:191], v174 offset:33792
	ds_read_b128 v[192:195], v174 offset:34816
	ds_read_b128 v[196:199], v174 offset:35840
	ds_read_b128 v[200:203], v174 offset:36864
	ds_read_b128 v[204:207], v174 offset:37888
	ds_read_b128 v[208:211], v174 offset:38912
	ds_read_b128 v[212:215], v174 offset:39936
	global_load_lds_dwordx4 v146, s[24:25]
	s_mov_b32 m0, s36
	s_nop 0
	global_load_lds_dwordx4 v150, s[24:25]
	s_waitcnt vmcnt(8)
	s_waitcnt lgkmcnt(0)
	s_barrier
	s_waitcnt lgkmcnt(0)
	v_mfma_f32_16x16x32_bf16 v[142:145], v[58:61], v[184:187], v[142:145]
	v_mfma_f32_16x16x32_bf16 v[138:141], v[74:77], v[184:187], v[138:141]
	v_mfma_f32_16x16x32_bf16 v[126:129], v[58:61], v[192:195], v[126:129]
	v_mfma_f32_16x16x32_bf16 v[122:125], v[74:77], v[192:195], v[122:125]
	v_mfma_f32_16x16x32_bf16 v[110:113], v[58:61], v[200:203], v[110:113]
	v_mfma_f32_16x16x32_bf16 v[106:109], v[74:77], v[200:203], v[106:109]
	v_mfma_f32_16x16x32_bf16 v[94:97], v[58:61], v[208:211], v[94:97]
	v_mfma_f32_16x16x32_bf16 v[90:93], v[74:77], v[208:211], v[90:93]
	v_mfma_f32_16x16x32_bf16 v[142:145], v[62:65], v[188:191], v[142:145]
	v_mfma_f32_16x16x32_bf16 v[138:141], v[78:81], v[188:191], v[138:141]
	v_mfma_f32_16x16x32_bf16 v[126:129], v[62:65], v[196:199], v[126:129]
	v_mfma_f32_16x16x32_bf16 v[122:125], v[78:81], v[196:199], v[122:125]
	v_mfma_f32_16x16x32_bf16 v[110:113], v[62:65], v[204:207], v[110:113]
	v_mfma_f32_16x16x32_bf16 v[106:109], v[78:81], v[204:207], v[106:109]
	v_mfma_f32_16x16x32_bf16 v[94:97], v[62:65], v[212:215], v[94:97]
	v_mfma_f32_16x16x32_bf16 v[90:93], v[78:81], v[212:215], v[90:93]
	v_mfma_f32_16x16x32_bf16 v[134:137], v[164:167], v[184:187], v[134:137]
	v_mfma_f32_16x16x32_bf16 v[130:133], v[176:179], v[184:187], v[130:133]
	v_mfma_f32_16x16x32_bf16 v[118:121], v[164:167], v[192:195], v[118:121]
	v_mfma_f32_16x16x32_bf16 v[114:117], v[176:179], v[192:195], v[114:117]
	v_mfma_f32_16x16x32_bf16 v[102:105], v[164:167], v[200:203], v[102:105]
	v_mfma_f32_16x16x32_bf16 v[98:101], v[176:179], v[200:203], v[98:101]
	v_mfma_f32_16x16x32_bf16 v[86:89], v[164:167], v[208:211], v[86:89]
	v_mfma_f32_16x16x32_bf16 v[82:85], v[176:179], v[208:211], v[82:85]
	v_mfma_f32_16x16x32_bf16 v[134:137], v[168:171], v[188:191], v[134:137]
	v_mfma_f32_16x16x32_bf16 v[130:133], v[180:183], v[188:191], v[130:133]
	v_mfma_f32_16x16x32_bf16 v[118:121], v[168:171], v[196:199], v[118:121]
	v_mfma_f32_16x16x32_bf16 v[114:117], v[180:183], v[196:199], v[114:117]
	v_mfma_f32_16x16x32_bf16 v[102:105], v[168:171], v[204:207], v[102:105]
	v_mfma_f32_16x16x32_bf16 v[98:101], v[180:183], v[204:207], v[98:101]
	v_mfma_f32_16x16x32_bf16 v[86:89], v[168:171], v[212:215], v[86:89]
	v_mfma_f32_16x16x32_bf16 v[82:85], v[180:183], v[212:215], v[82:85]
	s_barrier
	s_add_i32 s24, s56, s30
	s_add_i32 m0, s24, 0xffffff80
	ds_read_b128 v[184:187], v174 offset:49152
	ds_read_b128 v[188:191], v174 offset:50176
	ds_read_b128 v[192:195], v174 offset:51200
	ds_read_b128 v[196:199], v174 offset:52224
	ds_read_b128 v[200:203], v174 offset:53248
	ds_read_b128 v[204:207], v174 offset:54272
	ds_read_b128 v[208:211], v174 offset:55296
	ds_read_b128 v[212:215], v174 offset:56320
	global_load_lds_dwordx4 v148, s[98:99] offset:128
	s_add_i32 m0, s24, 0x1f80
	s_add_u32 s22, s22, 0x20080
	s_addc_u32 s23, s23, 0
	s_add_i32 s24, s57, s30
	global_load_lds_dwordx4 v152, s[98:99] offset:128
	s_mov_b32 m0, s24
	s_nop 0
	global_load_lds_dwordx4 v148, s[22:23]
	s_add_i32 m0, s24, 0x2000
	s_nop 0
	global_load_lds_dwordx4 v152, s[22:23]
	s_add_i32 m0, s40, 0xffffff80
	s_nop 0
	global_load_lds_dwordx4 v146, s[100:101] offset:128
	s_add_i32 m0, s41, 0xffffff80
	s_nop 0
	global_load_lds_dwordx4 v150, s[100:101] offset:128
	s_waitcnt vmcnt(8)
	s_waitcnt lgkmcnt(0)
	s_barrier
	s_waitcnt lgkmcnt(0)
	v_mfma_f32_16x16x32_bf16 v[70:73], v[58:61], v[184:187], v[70:73]
	v_mfma_f32_16x16x32_bf16 v[66:69], v[74:77], v[184:187], v[66:69]
	v_mfma_f32_16x16x32_bf16 v[46:49], v[58:61], v[192:195], v[46:49]
	v_mfma_f32_16x16x32_bf16 v[42:45], v[74:77], v[192:195], v[42:45]
	v_mfma_f32_16x16x32_bf16 v[30:33], v[58:61], v[200:203], v[30:33]
	v_mfma_f32_16x16x32_bf16 v[26:29], v[74:77], v[200:203], v[26:29]
	v_mfma_f32_16x16x32_bf16 v[14:17], v[58:61], v[208:211], v[14:17]
	v_mfma_f32_16x16x32_bf16 v[10:13], v[74:77], v[208:211], v[10:13]
	v_mfma_f32_16x16x32_bf16 v[70:73], v[62:65], v[188:191], v[70:73]
	v_mfma_f32_16x16x32_bf16 v[66:69], v[78:81], v[188:191], v[66:69]
	v_mfma_f32_16x16x32_bf16 v[46:49], v[62:65], v[196:199], v[46:49]
	v_mfma_f32_16x16x32_bf16 v[42:45], v[78:81], v[196:199], v[42:45]
	v_mfma_f32_16x16x32_bf16 v[30:33], v[62:65], v[204:207], v[30:33]
	v_mfma_f32_16x16x32_bf16 v[26:29], v[78:81], v[204:207], v[26:29]
	v_mfma_f32_16x16x32_bf16 v[14:17], v[62:65], v[212:215], v[14:17]
	v_mfma_f32_16x16x32_bf16 v[10:13], v[78:81], v[212:215], v[10:13]
	v_mfma_f32_16x16x32_bf16 v[54:57], v[164:167], v[184:187], v[54:57]
	v_mfma_f32_16x16x32_bf16 v[50:53], v[176:179], v[184:187], v[50:53]
	v_mfma_f32_16x16x32_bf16 v[38:41], v[164:167], v[192:195], v[38:41]
	v_mfma_f32_16x16x32_bf16 v[34:37], v[176:179], v[192:195], v[34:37]
	v_mfma_f32_16x16x32_bf16 v[22:25], v[164:167], v[200:203], v[22:25]
	v_mfma_f32_16x16x32_bf16 v[18:21], v[176:179], v[200:203], v[18:21]
	v_mfma_f32_16x16x32_bf16 v[6:9], v[164:167], v[208:211], v[6:9]
	v_mfma_f32_16x16x32_bf16 v[2:5], v[176:179], v[208:211], v[2:5]
	v_mfma_f32_16x16x32_bf16 v[54:57], v[168:171], v[188:191], v[54:57]
	v_mfma_f32_16x16x32_bf16 v[50:53], v[180:183], v[188:191], v[50:53]
	v_mfma_f32_16x16x32_bf16 v[38:41], v[168:171], v[196:199], v[38:41]
	v_mfma_f32_16x16x32_bf16 v[34:37], v[180:183], v[196:199], v[34:37]
	v_mfma_f32_16x16x32_bf16 v[22:25], v[168:171], v[204:207], v[22:25]
	v_mfma_f32_16x16x32_bf16 v[18:21], v[180:183], v[204:207], v[18:21]
	v_mfma_f32_16x16x32_bf16 v[6:9], v[168:171], v[212:215], v[6:9]
	v_mfma_f32_16x16x32_bf16 v[2:5], v[180:183], v[212:215], v[2:5]
	s_barrier
	s_add_u32 s8, s8, 0x100
	s_addc_u32 s9, s9, 0
	s_add_u32 s17, s17, 0x100
	s_addc_u32 s19, s19, 0
	s_cmp_ge_u32 s47, s7
	s_mov_b32 s22, s47
	s_cbranch_scc0 .LBB0_1092
	s_and_b64 vcc, exec, s[14:15]
	s_cbranch_vccz .LBB0_1095
	s_barrier

; #define PG8_STAGE(bufoff, gbase, voff) do { _Pragma("unroll") for (int _i = 0; _i < 2; ++_i) \
;         __builtin_amdgcn_global_load_lds((const unsigned*)((const char*)(gbase) + (voff)[_i]), (PG8_LAS unsigned*)(lds + (bufoff) + ldsw + _i * 8192), 16, 0, 0); } while (0)
; #define PG8_LDA(dst, b, h) do { _Pragma("unroll") for (int m = 0; m < 4; ++m) _Pragma("unroll") for (int k = 0; k < 2; ++k) dst[m][k] = *(const PG8_LAS bf16x8*)(lds + PG8_SA(b, h) + aoff + m * 2048 + k * 1024); } while (0)
; #define PG8_LDB(dst, b, h) do { _Pragma("unroll") for (int n = 0; n < 2; ++n) _Pragma("unroll") for (int k = 0; k < 2; ++k) dst[n][k] = *(const PG8_LAS bf16x8*)(lds + PG8_SB(b, h) + boff + n * 2048 + k * 1024); } while (0)
; #define PG8_MMA(ai, bj, At, Bt) do { __builtin_amdgcn_s_setprio(1); _Pragma("unroll") for (int m = 0; m < 4; ++m) _Pragma("unroll") for (int n = 0; n < 2; ++n) _Pragma("unroll") for (int k = 0; k < 2; ++k) \
;         acc[ai][bj][m][n] = mma_<I8>(Bt[n][k], At[m][k], acc[ai][bj][m][n]); __builtin_amdgcn_s_setprio(0); } while (0)
; #define PG8_WAIT_V(n) asm volatile("s_waitcnt vmcnt(" #n ")" ::: "memory")
; #define PG8_WAIT_L(n) asm volatile("s_waitcnt lgkmcnt(" #n ")" ::: "memory")
; #define PG8_BAR __builtin_amdgcn_s_barrier()
; template <class Epi, class Sched, bool ALIGN_EPI = false, bool SP2 = false, bool I8 = false>
; __device__ __forceinline__ void gemm_phase(PG8_LAS unsigned char* lds, const Gemm g, const Sched& S, const Epi& E) {
;     ...
;             const bool last = (t == nt - 2);
;             const char* a1 = cA + (size_t)(t + 1) * kstep;
;             const char* a2 = last ? nA : cA + (size_t)(t + 2) * kstep; const char* b2 = last ? nB : cB + (size_t)(t + 2) * kstep;
;             const char* a3 = a2 + kstep; const char* b3 = b2 + kstep;
;             if (last && has_next) S.a_ready(nxt);
;             if constexpr (SP2) {
;             PG8_LDB(B0, 0, 0); PG8_LDB(B1, 0, 1); PG8_SCHED; PG8_LDA(At, 0, 0); PG8_STAGE(PG8_SA(1, 1), a1 + hstepA, voffA);
;             PG8_WAIT_V(8); PG8_WAIT_L(0); PG8_BAR; PG8_MMA(0, 0, At, B0); PG8_MMA(0, 1, At, B1); PG8_BAR; PG8_SCHED;
;             PG8_LDA(At, 0, 1); PG8_STAGE(PG8_SB(0, 0), b2, voffB); PG8_STAGE(PG8_SB(0, 1), b2 + hstepB, voffB); PG8_STAGE(PG8_SA(0, 0), a2, voffA);
;             PG8_WAIT_V(8); PG8_WAIT_L(0); PG8_BAR; PG8_MMA(1, 0, At, B0); PG8_MMA(1, 1, At, B1); PG8_BAR; PG8_SCHED;
.LBB0_1538:
	ds_read_b128 v[146:149], v154
	ds_read_b128 v[150:153], v154 offset:1024
	ds_read_b128 v[158:161], v154 offset:2048
	ds_read_b128 v[162:165], v154 offset:3072
	ds_read_b128 v[166:169], v155
	ds_read_b128 v[170:173], v155 offset:1024
	ds_read_b128 v[174:177], v155 offset:2048
	ds_read_b128 v[178:181], v155 offset:3072
	s_add_u32 s24, s22, 0xfffe0080
	s_addc_u32 s25, s23, -1
	s_cmp_eq_u32 s49, 4
	s_cselect_b32 s27, s15, s25
	s_cselect_b32 s26, s45, s24
	s_cselect_b32 s25, s13, s48
	s_cselect_b32 s24, s46, s47
	s_add_i32 m0, s21, 0xc000
	ds_read_b128 v[182:185], v156
	ds_read_b128 v[186:189], v156 offset:1024
	ds_read_b128 v[190:193], v156 offset:2048
	ds_read_b128 v[194:197], v156 offset:3072
	ds_read_b128 v[198:201], v156 offset:4096
	ds_read_b128 v[202:205], v156 offset:5120
	ds_read_b128 v[206:209], v156 offset:6144
	ds_read_b128 v[210:213], v156 offset:7168
	global_load_lds_dwordx4 v138, s[22:23]
	s_add_i32 m0, s21, 0xe000
	s_nop 0
	global_load_lds_dwordx4 v140, s[22:23]
	s_waitcnt vmcnt(8)
	s_waitcnt lgkmcnt(0)
	s_barrier
	s_waitcnt lgkmcnt(0)
	v_mfma_f32_16x16x32_bf16 v[126:129], v[146:149], v[182:185], v[126:129]
	v_mfma_f32_16x16x32_bf16 v[122:125], v[158:161], v[182:185], v[122:125]
	v_mfma_f32_16x16x32_bf16 v[114:117], v[146:149], v[190:193], v[114:117]
	v_mfma_f32_16x16x32_bf16 v[106:109], v[158:161], v[190:193], v[106:109]
	v_mfma_f32_16x16x32_bf16 v[94:97], v[146:149], v[198:201], v[94:97]
	v_mfma_f32_16x16x32_bf16 v[90:93], v[158:161], v[198:201], v[90:93]
	v_mfma_f32_16x16x32_bf16 v[86:89], v[146:149], v[206:209], v[86:89]
	v_mfma_f32_16x16x32_bf16 v[82:85], v[158:161], v[206:209], v[82:85]
	v_mfma_f32_16x16x32_bf16 v[126:129], v[150:153], v[186:189], v[126:129]
	v_mfma_f32_16x16x32_bf16 v[122:125], v[162:165], v[186:189], v[122:125]
	v_mfma_f32_16x16x32_bf16 v[114:117], v[150:153], v[194:197], v[114:117]
	v_mfma_f32_16x16x32_bf16 v[106:109], v[162:165], v[194:197], v[106:109]
	v_mfma_f32_16x16x32_bf16 v[94:97], v[150:153], v[202:205], v[94:97]
	v_mfma_f32_16x16x32_bf16 v[90:93], v[162:165], v[202:205], v[90:93]
	v_mfma_f32_16x16x32_bf16 v[86:89], v[150:153], v[210:213], v[86:89]
	v_mfma_f32_16x16x32_bf16 v[82:85], v[162:165], v[210:213], v[82:85]
	v_mfma_f32_16x16x32_bf16 v[118:121], v[166:169], v[182:185], v[118:121]
	v_mfma_f32_16x16x32_bf16 v[110:113], v[174:177], v[182:185], v[110:113]
	v_mfma_f32_16x16x32_bf16 v[102:105], v[166:169], v[190:193], v[102:105]
	v_mfma_f32_16x16x32_bf16 v[98:101], v[174:177], v[190:193], v[98:101]
	v_mfma_f32_16x16x32_bf16 v[78:81], v[166:169], v[198:201], v[78:81]
	v_mfma_f32_16x16x32_bf16 v[74:77], v[174:177], v[198:201], v[74:77]
	v_mfma_f32_16x16x32_bf16 v[70:73], v[166:169], v[206:209], v[70:73]
	v_mfma_f32_16x16x32_bf16 v[66:69], v[174:177], v[206:209], v[66:69]
	v_mfma_f32_16x16x32_bf16 v[118:121], v[170:173], v[186:189], v[118:121]
	v_mfma_f32_16x16x32_bf16 v[110:113], v[178:181], v[186:189], v[110:113]
	v_mfma_f32_16x16x32_bf16 v[102:105], v[170:173], v[194:197], v[102:105]
	v_mfma_f32_16x16x32_bf16 v[98:101], v[178:181], v[194:197], v[98:101]
	v_mfma_f32_16x16x32_bf16 v[78:81], v[170:173], v[202:205], v[78:81]
	v_mfma_f32_16x16x32_bf16 v[74:77], v[178:181], v[202:205], v[74:77]
	v_mfma_f32_16x16x32_bf16 v[70:73], v[170:173], v[210:213], v[70:73]
	v_mfma_f32_16x16x32_bf16 v[66:69], v[178:181], v[210:213], v[66:69]
	s_barrier
	s_add_i32 s50, s42, s34
	s_mov_b64 s[98:99], s[24:25]
	s_mov_b32 m0, s50
	ds_read_b128 v[182:185], v156 offset:16384
	ds_read_b128 v[186:189], v156 offset:17408
	ds_read_b128 v[190:193], v156 offset:18432
	ds_read_b128 v[194:197], v156 offset:19456
	ds_read_b128 v[198:201], v156 offset:20480
	ds_read_b128 v[202:205], v156 offset:21504
	ds_read_b128 v[206:209], v156 offset:22528
	ds_read_b128 v[210:213], v156 offset:23552
	global_load_lds_dwordx4 v132, s[24:25]
	s_add_i32 m0, s50, 0x2000
	s_add_u32 s50, s24, 0x20000
	s_mov_b64 s[98:99], s[24:25]
	s_addc_u32 s51, s25, 0
	s_add_i32 s52, s43, s34
	global_load_lds_dwordx4 v136, s[24:25]
	s_mov_b32 m0, s52
	s_mov_b64 s[100:101], s[26:27]
	global_load_lds_dwordx4 v132, s[50:51]
	s_add_i32 m0, s52, 0x2000
	s_nop 0
	global_load_lds_dwordx4 v136, s[50:51]
	s_mov_b64 s[100:101], s[26:27]
	s_mov_b32 m0, s21
	s_nop 0
	global_load_lds_dwordx4 v130, s[26:27]
	s_mov_b32 m0, s35
	s_nop 0
	global_load_lds_dwordx4 v134, s[26:27]
	s_waitcnt vmcnt(8)
	s_waitcnt lgkmcnt(0)
	s_barrier
	s_waitcnt lgkmcnt(0)
	v_mfma_f32_16x16x32_bf16 v[62:65], v[146:149], v[182:185], v[62:65]
	v_mfma_f32_16x16x32_bf16 v[58:61], v[158:161], v[182:185], v[58:61]
	v_mfma_f32_16x16x32_bf16 v[54:57], v[146:149], v[190:193], v[54:57]
	v_mfma_f32_16x16x32_bf16 v[50:53], v[158:161], v[190:193], v[50:53]
	v_mfma_f32_16x16x32_bf16 v[30:33], v[146:149], v[198:201], v[30:33]
	v_mfma_f32_16x16x32_bf16 v[26:29], v[158:161], v[198:201], v[26:29]
	v_mfma_f32_16x16x32_bf16 v[22:25], v[146:149], v[206:209], v[22:25]
	v_mfma_f32_16x16x32_bf16 v[10:13], v[158:161], v[206:209], v[10:13]
	v_mfma_f32_16x16x32_bf16 v[62:65], v[150:153], v[186:189], v[62:65]
	v_mfma_f32_16x16x32_bf16 v[58:61], v[162:165], v[186:189], v[58:61]
	v_mfma_f32_16x16x32_bf16 v[54:57], v[150:153], v[194:197], v[54:57]
	v_mfma_f32_16x16x32_bf16 v[50:53], v[162:165], v[194:197], v[50:53]
	v_mfma_f32_16x16x32_bf16 v[30:33], v[150:153], v[202:205], v[30:33]
	v_mfma_f32_16x16x32_bf16 v[26:29], v[162:165], v[202:205], v[26:29]
	v_mfma_f32_16x16x32_bf16 v[22:25], v[150:153], v[210:213], v[22:25]
	v_mfma_f32_16x16x32_bf16 v[10:13], v[162:165], v[210:213], v[10:13]
	v_mfma_f32_16x16x32_bf16 v[46:49], v[166:169], v[182:185], v[46:49]
	v_mfma_f32_16x16x32_bf16 v[42:45], v[174:177], v[182:185], v[42:45]
	v_mfma_f32_16x16x32_bf16 v[38:41], v[166:169], v[190:193], v[38:41]
	v_mfma_f32_16x16x32_bf16 v[34:37], v[174:177], v[190:193], v[34:37]
	v_mfma_f32_16x16x32_bf16 v[18:21], v[166:169], v[198:201], v[18:21]
	v_mfma_f32_16x16x32_bf16 v[14:17], v[174:177], v[198:201], v[14:17]
	v_mfma_f32_16x16x32_bf16 v[6:9], v[166:169], v[206:209], v[6:9]
	v_mfma_f32_16x16x32_bf16 v[2:5], v[174:177], v[206:209], v[2:5]
	v_mfma_f32_16x16x32_bf16 v[46:49], v[170:173], v[186:189], v[46:49]
	v_mfma_f32_16x16x32_bf16 v[42:45], v[178:181], v[186:189], v[42:45]
	v_mfma_f32_16x16x32_bf16 v[38:41], v[170:173], v[194:197], v[38:41]
	v_mfma_f32_16x16x32_bf16 v[34:37], v[178:181], v[194:197], v[34:37]
	v_mfma_f32_16x16x32_bf16 v[18:21], v[170:173], v[202:205], v[18:21]
	v_mfma_f32_16x16x32_bf16 v[14:17], v[178:181], v[202:205], v[14:17]
	v_mfma_f32_16x16x32_bf16 v[6:9], v[170:173], v[210:213], v[6:9]
	v_mfma_f32_16x16x32_bf16 v[2:5], v[178:181], v[210:213], v[2:5]
	s_barrier
; #define PG8_STAGE(bufoff, gbase, voff) do { _Pragma("unroll") for (int _i = 0; _i < 2; ++_i) \
;         __builtin_amdgcn_global_load_lds((const unsigned*)((const char*)(gbase) + (voff)[_i]), (PG8_LAS unsigned*)(lds + (bufoff) + ldsw + _i * 8192), 16, 0, 0); } while (0)
; #define PG8_LDA(dst, b, h) do { _Pragma("unroll") for (int m = 0; m < 4; ++m) _Pragma("unroll") for (int k = 0; k < 2; ++k) dst[m][k] = *(const PG8_LAS bf16x8*)(lds + PG8_SA(b, h) + aoff + m * 2048 + k * 1024); } while (0)
; #define PG8_WAIT_V(n) asm volatile("s_waitcnt vmcnt(" #n ")" ::: "memory")
; #define PG8_WAIT_L(n) asm volatile("s_waitcnt lgkmcnt(" #n ")" ::: "memory")
; #define PG8_BAR __builtin_amdgcn_s_barrier()
; template <class Epi, class Sched, bool ALIGN_EPI = false, bool SP2 = false, bool I8 = false>
; __device__ __forceinline__ void gemm_phase(PG8_LAS unsigned char* lds, const Gemm g, const Sched& S, const Epi& E) {
;     ...
;         for (int t = 0; t < nt; t += 2) {
;             const bool last = (t == nt - 2);
;             const char* a1 = cA + (size_t)(t + 1) * kstep;
;             const char* a2 = last ? nA : cA + (size_t)(t + 2) * kstep; const char* b2 = last ? nB : cB + (size_t)(t + 2) * kstep;
;             const char* a3 = a2 + kstep; const char* b3 = b2 + kstep;
;             if (last && has_next) S.a_ready(nxt);
;             if constexpr (SP2) {
;             PG8_LDB(B0, 0, 0); PG8_LDB(B1, 0, 1); PG8_SCHED; PG8_LDA(At, 0, 0); PG8_STAGE(PG8_SA(1, 1), a1 + hstepA, voffA);
;             PG8_WAIT_V(8); PG8_WAIT_L(0); PG8_BAR; PG8_MMA(0, 0, At, B0); PG8_MMA(0, 1, At, B1); PG8_BAR; PG8_SCHED;
;             PG8_LDA(At, 0, 1); PG8_STAGE(PG8_SB(0, 0), b2, voffB); PG8_STAGE(PG8_SB(0, 1), b2 + hstepB, voffB); PG8_STAGE(PG8_SA(0, 0), a2, voffA);
;             PG8_WAIT_V(8); PG8_WAIT_L(0); PG8_BAR; PG8_MMA(1, 0, At, B0); PG8_MMA(1, 1, At, B1); PG8_BAR; PG8_SCHED;
;             PG8_LDB(B0, 1, 0); PG8_LDB(B1, 1, 1); PG8_SCHED; PG8_LDA(At, 1, 0); PG8_STAGE(PG8_SA(0, 1), a2 + hstepA, voffA);
;             PG8_WAIT_V(8); PG8_WAIT_L(0); PG8_BAR; PG8_MMA(0, 0, At, B0); PG8_MMA(0, 1, At, B1); PG8_BAR; PG8_SCHED;
;             PG8_LDA(At, 1, 1); PG8_STAGE(PG8_SB(1, 0), b3, voffB); PG8_STAGE(PG8_SB(1, 1), b3 + hstepB, voffB); PG8_STAGE(PG8_SA(1, 0), a3, voffA);
;             PG8_WAIT_V(8); PG8_WAIT_L(0); PG8_BAR; PG8_MMA(1, 0, At, B0); PG8_MMA(1, 1, At, B1); PG8_BAR; PG8_SCHED;
	s_add_i32 s50, 0, 0x18000
	v_add_u32_e32 v157, s50, v1
	s_add_i32 s51, 0, 0x1c000
	ds_read_b128 v[146:149], v157
	ds_read_b128 v[150:153], v157 offset:1024
	ds_read_b128 v[158:161], v157 offset:2048
	ds_read_b128 v[162:165], v157 offset:3072
	v_add_u32_e32 v157, s51, v1
	ds_read_b128 v[166:169], v157
	ds_read_b128 v[170:173], v157 offset:1024
	ds_read_b128 v[174:177], v157 offset:2048
	ds_read_b128 v[178:181], v157 offset:3072
	s_add_u32 s26, s26, 0x20000
	s_addc_u32 s27, s27, 0
	s_mov_b32 m0, s36
	ds_read_b128 v[182:185], v156 offset:32768
	ds_read_b128 v[186:189], v156 offset:33792
	ds_read_b128 v[190:193], v156 offset:34816
	ds_read_b128 v[194:197], v156 offset:35840
	ds_read_b128 v[198:201], v156 offset:36864
	ds_read_b128 v[202:205], v156 offset:37888
	ds_read_b128 v[206:209], v156 offset:38912
	ds_read_b128 v[210:213], v156 offset:39936
	global_load_lds_dwordx4 v130, s[26:27]
	s_mov_b32 m0, s37
	s_nop 0
	global_load_lds_dwordx4 v134, s[26:27]
	s_waitcnt vmcnt(8)
	s_waitcnt lgkmcnt(0)
	s_barrier
	s_waitcnt lgkmcnt(0)
	v_mfma_f32_16x16x32_bf16 v[126:129], v[146:149], v[182:185], v[126:129]
	v_mfma_f32_16x16x32_bf16 v[122:125], v[158:161], v[182:185], v[122:125]
	v_mfma_f32_16x16x32_bf16 v[114:117], v[146:149], v[190:193], v[114:117]
	v_mfma_f32_16x16x32_bf16 v[106:109], v[158:161], v[190:193], v[106:109]
	v_mfma_f32_16x16x32_bf16 v[94:97], v[146:149], v[198:201], v[94:97]
	v_mfma_f32_16x16x32_bf16 v[90:93], v[158:161], v[198:201], v[90:93]
	v_mfma_f32_16x16x32_bf16 v[86:89], v[146:149], v[206:209], v[86:89]
	v_mfma_f32_16x16x32_bf16 v[82:85], v[158:161], v[206:209], v[82:85]
	v_mfma_f32_16x16x32_bf16 v[126:129], v[150:153], v[186:189], v[126:129]
	v_mfma_f32_16x16x32_bf16 v[122:125], v[162:165], v[186:189], v[122:125]
	v_mfma_f32_16x16x32_bf16 v[114:117], v[150:153], v[194:197], v[114:117]
	v_mfma_f32_16x16x32_bf16 v[106:109], v[162:165], v[194:197], v[106:109]
	v_mfma_f32_16x16x32_bf16 v[94:97], v[150:153], v[202:205], v[94:97]
	v_mfma_f32_16x16x32_bf16 v[90:93], v[162:165], v[202:205], v[90:93]
	v_mfma_f32_16x16x32_bf16 v[86:89], v[150:153], v[210:213], v[86:89]
	v_mfma_f32_16x16x32_bf16 v[82:85], v[162:165], v[210:213], v[82:85]
	v_mfma_f32_16x16x32_bf16 v[118:121], v[166:169], v[182:185], v[118:121]
	v_mfma_f32_16x16x32_bf16 v[110:113], v[174:177], v[182:185], v[110:113]
	v_mfma_f32_16x16x32_bf16 v[102:105], v[166:169], v[190:193], v[102:105]
	v_mfma_f32_16x16x32_bf16 v[98:101], v[174:177], v[190:193], v[98:101]
	v_mfma_f32_16x16x32_bf16 v[78:81], v[166:169], v[198:201], v[78:81]
	v_mfma_f32_16x16x32_bf16 v[74:77], v[174:177], v[198:201], v[74:77]
	v_mfma_f32_16x16x32_bf16 v[70:73], v[166:169], v[206:209], v[70:73]
	v_mfma_f32_16x16x32_bf16 v[66:69], v[174:177], v[206:209], v[66:69]
	v_mfma_f32_16x16x32_bf16 v[118:121], v[170:173], v[186:189], v[118:121]
	v_mfma_f32_16x16x32_bf16 v[110:113], v[178:181], v[186:189], v[110:113]
	v_mfma_f32_16x16x32_bf16 v[102:105], v[170:173], v[194:197], v[102:105]
	v_mfma_f32_16x16x32_bf16 v[98:101], v[178:181], v[194:197], v[98:101]
	v_mfma_f32_16x16x32_bf16 v[78:81], v[170:173], v[202:205], v[78:81]
	v_mfma_f32_16x16x32_bf16 v[74:77], v[178:181], v[202:205], v[74:77]
	v_mfma_f32_16x16x32_bf16 v[70:73], v[170:173], v[210:213], v[70:73]
	v_mfma_f32_16x16x32_bf16 v[66:69], v[178:181], v[210:213], v[66:69]
	s_barrier
	s_add_i32 s26, s50, s34
	s_add_i32 m0, s26, 0xffffff80
	ds_read_b128 v[182:185], v156 offset:49152
	ds_read_b128 v[186:189], v156 offset:50176
	ds_read_b128 v[190:193], v156 offset:51200
	ds_read_b128 v[194:197], v156 offset:52224
	ds_read_b128 v[198:201], v156 offset:53248
	ds_read_b128 v[202:205], v156 offset:54272
	ds_read_b128 v[206:209], v156 offset:55296
	ds_read_b128 v[210:213], v156 offset:56320
	global_load_lds_dwordx4 v132, s[98:99] offset:128
	s_add_i32 m0, s26, 0x1f80
	s_add_u32 s24, s24, 0x20080
	s_addc_u32 s25, s25, 0
	s_add_i32 s26, s51, s34
	global_load_lds_dwordx4 v136, s[98:99] offset:128
	s_mov_b32 m0, s26
	s_nop 0
	global_load_lds_dwordx4 v132, s[24:25]
	s_add_i32 m0, s26, 0x2000
	s_nop 0
	global_load_lds_dwordx4 v136, s[24:25]
	s_add_i32 m0, s39, 0xffffff80
	s_nop 0
	global_load_lds_dwordx4 v130, s[100:101] offset:128
	s_add_i32 m0, s40, 0xffffff80
	s_nop 0
	global_load_lds_dwordx4 v134, s[100:101] offset:128
	s_waitcnt vmcnt(8)
	s_waitcnt lgkmcnt(0)
	s_barrier
	s_waitcnt lgkmcnt(0)
	v_mfma_f32_16x16x32_bf16 v[62:65], v[146:149], v[182:185], v[62:65]
	v_mfma_f32_16x16x32_bf16 v[58:61], v[158:161], v[182:185], v[58:61]
	v_mfma_f32_16x16x32_bf16 v[54:57], v[146:149], v[190:193], v[54:57]
	v_mfma_f32_16x16x32_bf16 v[50:53], v[158:161], v[190:193], v[50:53]
	v_mfma_f32_16x16x32_bf16 v[30:33], v[146:149], v[198:201], v[30:33]
	v_mfma_f32_16x16x32_bf16 v[26:29], v[158:161], v[198:201], v[26:29]
	v_mfma_f32_16x16x32_bf16 v[22:25], v[146:149], v[206:209], v[22:25]
	v_mfma_f32_16x16x32_bf16 v[10:13], v[158:161], v[206:209], v[10:13]
	v_mfma_f32_16x16x32_bf16 v[62:65], v[150:153], v[186:189], v[62:65]
	v_mfma_f32_16x16x32_bf16 v[58:61], v[162:165], v[186:189], v[58:61]
	v_mfma_f32_16x16x32_bf16 v[54:57], v[150:153], v[194:197], v[54:57]
	v_mfma_f32_16x16x32_bf16 v[50:53], v[162:165], v[194:197], v[50:53]
	v_mfma_f32_16x16x32_bf16 v[30:33], v[150:153], v[202:205], v[30:33]
	v_mfma_f32_16x16x32_bf16 v[26:29], v[162:165], v[202:205], v[26:29]
	v_mfma_f32_16x16x32_bf16 v[22:25], v[150:153], v[210:213], v[22:25]
	v_mfma_f32_16x16x32_bf16 v[10:13], v[162:165], v[210:213], v[10:13]
	v_mfma_f32_16x16x32_bf16 v[46:49], v[166:169], v[182:185], v[46:49]
	v_mfma_f32_16x16x32_bf16 v[42:45], v[174:177], v[182:185], v[42:45]
	v_mfma_f32_16x16x32_bf16 v[38:41], v[166:169], v[190:193], v[38:41]
	v_mfma_f32_16x16x32_bf16 v[34:37], v[174:177], v[190:193], v[34:37]
	v_mfma_f32_16x16x32_bf16 v[18:21], v[166:169], v[198:201], v[18:21]
	v_mfma_f32_16x16x32_bf16 v[14:17], v[174:177], v[198:201], v[14:17]
	v_mfma_f32_16x16x32_bf16 v[6:9], v[166:169], v[206:209], v[6:9]
	v_mfma_f32_16x16x32_bf16 v[2:5], v[174:177], v[206:209], v[2:5]
	v_mfma_f32_16x16x32_bf16 v[46:49], v[170:173], v[186:189], v[46:49]
	v_mfma_f32_16x16x32_bf16 v[42:45], v[178:181], v[186:189], v[42:45]
	v_mfma_f32_16x16x32_bf16 v[38:41], v[170:173], v[194:197], v[38:41]
	v_mfma_f32_16x16x32_bf16 v[34:37], v[178:181], v[194:197], v[34:37]
	v_mfma_f32_16x16x32_bf16 v[18:21], v[170:173], v[202:205], v[18:21]
	v_mfma_f32_16x16x32_bf16 v[14:17], v[178:181], v[202:205], v[14:17]
	v_mfma_f32_16x16x32_bf16 v[6:9], v[170:173], v[210:213], v[6:9]
	v_mfma_f32_16x16x32_bf16 v[2:5], v[178:181], v[210:213], v[2:5]
	s_barrier
	s_add_i32 s49, s49, 2
	s_add_u32 s22, s22, 0x100
	s_addc_u32 s23, s23, 0
	s_add_u32 s47, s47, 0x100
	s_addc_u32 s48, s48, 0
	s_cmp_gt_u32 s49, 5
	s_cbranch_scc0 .LBB0_1538
	s_and_b64 vcc, exec, s[10:11]
	s_cbranch_vccz .LBB0_1541
	s_barrier

; #define PG8_STAGE(bufoff, gbase, voff) do { _Pragma("unroll") for (int _i = 0; _i < 2; ++_i) \
;         __builtin_amdgcn_global_load_lds((const unsigned*)((const char*)(gbase) + (voff)[_i]), (PG8_LAS unsigned*)(lds + (bufoff) + ldsw + _i * 8192), 16, 0, 0); } while (0)
; #define PG8_LDA(dst, b, h) do { _Pragma("unroll") for (int m = 0; m < 4; ++m) _Pragma("unroll") for (int k = 0; k < 2; ++k) dst[m][k] = *(const PG8_LAS bf16x8*)(lds + PG8_SA(b, h) + aoff + m * 2048 + k * 1024); } while (0)
; #define PG8_LDB(dst, b, h) do { _Pragma("unroll") for (int n = 0; n < 2; ++n) _Pragma("unroll") for (int k = 0; k < 2; ++k) dst[n][k] = *(const PG8_LAS bf16x8*)(lds + PG8_SB(b, h) + boff + n * 2048 + k * 1024); } while (0)
; #define PG8_MMA(ai, bj, At, Bt) do { __builtin_amdgcn_s_setprio(1); _Pragma("unroll") for (int m = 0; m < 4; ++m) _Pragma("unroll") for (int n = 0; n < 2; ++n) _Pragma("unroll") for (int k = 0; k < 2; ++k) \
;         acc[ai][bj][m][n] = mma_<I8>(Bt[n][k], At[m][k], acc[ai][bj][m][n]); __builtin_amdgcn_s_setprio(0); } while (0)
; #define PG8_WAIT_V(n) asm volatile("s_waitcnt vmcnt(" #n ")" ::: "memory")
; #define PG8_WAIT_L(n) asm volatile("s_waitcnt lgkmcnt(" #n ")" ::: "memory")
; #define PG8_BAR __builtin_amdgcn_s_barrier()
; template <class Epi, class Sched, bool ALIGN_EPI = false, bool SP2 = false, bool I8 = false>
; __device__ __forceinline__ void gemm_phase(PG8_LAS unsigned char* lds, const Gemm g, const Sched& S, const Epi& E) {
;     ...
;             const bool last = (t == nt - 2);
;             const char* a1 = cA + (size_t)(t + 1) * kstep;
;             const char* a2 = last ? nA : cA + (size_t)(t + 2) * kstep; const char* b2 = last ? nB : cB + (size_t)(t + 2) * kstep;
;             const char* a3 = a2 + kstep; const char* b3 = b2 + kstep;
;             if (last && has_next) S.a_ready(nxt);
;             if constexpr (SP2) {
;             PG8_LDB(B0, 0, 0); PG8_LDB(B1, 0, 1); PG8_SCHED; PG8_LDA(At, 0, 0); PG8_STAGE(PG8_SA(1, 1), a1 + hstepA, voffA);
;             PG8_WAIT_V(8); PG8_WAIT_L(0); PG8_BAR; PG8_MMA(0, 0, At, B0); PG8_MMA(0, 1, At, B1); PG8_BAR; PG8_SCHED;
;             PG8_LDA(At, 0, 1); PG8_STAGE(PG8_SB(0, 0), b2, voffB); PG8_STAGE(PG8_SB(0, 1), b2 + hstepB, voffB); PG8_STAGE(PG8_SA(0, 0), a2, voffA);
;             PG8_WAIT_V(8); PG8_WAIT_L(0); PG8_BAR; PG8_MMA(1, 0, At, B0); PG8_MMA(1, 1, At, B1); PG8_BAR; PG8_SCHED;
.LBB0_1565:
	ds_read_b128 v[130:133], v176
	ds_read_b128 v[134:137], v176 offset:1024
	ds_read_b128 v[138:141], v176 offset:2048
	ds_read_b128 v[142:145], v176 offset:3072
	ds_read_b128 v[162:165], v177
	ds_read_b128 v[166:169], v177 offset:1024
	ds_read_b128 v[170:173], v177 offset:2048
	ds_read_b128 v[180:183], v177 offset:3072
	s_add_u32 s30, s28, 0xfff80080
	s_addc_u32 s31, s29, -1
	s_cmp_eq_u32 s54, 28
	s_cselect_b32 s35, s7, s31
	s_cselect_b32 s34, s21, s30
	s_cselect_b32 s31, s19, s53
	s_cselect_b32 s30, s27, s52
	s_add_i32 m0, s40, 0xc000
	ds_read_b128 v[184:187], v178
	ds_read_b128 v[188:191], v178 offset:1024
	ds_read_b128 v[192:195], v178 offset:2048
	ds_read_b128 v[196:199], v178 offset:3072
	ds_read_b128 v[200:203], v178 offset:4096
	ds_read_b128 v[204:207], v178 offset:5120
	ds_read_b128 v[208:211], v178 offset:6144
	ds_read_b128 v[212:215], v178 offset:7168
	global_load_lds_dwordx4 v154, s[28:29]
	s_add_i32 m0, s40, 0xe000
	s_nop 0
	global_load_lds_dwordx4 v156, s[28:29]
	s_waitcnt vmcnt(8)
	s_waitcnt lgkmcnt(0)
	s_barrier
	s_waitcnt lgkmcnt(0)
	v_mfma_f32_16x16x32_bf16 v[126:129], v[130:133], v[184:187], v[126:129]
	v_mfma_f32_16x16x32_bf16 v[122:125], v[138:141], v[184:187], v[122:125]
	v_mfma_f32_16x16x32_bf16 v[110:113], v[130:133], v[192:195], v[110:113]
	v_mfma_f32_16x16x32_bf16 v[106:109], v[138:141], v[192:195], v[106:109]
	v_mfma_f32_16x16x32_bf16 v[94:97], v[130:133], v[200:203], v[94:97]
	v_mfma_f32_16x16x32_bf16 v[90:93], v[138:141], v[200:203], v[90:93]
	v_mfma_f32_16x16x32_bf16 v[78:81], v[130:133], v[208:211], v[78:81]
	v_mfma_f32_16x16x32_bf16 v[74:77], v[138:141], v[208:211], v[74:77]
	v_mfma_f32_16x16x32_bf16 v[126:129], v[134:137], v[188:191], v[126:129]
	v_mfma_f32_16x16x32_bf16 v[122:125], v[142:145], v[188:191], v[122:125]
	v_mfma_f32_16x16x32_bf16 v[110:113], v[134:137], v[196:199], v[110:113]
	v_mfma_f32_16x16x32_bf16 v[106:109], v[142:145], v[196:199], v[106:109]
	v_mfma_f32_16x16x32_bf16 v[94:97], v[134:137], v[204:207], v[94:97]
	v_mfma_f32_16x16x32_bf16 v[90:93], v[142:145], v[204:207], v[90:93]
	v_mfma_f32_16x16x32_bf16 v[78:81], v[134:137], v[212:215], v[78:81]
	v_mfma_f32_16x16x32_bf16 v[74:77], v[142:145], v[212:215], v[74:77]
	v_mfma_f32_16x16x32_bf16 v[118:121], v[162:165], v[184:187], v[118:121]
	v_mfma_f32_16x16x32_bf16 v[114:117], v[170:173], v[184:187], v[114:117]
	v_mfma_f32_16x16x32_bf16 v[102:105], v[162:165], v[192:195], v[102:105]
	v_mfma_f32_16x16x32_bf16 v[98:101], v[170:173], v[192:195], v[98:101]
	v_mfma_f32_16x16x32_bf16 v[86:89], v[162:165], v[200:203], v[86:89]
	v_mfma_f32_16x16x32_bf16 v[82:85], v[170:173], v[200:203], v[82:85]
	v_mfma_f32_16x16x32_bf16 v[70:73], v[162:165], v[208:211], v[70:73]
	v_mfma_f32_16x16x32_bf16 v[66:69], v[170:173], v[208:211], v[66:69]
	v_mfma_f32_16x16x32_bf16 v[118:121], v[166:169], v[188:191], v[118:121]
	v_mfma_f32_16x16x32_bf16 v[114:117], v[180:183], v[188:191], v[114:117]
	v_mfma_f32_16x16x32_bf16 v[102:105], v[166:169], v[196:199], v[102:105]
	v_mfma_f32_16x16x32_bf16 v[98:101], v[180:183], v[196:199], v[98:101]
	v_mfma_f32_16x16x32_bf16 v[86:89], v[166:169], v[204:207], v[86:89]
	v_mfma_f32_16x16x32_bf16 v[82:85], v[180:183], v[204:207], v[82:85]
	v_mfma_f32_16x16x32_bf16 v[70:73], v[166:169], v[212:215], v[70:73]
	v_mfma_f32_16x16x32_bf16 v[66:69], v[180:183], v[212:215], v[66:69]
	s_barrier
	s_add_i32 s55, s50, s39
	s_mov_b64 s[98:99], s[30:31]
	s_mov_b32 m0, s55
	ds_read_b128 v[184:187], v178 offset:16384
	ds_read_b128 v[188:191], v178 offset:17408
	ds_read_b128 v[192:195], v178 offset:18432
	ds_read_b128 v[196:199], v178 offset:19456
	ds_read_b128 v[200:203], v178 offset:20480
	ds_read_b128 v[204:207], v178 offset:21504
	ds_read_b128 v[208:211], v178 offset:22528
	ds_read_b128 v[212:215], v178 offset:23552
	global_load_lds_dwordx4 v148, s[30:31]
	s_add_i32 m0, s55, 0x2000
	s_add_u32 s56, s30, 0x80000
	s_mov_b64 s[98:99], s[30:31]
	s_addc_u32 s57, s31, 0
	s_add_i32 s55, s51, s39
	global_load_lds_dwordx4 v152, s[30:31]
	s_mov_b32 m0, s55
	s_mov_b64 s[100:101], s[34:35]
	global_load_lds_dwordx4 v148, s[56:57]
	s_add_i32 m0, s55, 0x2000
	s_nop 0
	global_load_lds_dwordx4 v152, s[56:57]
	s_mov_b64 s[100:101], s[34:35]
	s_mov_b32 m0, s40
	s_nop 0
	global_load_lds_dwordx4 v146, s[34:35]
	s_mov_b32 m0, s41
	s_nop 0
	global_load_lds_dwordx4 v150, s[34:35]
	s_waitcnt vmcnt(8)
	s_waitcnt lgkmcnt(0)
	s_barrier
	s_waitcnt lgkmcnt(0)
	v_mfma_f32_16x16x32_bf16 v[62:65], v[130:133], v[184:187], v[62:65]
	v_mfma_f32_16x16x32_bf16 v[58:61], v[138:141], v[184:187], v[58:61]
	v_mfma_f32_16x16x32_bf16 v[46:49], v[130:133], v[192:195], v[46:49]
	v_mfma_f32_16x16x32_bf16 v[42:45], v[138:141], v[192:195], v[42:45]
	v_mfma_f32_16x16x32_bf16 v[30:33], v[130:133], v[200:203], v[30:33]
	v_mfma_f32_16x16x32_bf16 v[26:29], v[138:141], v[200:203], v[26:29]
	v_mfma_f32_16x16x32_bf16 v[14:17], v[130:133], v[208:211], v[14:17]
	v_mfma_f32_16x16x32_bf16 v[10:13], v[138:141], v[208:211], v[10:13]
	v_mfma_f32_16x16x32_bf16 v[62:65], v[134:137], v[188:191], v[62:65]
	v_mfma_f32_16x16x32_bf16 v[58:61], v[142:145], v[188:191], v[58:61]
	v_mfma_f32_16x16x32_bf16 v[46:49], v[134:137], v[196:199], v[46:49]
	v_mfma_f32_16x16x32_bf16 v[42:45], v[142:145], v[196:199], v[42:45]
	v_mfma_f32_16x16x32_bf16 v[30:33], v[134:137], v[204:207], v[30:33]
	v_mfma_f32_16x16x32_bf16 v[26:29], v[142:145], v[204:207], v[26:29]
	v_mfma_f32_16x16x32_bf16 v[14:17], v[134:137], v[212:215], v[14:17]
	v_mfma_f32_16x16x32_bf16 v[10:13], v[142:145], v[212:215], v[10:13]
	v_mfma_f32_16x16x32_bf16 v[54:57], v[162:165], v[184:187], v[54:57]
	v_mfma_f32_16x16x32_bf16 v[50:53], v[170:173], v[184:187], v[50:53]
	v_mfma_f32_16x16x32_bf16 v[38:41], v[162:165], v[192:195], v[38:41]
	v_mfma_f32_16x16x32_bf16 v[34:37], v[170:173], v[192:195], v[34:37]
	v_mfma_f32_16x16x32_bf16 v[22:25], v[162:165], v[200:203], v[22:25]
	v_mfma_f32_16x16x32_bf16 v[18:21], v[170:173], v[200:203], v[18:21]
	v_mfma_f32_16x16x32_bf16 v[6:9], v[162:165], v[208:211], v[6:9]
	v_mfma_f32_16x16x32_bf16 v[2:5], v[170:173], v[208:211], v[2:5]
	v_mfma_f32_16x16x32_bf16 v[54:57], v[166:169], v[188:191], v[54:57]
	v_mfma_f32_16x16x32_bf16 v[50:53], v[180:183], v[188:191], v[50:53]
	v_mfma_f32_16x16x32_bf16 v[38:41], v[166:169], v[196:199], v[38:41]
	v_mfma_f32_16x16x32_bf16 v[34:37], v[180:183], v[196:199], v[34:37]
	v_mfma_f32_16x16x32_bf16 v[22:25], v[166:169], v[204:207], v[22:25]
	v_mfma_f32_16x16x32_bf16 v[18:21], v[180:183], v[204:207], v[18:21]
	v_mfma_f32_16x16x32_bf16 v[6:9], v[166:169], v[212:215], v[6:9]
	v_mfma_f32_16x16x32_bf16 v[2:5], v[180:183], v[212:215], v[2:5]
	s_barrier
; #define PG8_STAGE(bufoff, gbase, voff) do { _Pragma("unroll") for (int _i = 0; _i < 2; ++_i) \
;         __builtin_amdgcn_global_load_lds((const unsigned*)((const char*)(gbase) + (voff)[_i]), (PG8_LAS unsigned*)(lds + (bufoff) + ldsw + _i * 8192), 16, 0, 0); } while (0)
; #define PG8_LDA(dst, b, h) do { _Pragma("unroll") for (int m = 0; m < 4; ++m) _Pragma("unroll") for (int k = 0; k < 2; ++k) dst[m][k] = *(const PG8_LAS bf16x8*)(lds + PG8_SA(b, h) + aoff + m * 2048 + k * 1024); } while (0)
; #define PG8_WAIT_V(n) asm volatile("s_waitcnt vmcnt(" #n ")" ::: "memory")
; #define PG8_WAIT_L(n) asm volatile("s_waitcnt lgkmcnt(" #n ")" ::: "memory")
; #define PG8_BAR __builtin_amdgcn_s_barrier()
; template <class Epi, class Sched, bool ALIGN_EPI = false, bool SP2 = false, bool I8 = false>
; __device__ __forceinline__ void gemm_phase(PG8_LAS unsigned char* lds, const Gemm g, const Sched& S, const Epi& E) {
;     ...
;         for (int t = 0; t < nt; t += 2) {
;             const bool last = (t == nt - 2);
;             const char* a1 = cA + (size_t)(t + 1) * kstep;
;             const char* a2 = last ? nA : cA + (size_t)(t + 2) * kstep; const char* b2 = last ? nB : cB + (size_t)(t + 2) * kstep;
;             const char* a3 = a2 + kstep; const char* b3 = b2 + kstep;
;             if (last && has_next) S.a_ready(nxt);
;             if constexpr (SP2) {
;             PG8_LDB(B0, 0, 0); PG8_LDB(B1, 0, 1); PG8_SCHED; PG8_LDA(At, 0, 0); PG8_STAGE(PG8_SA(1, 1), a1 + hstepA, voffA);
;             PG8_WAIT_V(8); PG8_WAIT_L(0); PG8_BAR; PG8_MMA(0, 0, At, B0); PG8_MMA(0, 1, At, B1); PG8_BAR; PG8_SCHED;
;             PG8_LDA(At, 0, 1); PG8_STAGE(PG8_SB(0, 0), b2, voffB); PG8_STAGE(PG8_SB(0, 1), b2 + hstepB, voffB); PG8_STAGE(PG8_SA(0, 0), a2, voffA);
;             PG8_WAIT_V(8); PG8_WAIT_L(0); PG8_BAR; PG8_MMA(1, 0, At, B0); PG8_MMA(1, 1, At, B1); PG8_BAR; PG8_SCHED;
;             PG8_LDB(B0, 1, 0); PG8_LDB(B1, 1, 1); PG8_SCHED; PG8_LDA(At, 1, 0); PG8_STAGE(PG8_SA(0, 1), a2 + hstepA, voffA);
;             PG8_WAIT_V(8); PG8_WAIT_L(0); PG8_BAR; PG8_MMA(0, 0, At, B0); PG8_MMA(0, 1, At, B1); PG8_BAR; PG8_SCHED;
;             PG8_LDA(At, 1, 1); PG8_STAGE(PG8_SB(1, 0), b3, voffB); PG8_STAGE(PG8_SB(1, 1), b3 + hstepB, voffB); PG8_STAGE(PG8_SA(1, 0), a3, voffA);
;             PG8_WAIT_V(8); PG8_WAIT_L(0); PG8_BAR; PG8_MMA(1, 0, At, B0); PG8_MMA(1, 1, At, B1); PG8_BAR; PG8_SCHED;
	s_add_i32 s55, 0, 0x18000
	s_add_i32 s56, 0, 0x1c000
	v_add_u32_e32 v142, s55, v1
	v_add_u32_e32 v180, s56, v1
	ds_read_b128 v[130:133], v142
	ds_read_b128 v[134:137], v142 offset:1024
	ds_read_b128 v[138:141], v142 offset:2048
	ds_read_b128 v[142:145], v142 offset:3072
	ds_read_b128 v[162:165], v180
	ds_read_b128 v[166:169], v180 offset:1024
	ds_read_b128 v[170:173], v180 offset:2048
	ds_read_b128 v[180:183], v180 offset:3072
	s_add_u32 s34, s34, 0x80000
	s_addc_u32 s35, s35, 0
	s_mov_b32 m0, s42
	ds_read_b128 v[184:187], v178 offset:32768
	ds_read_b128 v[188:191], v178 offset:33792
	ds_read_b128 v[192:195], v178 offset:34816
	ds_read_b128 v[196:199], v178 offset:35840
	ds_read_b128 v[200:203], v178 offset:36864
	ds_read_b128 v[204:207], v178 offset:37888
	ds_read_b128 v[208:211], v178 offset:38912
	ds_read_b128 v[212:215], v178 offset:39936
	global_load_lds_dwordx4 v146, s[34:35]
	s_mov_b32 m0, s43
	s_nop 0
	global_load_lds_dwordx4 v150, s[34:35]
	s_waitcnt vmcnt(8)
	s_waitcnt lgkmcnt(0)
	s_barrier
	s_waitcnt lgkmcnt(0)
	v_mfma_f32_16x16x32_bf16 v[126:129], v[130:133], v[184:187], v[126:129]
	v_mfma_f32_16x16x32_bf16 v[122:125], v[138:141], v[184:187], v[122:125]
	v_mfma_f32_16x16x32_bf16 v[110:113], v[130:133], v[192:195], v[110:113]
	v_mfma_f32_16x16x32_bf16 v[106:109], v[138:141], v[192:195], v[106:109]
	v_mfma_f32_16x16x32_bf16 v[94:97], v[130:133], v[200:203], v[94:97]
	v_mfma_f32_16x16x32_bf16 v[90:93], v[138:141], v[200:203], v[90:93]
	v_mfma_f32_16x16x32_bf16 v[78:81], v[130:133], v[208:211], v[78:81]
	v_mfma_f32_16x16x32_bf16 v[74:77], v[138:141], v[208:211], v[74:77]
	v_mfma_f32_16x16x32_bf16 v[126:129], v[134:137], v[188:191], v[126:129]
	v_mfma_f32_16x16x32_bf16 v[122:125], v[142:145], v[188:191], v[122:125]
	v_mfma_f32_16x16x32_bf16 v[110:113], v[134:137], v[196:199], v[110:113]
	v_mfma_f32_16x16x32_bf16 v[106:109], v[142:145], v[196:199], v[106:109]
	v_mfma_f32_16x16x32_bf16 v[94:97], v[134:137], v[204:207], v[94:97]
	v_mfma_f32_16x16x32_bf16 v[90:93], v[142:145], v[204:207], v[90:93]
	v_mfma_f32_16x16x32_bf16 v[78:81], v[134:137], v[212:215], v[78:81]
	v_mfma_f32_16x16x32_bf16 v[74:77], v[142:145], v[212:215], v[74:77]
	v_mfma_f32_16x16x32_bf16 v[118:121], v[162:165], v[184:187], v[118:121]
	v_mfma_f32_16x16x32_bf16 v[114:117], v[170:173], v[184:187], v[114:117]
	v_mfma_f32_16x16x32_bf16 v[102:105], v[162:165], v[192:195], v[102:105]
	v_mfma_f32_16x16x32_bf16 v[98:101], v[170:173], v[192:195], v[98:101]
	v_mfma_f32_16x16x32_bf16 v[86:89], v[162:165], v[200:203], v[86:89]
	v_mfma_f32_16x16x32_bf16 v[82:85], v[170:173], v[200:203], v[82:85]
	v_mfma_f32_16x16x32_bf16 v[70:73], v[162:165], v[208:211], v[70:73]
	v_mfma_f32_16x16x32_bf16 v[66:69], v[170:173], v[208:211], v[66:69]
	v_mfma_f32_16x16x32_bf16 v[118:121], v[166:169], v[188:191], v[118:121]
	v_mfma_f32_16x16x32_bf16 v[114:117], v[180:183], v[188:191], v[114:117]
	v_mfma_f32_16x16x32_bf16 v[102:105], v[166:169], v[196:199], v[102:105]
	v_mfma_f32_16x16x32_bf16 v[98:101], v[180:183], v[196:199], v[98:101]
	v_mfma_f32_16x16x32_bf16 v[86:89], v[166:169], v[204:207], v[86:89]
	v_mfma_f32_16x16x32_bf16 v[82:85], v[180:183], v[204:207], v[82:85]
	v_mfma_f32_16x16x32_bf16 v[70:73], v[166:169], v[212:215], v[70:73]
	v_mfma_f32_16x16x32_bf16 v[66:69], v[180:183], v[212:215], v[66:69]
	s_barrier
	s_add_i32 s34, s55, s39
	s_add_i32 m0, s34, 0xffffff80
	ds_read_b128 v[184:187], v178 offset:49152
	ds_read_b128 v[188:191], v178 offset:50176
	ds_read_b128 v[192:195], v178 offset:51200
	ds_read_b128 v[196:199], v178 offset:52224
	ds_read_b128 v[200:203], v178 offset:53248
	ds_read_b128 v[204:207], v178 offset:54272
	ds_read_b128 v[208:211], v178 offset:55296
	ds_read_b128 v[212:215], v178 offset:56320
	global_load_lds_dwordx4 v148, s[98:99] offset:128
	s_add_i32 m0, s34, 0x1f80
	s_add_u32 s30, s30, 0x80080
	s_addc_u32 s31, s31, 0
	s_add_i32 s34, s56, s39
	global_load_lds_dwordx4 v152, s[98:99] offset:128
	s_mov_b32 m0, s34
	s_nop 0
	global_load_lds_dwordx4 v148, s[30:31]
	s_add_i32 m0, s34, 0x2000
	s_nop 0
	global_load_lds_dwordx4 v152, s[30:31]
	s_add_i32 m0, s46, 0xffffff80
	s_nop 0
	global_load_lds_dwordx4 v146, s[100:101] offset:128
	s_add_i32 m0, s47, 0xffffff80
	s_nop 0
	global_load_lds_dwordx4 v150, s[100:101] offset:128
	s_waitcnt vmcnt(8)
	s_waitcnt lgkmcnt(0)
	s_barrier
	s_waitcnt lgkmcnt(0)
	v_mfma_f32_16x16x32_bf16 v[62:65], v[130:133], v[184:187], v[62:65]
	v_mfma_f32_16x16x32_bf16 v[58:61], v[138:141], v[184:187], v[58:61]
	v_mfma_f32_16x16x32_bf16 v[46:49], v[130:133], v[192:195], v[46:49]
	v_mfma_f32_16x16x32_bf16 v[42:45], v[138:141], v[192:195], v[42:45]
	v_mfma_f32_16x16x32_bf16 v[30:33], v[130:133], v[200:203], v[30:33]
	v_mfma_f32_16x16x32_bf16 v[26:29], v[138:141], v[200:203], v[26:29]
	v_mfma_f32_16x16x32_bf16 v[14:17], v[130:133], v[208:211], v[14:17]
	v_mfma_f32_16x16x32_bf16 v[10:13], v[138:141], v[208:211], v[10:13]
	v_mfma_f32_16x16x32_bf16 v[62:65], v[134:137], v[188:191], v[62:65]
	v_mfma_f32_16x16x32_bf16 v[58:61], v[142:145], v[188:191], v[58:61]
	v_mfma_f32_16x16x32_bf16 v[46:49], v[134:137], v[196:199], v[46:49]
	v_mfma_f32_16x16x32_bf16 v[42:45], v[142:145], v[196:199], v[42:45]
	v_mfma_f32_16x16x32_bf16 v[30:33], v[134:137], v[204:207], v[30:33]
	v_mfma_f32_16x16x32_bf16 v[26:29], v[142:145], v[204:207], v[26:29]
	v_mfma_f32_16x16x32_bf16 v[14:17], v[134:137], v[212:215], v[14:17]
	v_mfma_f32_16x16x32_bf16 v[10:13], v[142:145], v[212:215], v[10:13]
	v_mfma_f32_16x16x32_bf16 v[54:57], v[162:165], v[184:187], v[54:57]
	v_mfma_f32_16x16x32_bf16 v[50:53], v[170:173], v[184:187], v[50:53]
	v_mfma_f32_16x16x32_bf16 v[38:41], v[162:165], v[192:195], v[38:41]
	v_mfma_f32_16x16x32_bf16 v[34:37], v[170:173], v[192:195], v[34:37]
	v_mfma_f32_16x16x32_bf16 v[22:25], v[162:165], v[200:203], v[22:25]
	v_mfma_f32_16x16x32_bf16 v[18:21], v[170:173], v[200:203], v[18:21]
	v_mfma_f32_16x16x32_bf16 v[6:9], v[162:165], v[208:211], v[6:9]
	v_mfma_f32_16x16x32_bf16 v[2:5], v[170:173], v[208:211], v[2:5]
	v_mfma_f32_16x16x32_bf16 v[54:57], v[166:169], v[188:191], v[54:57]
	v_mfma_f32_16x16x32_bf16 v[50:53], v[180:183], v[188:191], v[50:53]
	v_mfma_f32_16x16x32_bf16 v[38:41], v[166:169], v[196:199], v[38:41]
	v_mfma_f32_16x16x32_bf16 v[34:37], v[180:183], v[196:199], v[34:37]
	v_mfma_f32_16x16x32_bf16 v[22:25], v[166:169], v[204:207], v[22:25]
	v_mfma_f32_16x16x32_bf16 v[18:21], v[180:183], v[204:207], v[18:21]
	v_mfma_f32_16x16x32_bf16 v[6:9], v[166:169], v[212:215], v[6:9]
	v_mfma_f32_16x16x32_bf16 v[2:5], v[180:183], v[212:215], v[2:5]
	s_barrier
	s_add_i32 s54, s54, 2
	s_add_u32 s28, s28, 0x100
	s_addc_u32 s29, s29, 0
	s_add_u32 s52, s52, 0x100
	s_addc_u32 s53, s53, 0
	s_cmp_gt_u32 s54, 29
	s_cbranch_scc0 .LBB0_1565
	s_and_b64 vcc, exec, s[16:17]
	s_cbranch_vccz .LBB0_1568
	s_barrier

; #define PG8_STAGE(bufoff, gbase, voff) do { _Pragma("unroll") for (int _i = 0; _i < 2; ++_i) \
;         __builtin_amdgcn_global_load_lds((const unsigned*)((const char*)(gbase) + (voff)[_i]), (PG8_LAS unsigned*)(lds + (bufoff) + ldsw + _i * 8192), 16, 0, 0); } while (0)
; #define PG8_LDA(dst, b, h) do { _Pragma("unroll") for (int m = 0; m < 4; ++m) _Pragma("unroll") for (int k = 0; k < 2; ++k) dst[m][k] = *(const PG8_LAS bf16x8*)(lds + PG8_SA(b, h) + aoff + m * 2048 + k * 1024); } while (0)
; #define PG8_LDB(dst, b, h) do { _Pragma("unroll") for (int n = 0; n < 2; ++n) _Pragma("unroll") for (int k = 0; k < 2; ++k) dst[n][k] = *(const PG8_LAS bf16x8*)(lds + PG8_SB(b, h) + boff + n * 2048 + k * 1024); } while (0)
; #define PG8_MMA(ai, bj, At, Bt) do { __builtin_amdgcn_s_setprio(1); _Pragma("unroll") for (int m = 0; m < 4; ++m) _Pragma("unroll") for (int n = 0; n < 2; ++n) _Pragma("unroll") for (int k = 0; k < 2; ++k) \
;         acc[ai][bj][m][n] = mma_<I8>(Bt[n][k], At[m][k], acc[ai][bj][m][n]); __builtin_amdgcn_s_setprio(0); } while (0)
; #define PG8_WAIT_V(n) asm volatile("s_waitcnt vmcnt(" #n ")" ::: "memory")
; #define PG8_WAIT_L(n) asm volatile("s_waitcnt lgkmcnt(" #n ")" ::: "memory")
; #define PG8_BAR __builtin_amdgcn_s_barrier()
; template <class Epi, class Sched, bool ALIGN_EPI = false, bool SP2 = false, bool I8 = false>
; __device__ __forceinline__ void gemm_phase(PG8_LAS unsigned char* lds, const Gemm g, const Sched& S, const Epi& E) {
;     ...
;             const bool last = (t == nt - 2);
;             const char* a1 = cA + (size_t)(t + 1) * kstep;
;             const char* a2 = last ? nA : cA + (size_t)(t + 2) * kstep; const char* b2 = last ? nB : cB + (size_t)(t + 2) * kstep;
;             const char* a3 = a2 + kstep; const char* b3 = b2 + kstep;
;             if (last && has_next) S.a_ready(nxt);
;             if constexpr (SP2) {
;             PG8_LDB(B0, 0, 0); PG8_LDB(B1, 0, 1); PG8_SCHED; PG8_LDA(At, 0, 0); PG8_STAGE(PG8_SA(1, 1), a1 + hstepA, voffA);
;             PG8_WAIT_V(8); PG8_WAIT_L(0); PG8_BAR; PG8_MMA(0, 0, At, B0); PG8_MMA(0, 1, At, B1); PG8_BAR; PG8_SCHED;
;             PG8_LDA(At, 0, 1); PG8_STAGE(PG8_SB(0, 0), b2, voffB); PG8_STAGE(PG8_SB(0, 1), b2 + hstepB, voffB); PG8_STAGE(PG8_SA(0, 0), a2, voffA);
;             PG8_WAIT_V(8); PG8_WAIT_L(0); PG8_BAR; PG8_MMA(1, 0, At, B0); PG8_MMA(1, 1, At, B1); PG8_BAR; PG8_SCHED;
.LBB0_1721:
	ds_read_b128 v[34:37], v233
	ds_read_b128 v[38:41], v233 offset:1024
	ds_read_b128 v[42:45], v233 offset:2048
	ds_read_b128 v[62:65], v233 offset:3072
	ds_read_b128 v[146:149], v234
	ds_read_b128 v[150:153], v234 offset:1024
	ds_read_b128 v[154:157], v234 offset:2048
	ds_read_b128 v[158:161], v234 offset:3072
	s_add_u32 s34, s8, 0xfff80080
	s_addc_u32 s35, s9, -1
	s_cmp_eq_u32 s55, 28
	s_cselect_b32 s37, s3, s35
	s_cselect_b32 s36, s7, s34
	s_cselect_b32 s35, s25, s54
	s_cselect_b32 s34, s27, s33
	s_add_i32 m0, s43, 0xc000
	ds_read_b128 v[162:165], v235
	ds_read_b128 v[166:169], v235 offset:1024
	ds_read_b128 v[170:173], v235 offset:2048
	ds_read_b128 v[186:189], v235 offset:3072
	ds_read_b128 v[190:193], v235 offset:4096
	ds_read_b128 v[194:197], v235 offset:5120
	ds_read_b128 v[198:201], v235 offset:6144
	ds_read_b128 v[202:205], v235 offset:7168
	global_load_lds_dwordx4 v178, s[8:9]
	s_add_i32 m0, s43, 0xe000
	s_nop 0
	global_load_lds_dwordx4 v180, s[8:9]
	s_waitcnt vmcnt(8)
	s_waitcnt lgkmcnt(0)
	s_barrier
	s_waitcnt lgkmcnt(0)
	v_mfma_i32_16x16x64_i8 v[142:145], v[34:37], v[162:165], v[142:145]
	v_mfma_i32_16x16x64_i8 v[138:141], v[42:45], v[162:165], v[138:141]
	v_mfma_i32_16x16x64_i8 v[126:129], v[34:37], v[170:173], v[126:129]
	v_mfma_i32_16x16x64_i8 v[122:125], v[42:45], v[170:173], v[122:125]
	v_mfma_i32_16x16x64_i8 v[110:113], v[34:37], v[190:193], v[110:113]
	v_mfma_i32_16x16x64_i8 v[106:109], v[42:45], v[190:193], v[106:109]
	v_mfma_i32_16x16x64_i8 v[94:97], v[34:37], v[198:201], v[94:97]
	v_mfma_i32_16x16x64_i8 v[90:93], v[42:45], v[198:201], v[90:93]
	v_mfma_i32_16x16x64_i8 v[142:145], v[38:41], v[166:169], v[142:145]
	v_mfma_i32_16x16x64_i8 v[138:141], v[62:65], v[166:169], v[138:141]
	v_mfma_i32_16x16x64_i8 v[126:129], v[38:41], v[186:189], v[126:129]
	v_mfma_i32_16x16x64_i8 v[122:125], v[62:65], v[186:189], v[122:125]
	v_mfma_i32_16x16x64_i8 v[110:113], v[38:41], v[194:197], v[110:113]
	v_mfma_i32_16x16x64_i8 v[106:109], v[62:65], v[194:197], v[106:109]
	v_mfma_i32_16x16x64_i8 v[94:97], v[38:41], v[202:205], v[94:97]
	v_mfma_i32_16x16x64_i8 v[90:93], v[62:65], v[202:205], v[90:93]
	v_mfma_i32_16x16x64_i8 v[134:137], v[146:149], v[162:165], v[134:137]
	v_mfma_i32_16x16x64_i8 v[130:133], v[154:157], v[162:165], v[130:133]
	v_mfma_i32_16x16x64_i8 v[118:121], v[146:149], v[170:173], v[118:121]
	v_mfma_i32_16x16x64_i8 v[114:117], v[154:157], v[170:173], v[114:117]
	v_mfma_i32_16x16x64_i8 v[102:105], v[146:149], v[190:193], v[102:105]
	v_mfma_i32_16x16x64_i8 v[98:101], v[154:157], v[190:193], v[98:101]
	v_mfma_i32_16x16x64_i8 v[86:89], v[146:149], v[198:201], v[86:89]
	v_mfma_i32_16x16x64_i8 v[82:85], v[154:157], v[198:201], v[82:85]
	v_mfma_i32_16x16x64_i8 v[134:137], v[150:153], v[166:169], v[134:137]
	v_mfma_i32_16x16x64_i8 v[130:133], v[158:161], v[166:169], v[130:133]
	v_mfma_i32_16x16x64_i8 v[118:121], v[150:153], v[186:189], v[118:121]
	v_mfma_i32_16x16x64_i8 v[114:117], v[158:161], v[186:189], v[114:117]
	v_mfma_i32_16x16x64_i8 v[102:105], v[150:153], v[194:197], v[102:105]
	v_mfma_i32_16x16x64_i8 v[98:101], v[158:161], v[194:197], v[98:101]
	v_mfma_i32_16x16x64_i8 v[86:89], v[150:153], v[202:205], v[86:89]
	v_mfma_i32_16x16x64_i8 v[82:85], v[158:161], v[202:205], v[82:85]
	s_barrier
	s_add_i32 s56, s52, s40
	s_mov_b64 s[98:99], s[34:35]
	s_mov_b32 m0, s56
	ds_read_b128 v[162:165], v235 offset:16384
	ds_read_b128 v[166:169], v235 offset:17408
	ds_read_b128 v[170:173], v235 offset:18432
	ds_read_b128 v[186:189], v235 offset:19456
	ds_read_b128 v[190:193], v235 offset:20480
	ds_read_b128 v[194:197], v235 offset:21504
	ds_read_b128 v[198:201], v235 offset:22528
	ds_read_b128 v[202:205], v235 offset:23552
	global_load_lds_dwordx4 v174, s[34:35]
	s_add_i32 m0, s56, 0x2000
	s_add_u32 s56, s34, 0x80000
	s_mov_b64 s[98:99], s[34:35]
	s_addc_u32 s57, s35, 0
	s_add_i32 s58, s53, s40
	global_load_lds_dwordx4 v176, s[34:35]
	s_mov_b32 m0, s58
	s_mov_b64 s[100:101], s[36:37]
	global_load_lds_dwordx4 v174, s[56:57]
	s_add_i32 m0, s58, 0x2000
	s_nop 0
	global_load_lds_dwordx4 v176, s[56:57]
	s_mov_b64 s[100:101], s[36:37]
	s_mov_b32 m0, s43
	s_nop 0
	global_load_lds_dwordx4 v174, s[36:37]
	s_mov_b32 m0, s44
	s_nop 0
	global_load_lds_dwordx4 v176, s[36:37]
	s_waitcnt vmcnt(8)
	s_waitcnt lgkmcnt(0)
	s_barrier
	s_waitcnt lgkmcnt(0)
	v_mfma_i32_16x16x64_i8 v[78:81], v[34:37], v[162:165], v[78:81]
	v_mfma_i32_16x16x64_i8 v[74:77], v[42:45], v[162:165], v[74:77]
	v_mfma_i32_16x16x64_i8 v[58:61], v[34:37], v[170:173], v[58:61]
	v_mfma_i32_16x16x64_i8 v[54:57], v[42:45], v[170:173], v[54:57]
	v_mfma_i32_16x16x64_i8 v[30:33], v[34:37], v[190:193], v[30:33]
	v_mfma_i32_16x16x64_i8 v[26:29], v[42:45], v[190:193], v[26:29]
	v_mfma_i32_16x16x64_i8 v[14:17], v[34:37], v[198:201], v[14:17]
	v_mfma_i32_16x16x64_i8 v[10:13], v[42:45], v[198:201], v[10:13]
	v_mfma_i32_16x16x64_i8 v[78:81], v[38:41], v[166:169], v[78:81]
	v_mfma_i32_16x16x64_i8 v[74:77], v[62:65], v[166:169], v[74:77]
	v_mfma_i32_16x16x64_i8 v[58:61], v[38:41], v[186:189], v[58:61]
	v_mfma_i32_16x16x64_i8 v[54:57], v[62:65], v[186:189], v[54:57]
	v_mfma_i32_16x16x64_i8 v[30:33], v[38:41], v[194:197], v[30:33]
	v_mfma_i32_16x16x64_i8 v[26:29], v[62:65], v[194:197], v[26:29]
	v_mfma_i32_16x16x64_i8 v[14:17], v[38:41], v[202:205], v[14:17]
	v_mfma_i32_16x16x64_i8 v[10:13], v[62:65], v[202:205], v[10:13]
	v_mfma_i32_16x16x64_i8 v[46:49], v[154:157], v[170:173], v[46:49]
	v_mfma_i32_16x16x64_i8 v[22:25], v[146:149], v[190:193], v[22:25]
	v_mfma_i32_16x16x64_i8 v[18:21], v[154:157], v[190:193], v[18:21]
	v_mfma_i32_16x16x64_i8 v[6:9], v[146:149], v[198:201], v[6:9]
	v_mfma_i32_16x16x64_i8 v[2:5], v[154:157], v[198:201], v[2:5]
	v_mfma_i32_16x16x64_i8 v[34:37], v[146:149], v[162:165], v[70:73]
	v_mfma_i32_16x16x64_i8 v[38:41], v[154:157], v[162:165], v[66:69]
	v_mfma_i32_16x16x64_i8 v[42:45], v[146:149], v[170:173], v[50:53]
	v_mfma_i32_16x16x64_i8 v[46:49], v[158:161], v[186:189], v[46:49]
	v_mfma_i32_16x16x64_i8 v[22:25], v[150:153], v[194:197], v[22:25]
	v_mfma_i32_16x16x64_i8 v[18:21], v[158:161], v[194:197], v[18:21]
	v_mfma_i32_16x16x64_i8 v[6:9], v[150:153], v[202:205], v[6:9]
	v_mfma_i32_16x16x64_i8 v[2:5], v[158:161], v[202:205], v[2:5]
	v_mfma_i32_16x16x64_i8 v[34:37], v[150:153], v[166:169], v[34:37]
	v_mfma_i32_16x16x64_i8 v[38:41], v[158:161], v[166:169], v[38:41]
	v_mfma_i32_16x16x64_i8 v[42:45], v[150:153], v[186:189], v[42:45]
	s_barrier
; #define PG8_STAGE(bufoff, gbase, voff) do { _Pragma("unroll") for (int _i = 0; _i < 2; ++_i) \
;         __builtin_amdgcn_global_load_lds((const unsigned*)((const char*)(gbase) + (voff)[_i]), (PG8_LAS unsigned*)(lds + (bufoff) + ldsw + _i * 8192), 16, 0, 0); } while (0)
; #define PG8_LDA(dst, b, h) do { _Pragma("unroll") for (int m = 0; m < 4; ++m) _Pragma("unroll") for (int k = 0; k < 2; ++k) dst[m][k] = *(const PG8_LAS bf16x8*)(lds + PG8_SA(b, h) + aoff + m * 2048 + k * 1024); } while (0)
; #define PG8_WAIT_V(n) asm volatile("s_waitcnt vmcnt(" #n ")" ::: "memory")
; #define PG8_WAIT_L(n) asm volatile("s_waitcnt lgkmcnt(" #n ")" ::: "memory")
; #define PG8_BAR __builtin_amdgcn_s_barrier()
; template <class Epi, class Sched, bool ALIGN_EPI = false, bool SP2 = false, bool I8 = false>
; __device__ __forceinline__ void gemm_phase(PG8_LAS unsigned char* lds, const Gemm g, const Sched& S, const Epi& E) {
;     ...
;         for (int t = 0; t < nt; t += 2) {
;             const bool last = (t == nt - 2);
;             const char* a1 = cA + (size_t)(t + 1) * kstep;
;             const char* a2 = last ? nA : cA + (size_t)(t + 2) * kstep; const char* b2 = last ? nB : cB + (size_t)(t + 2) * kstep;
;             const char* a3 = a2 + kstep; const char* b3 = b2 + kstep;
;             if (last && has_next) S.a_ready(nxt);
;             if constexpr (SP2) {
;             PG8_LDB(B0, 0, 0); PG8_LDB(B1, 0, 1); PG8_SCHED; PG8_LDA(At, 0, 0); PG8_STAGE(PG8_SA(1, 1), a1 + hstepA, voffA);
;             PG8_WAIT_V(8); PG8_WAIT_L(0); PG8_BAR; PG8_MMA(0, 0, At, B0); PG8_MMA(0, 1, At, B1); PG8_BAR; PG8_SCHED;
;             PG8_LDA(At, 0, 1); PG8_STAGE(PG8_SB(0, 0), b2, voffB); PG8_STAGE(PG8_SB(0, 1), b2 + hstepB, voffB); PG8_STAGE(PG8_SA(0, 0), a2, voffA);
;             PG8_WAIT_V(8); PG8_WAIT_L(0); PG8_BAR; PG8_MMA(1, 0, At, B0); PG8_MMA(1, 1, At, B1); PG8_BAR; PG8_SCHED;
;             PG8_LDB(B0, 1, 0); PG8_LDB(B1, 1, 1); PG8_SCHED; PG8_LDA(At, 1, 0); PG8_STAGE(PG8_SA(0, 1), a2 + hstepA, voffA);
;             PG8_WAIT_V(8); PG8_WAIT_L(0); PG8_BAR; PG8_MMA(0, 0, At, B0); PG8_MMA(0, 1, At, B1); PG8_BAR; PG8_SCHED;
;             PG8_LDA(At, 1, 1); PG8_STAGE(PG8_SB(1, 0), b3, voffB); PG8_STAGE(PG8_SB(1, 1), b3 + hstepB, voffB); PG8_STAGE(PG8_SA(1, 0), a3, voffA);
;             PG8_WAIT_V(8); PG8_WAIT_L(0); PG8_BAR; PG8_MMA(1, 0, At, B0); PG8_MMA(1, 1, At, B1); PG8_BAR; PG8_SCHED;
	s_add_i32 s56, 0, 0x18000
	s_add_i32 s57, 0, 0x1c000
	v_add_u32_e32 v70, s56, v1
	v_add_u32_e32 v158, s57, v1
	ds_read_b128 v[50:53], v70
	ds_read_b128 v[62:65], v70 offset:1024
	ds_read_b128 v[66:69], v70 offset:2048
	ds_read_b128 v[70:73], v70 offset:3072
	ds_read_b128 v[146:149], v158
	ds_read_b128 v[150:153], v158 offset:1024
	ds_read_b128 v[154:157], v158 offset:2048
	ds_read_b128 v[158:161], v158 offset:3072
	s_add_u32 s36, s36, 0x80000
	s_addc_u32 s37, s37, 0
	s_mov_b32 m0, s45
	ds_read_b128 v[162:165], v235 offset:32768
	ds_read_b128 v[166:169], v235 offset:33792
	ds_read_b128 v[170:173], v235 offset:34816
	ds_read_b128 v[186:189], v235 offset:35840
	ds_read_b128 v[190:193], v235 offset:36864
	ds_read_b128 v[194:197], v235 offset:37888
	ds_read_b128 v[198:201], v235 offset:38912
	ds_read_b128 v[202:205], v235 offset:39936
	global_load_lds_dwordx4 v174, s[36:37]
	s_mov_b32 m0, s46
	s_nop 0
	global_load_lds_dwordx4 v176, s[36:37]
	s_waitcnt vmcnt(8)
	s_waitcnt lgkmcnt(0)
	s_barrier
	s_waitcnt lgkmcnt(0)
	v_mfma_i32_16x16x64_i8 v[142:145], v[50:53], v[162:165], v[142:145]
	v_mfma_i32_16x16x64_i8 v[138:141], v[66:69], v[162:165], v[138:141]
	v_mfma_i32_16x16x64_i8 v[126:129], v[50:53], v[170:173], v[126:129]
	v_mfma_i32_16x16x64_i8 v[122:125], v[66:69], v[170:173], v[122:125]
	v_mfma_i32_16x16x64_i8 v[110:113], v[50:53], v[190:193], v[110:113]
	v_mfma_i32_16x16x64_i8 v[106:109], v[66:69], v[190:193], v[106:109]
	v_mfma_i32_16x16x64_i8 v[94:97], v[50:53], v[198:201], v[94:97]
	v_mfma_i32_16x16x64_i8 v[90:93], v[66:69], v[198:201], v[90:93]
	v_mfma_i32_16x16x64_i8 v[142:145], v[62:65], v[166:169], v[142:145]
	v_mfma_i32_16x16x64_i8 v[138:141], v[70:73], v[166:169], v[138:141]
	v_mfma_i32_16x16x64_i8 v[126:129], v[62:65], v[186:189], v[126:129]
	v_mfma_i32_16x16x64_i8 v[122:125], v[70:73], v[186:189], v[122:125]
	v_mfma_i32_16x16x64_i8 v[110:113], v[62:65], v[194:197], v[110:113]
	v_mfma_i32_16x16x64_i8 v[106:109], v[70:73], v[194:197], v[106:109]
	v_mfma_i32_16x16x64_i8 v[94:97], v[62:65], v[202:205], v[94:97]
	v_mfma_i32_16x16x64_i8 v[90:93], v[70:73], v[202:205], v[90:93]
	v_mfma_i32_16x16x64_i8 v[134:137], v[146:149], v[162:165], v[134:137]
	v_mfma_i32_16x16x64_i8 v[130:133], v[154:157], v[162:165], v[130:133]
	v_mfma_i32_16x16x64_i8 v[118:121], v[146:149], v[170:173], v[118:121]
	v_mfma_i32_16x16x64_i8 v[114:117], v[154:157], v[170:173], v[114:117]
	v_mfma_i32_16x16x64_i8 v[102:105], v[146:149], v[190:193], v[102:105]
	v_mfma_i32_16x16x64_i8 v[98:101], v[154:157], v[190:193], v[98:101]
	v_mfma_i32_16x16x64_i8 v[86:89], v[146:149], v[198:201], v[86:89]
	v_mfma_i32_16x16x64_i8 v[82:85], v[154:157], v[198:201], v[82:85]
	v_mfma_i32_16x16x64_i8 v[134:137], v[150:153], v[166:169], v[134:137]
	v_mfma_i32_16x16x64_i8 v[130:133], v[158:161], v[166:169], v[130:133]
	v_mfma_i32_16x16x64_i8 v[118:121], v[150:153], v[186:189], v[118:121]
	v_mfma_i32_16x16x64_i8 v[114:117], v[158:161], v[186:189], v[114:117]
	v_mfma_i32_16x16x64_i8 v[102:105], v[150:153], v[194:197], v[102:105]
	v_mfma_i32_16x16x64_i8 v[98:101], v[158:161], v[194:197], v[98:101]
	v_mfma_i32_16x16x64_i8 v[86:89], v[150:153], v[202:205], v[86:89]
	v_mfma_i32_16x16x64_i8 v[82:85], v[158:161], v[202:205], v[82:85]
	s_barrier
	s_add_i32 s36, s56, s40
	s_add_i32 m0, s36, 0xffffff80
	ds_read_b128 v[162:165], v235 offset:49152
	ds_read_b128 v[166:169], v235 offset:50176
	ds_read_b128 v[170:173], v235 offset:51200
	ds_read_b128 v[186:189], v235 offset:52224
	ds_read_b128 v[190:193], v235 offset:53248
	ds_read_b128 v[194:197], v235 offset:54272
	ds_read_b128 v[198:201], v235 offset:55296
	ds_read_b128 v[202:205], v235 offset:56320
	global_load_lds_dwordx4 v174, s[98:99] offset:128
	s_add_i32 m0, s36, 0x1f80
	s_add_u32 s34, s34, 0x80080
	s_addc_u32 s35, s35, 0
	s_add_i32 s36, s57, s40
	global_load_lds_dwordx4 v176, s[98:99] offset:128
	s_mov_b32 m0, s36
	s_nop 0
	global_load_lds_dwordx4 v174, s[34:35]
	s_add_i32 m0, s36, 0x2000
	s_nop 0
	global_load_lds_dwordx4 v176, s[34:35]
	s_add_i32 m0, s48, 0xffffff80
	s_nop 0
	global_load_lds_dwordx4 v174, s[100:101] offset:128
	s_add_i32 m0, s49, 0xffffff80
	s_nop 0
	global_load_lds_dwordx4 v176, s[100:101] offset:128
	s_waitcnt vmcnt(8)
	s_waitcnt lgkmcnt(0)
	s_barrier
	s_waitcnt lgkmcnt(0)
	v_mfma_i32_16x16x64_i8 v[78:81], v[50:53], v[162:165], v[78:81]
	v_mfma_i32_16x16x64_i8 v[74:77], v[66:69], v[162:165], v[74:77]
	v_mfma_i32_16x16x64_i8 v[58:61], v[50:53], v[170:173], v[58:61]
	v_mfma_i32_16x16x64_i8 v[54:57], v[66:69], v[170:173], v[54:57]
	v_mfma_i32_16x16x64_i8 v[30:33], v[50:53], v[190:193], v[30:33]
	v_mfma_i32_16x16x64_i8 v[26:29], v[66:69], v[190:193], v[26:29]
	v_mfma_i32_16x16x64_i8 v[14:17], v[50:53], v[198:201], v[14:17]
	v_mfma_i32_16x16x64_i8 v[10:13], v[66:69], v[198:201], v[10:13]
	v_mfma_i32_16x16x64_i8 v[78:81], v[62:65], v[166:169], v[78:81]
	v_mfma_i32_16x16x64_i8 v[74:77], v[70:73], v[166:169], v[74:77]
	v_mfma_i32_16x16x64_i8 v[58:61], v[62:65], v[186:189], v[58:61]
	v_mfma_i32_16x16x64_i8 v[54:57], v[70:73], v[186:189], v[54:57]
	v_mfma_i32_16x16x64_i8 v[30:33], v[62:65], v[194:197], v[30:33]
	v_mfma_i32_16x16x64_i8 v[26:29], v[70:73], v[194:197], v[26:29]
	v_mfma_i32_16x16x64_i8 v[14:17], v[62:65], v[202:205], v[14:17]
	v_mfma_i32_16x16x64_i8 v[10:13], v[70:73], v[202:205], v[10:13]
	v_mfma_i32_16x16x64_i8 v[34:37], v[146:149], v[162:165], v[34:37]
	v_mfma_i32_16x16x64_i8 v[70:73], v[150:153], v[166:169], v[34:37]
	v_mfma_i32_16x16x64_i8 v[34:37], v[154:157], v[162:165], v[38:41]
	v_mfma_i32_16x16x64_i8 v[66:69], v[158:161], v[166:169], v[34:37]
	v_mfma_i32_16x16x64_i8 v[34:37], v[146:149], v[170:173], v[42:45]
	v_mfma_i32_16x16x64_i8 v[50:53], v[150:153], v[186:189], v[34:37]
	v_mfma_i32_16x16x64_i8 v[34:37], v[154:157], v[170:173], v[46:49]
	v_mfma_i32_16x16x64_i8 v[22:25], v[146:149], v[190:193], v[22:25]
	v_mfma_i32_16x16x64_i8 v[18:21], v[154:157], v[190:193], v[18:21]
	v_mfma_i32_16x16x64_i8 v[6:9], v[146:149], v[198:201], v[6:9]
	v_mfma_i32_16x16x64_i8 v[2:5], v[154:157], v[198:201], v[2:5]
	v_mfma_i32_16x16x64_i8 v[46:49], v[158:161], v[186:189], v[34:37]
	v_mfma_i32_16x16x64_i8 v[22:25], v[150:153], v[194:197], v[22:25]
	v_mfma_i32_16x16x64_i8 v[18:21], v[158:161], v[194:197], v[18:21]
	v_mfma_i32_16x16x64_i8 v[6:9], v[150:153], v[202:205], v[6:9]
	v_mfma_i32_16x16x64_i8 v[2:5], v[158:161], v[202:205], v[2:5]
	s_barrier
	s_add_i32 s55, s55, 2
	s_add_u32 s8, s8, 0x100
	s_addc_u32 s9, s9, 0
	s_add_u32 s33, s33, 0x100
	s_addc_u32 s54, s54, 0
	s_cmp_gt_u32 s55, 29
	s_cbranch_scc0 .LBB0_1721
	s_and_b64 vcc, exec, s[20:21]
	s_cbranch_vccz .LBB0_1724
	s_barrier

; #define PG8_STAGE(bufoff, gbase, voff) do { _Pragma("unroll") for (int _i = 0; _i < 2; ++_i) \
;         __builtin_amdgcn_global_load_lds((const unsigned*)((const char*)(gbase) + (voff)[_i]), (PG8_LAS unsigned*)(lds + (bufoff) + ldsw + _i * 8192), 16, 0, 0); } while (0)
; #define PG8_LDA(dst, b, h) do { _Pragma("unroll") for (int m = 0; m < 4; ++m) _Pragma("unroll") for (int k = 0; k < 2; ++k) dst[m][k] = *(const PG8_LAS bf16x8*)(lds + PG8_SA(b, h) + aoff + m * 2048 + k * 1024); } while (0)
; #define PG8_LDB(dst, b, h) do { _Pragma("unroll") for (int n = 0; n < 2; ++n) _Pragma("unroll") for (int k = 0; k < 2; ++k) dst[n][k] = *(const PG8_LAS bf16x8*)(lds + PG8_SB(b, h) + boff + n * 2048 + k * 1024); } while (0)
; #define PG8_MMA(ai, bj, At, Bt) do { __builtin_amdgcn_s_setprio(1); _Pragma("unroll") for (int m = 0; m < 4; ++m) _Pragma("unroll") for (int n = 0; n < 2; ++n) _Pragma("unroll") for (int k = 0; k < 2; ++k) \
;         acc[ai][bj][m][n] = mma_<I8>(Bt[n][k], At[m][k], acc[ai][bj][m][n]); __builtin_amdgcn_s_setprio(0); } while (0)
; #define PG8_WAIT_V(n) asm volatile("s_waitcnt vmcnt(" #n ")" ::: "memory")
; #define PG8_WAIT_L(n) asm volatile("s_waitcnt lgkmcnt(" #n ")" ::: "memory")
; #define PG8_BAR __builtin_amdgcn_s_barrier()
; template <class Epi, class Sched, bool ALIGN_EPI = false, bool SP2 = false, bool I8 = false>
; __device__ __forceinline__ void gemm_phase(PG8_LAS unsigned char* lds, const Gemm g, const Sched& S, const Epi& E) {
;     ...
;             const bool last = (t == nt - 2);
;             const char* a1 = cA + (size_t)(t + 1) * kstep;
;             const char* a2 = last ? nA : cA + (size_t)(t + 2) * kstep; const char* b2 = last ? nB : cB + (size_t)(t + 2) * kstep;
;             const char* a3 = a2 + kstep; const char* b3 = b2 + kstep;
;             if (last && has_next) S.a_ready(nxt);
;             if constexpr (SP2) {
;             PG8_LDB(B0, 0, 0); PG8_LDB(B1, 0, 1); PG8_SCHED; PG8_LDA(At, 0, 0); PG8_STAGE(PG8_SA(1, 1), a1 + hstepA, voffA);
;             PG8_WAIT_V(8); PG8_WAIT_L(0); PG8_BAR; PG8_MMA(0, 0, At, B0); PG8_MMA(0, 1, At, B1); PG8_BAR; PG8_SCHED;
;             PG8_LDA(At, 0, 1); PG8_STAGE(PG8_SB(0, 0), b2, voffB); PG8_STAGE(PG8_SB(0, 1), b2 + hstepB, voffB); PG8_STAGE(PG8_SA(0, 0), a2, voffA);
;             PG8_WAIT_V(8); PG8_WAIT_L(0); PG8_BAR; PG8_MMA(1, 0, At, B0); PG8_MMA(1, 1, At, B1); PG8_BAR; PG8_SCHED;
.LBB0_2014:
	ds_read_b128 v[118:121], v163
	ds_read_b128 v[126:129], v163 offset:1024
	ds_read_b128 v[130:133], v163 offset:2048
	ds_read_b128 v[134:137], v163 offset:3072
	ds_read_b128 v[168:171], v167
	ds_read_b128 v[176:179], v167 offset:1024
	ds_read_b128 v[180:183], v167 offset:2048
	ds_read_b128 v[184:187], v167 offset:3072
	s_add_u32 s38, s36, 0xfff80080
	s_addc_u32 s39, s37, -1
	s_cmp_eq_u32 s65, 28
	s_cselect_b32 s41, s27, s39
	s_cselect_b32 s40, s61, s38
	s_cselect_b32 s39, s25, s64
	s_cselect_b32 s38, s62, s63
	s_add_i32 m0, s35, 0xc000
	ds_read_b128 v[188:191], v173
	ds_read_b128 v[192:195], v173 offset:1024
	ds_read_b128 v[196:199], v173 offset:2048
	ds_read_b128 v[200:203], v173 offset:3072
	ds_read_b128 v[204:207], v173 offset:4096
	ds_read_b128 v[208:211], v173 offset:5120
	ds_read_b128 v[212:215], v173 offset:6144
	ds_read_b128 v[216:219], v173 offset:7168
	global_load_lds_dwordx4 v154, s[36:37]
	s_add_i32 m0, s35, 0xe000
	s_nop 0
	global_load_lds_dwordx4 v156, s[36:37]
	s_waitcnt vmcnt(8)
	s_waitcnt lgkmcnt(0)
	s_barrier
	s_waitcnt lgkmcnt(0)
	v_mfma_i32_16x16x64_i8 v[142:145], v[118:121], v[188:191], v[142:145]
	v_mfma_i32_16x16x64_i8 v[138:141], v[130:133], v[188:191], v[138:141]
	v_mfma_i32_16x16x64_i8 v[110:113], v[118:121], v[196:199], v[110:113]
	v_mfma_i32_16x16x64_i8 v[106:109], v[130:133], v[196:199], v[106:109]
	v_mfma_i32_16x16x64_i8 v[94:97], v[118:121], v[204:207], v[94:97]
	v_mfma_i32_16x16x64_i8 v[90:93], v[130:133], v[204:207], v[90:93]
	v_mfma_i32_16x16x64_i8 v[78:81], v[118:121], v[212:215], v[78:81]
	v_mfma_i32_16x16x64_i8 v[74:77], v[130:133], v[212:215], v[74:77]
	v_mfma_i32_16x16x64_i8 v[142:145], v[126:129], v[192:195], v[142:145]
	v_mfma_i32_16x16x64_i8 v[138:141], v[134:137], v[192:195], v[138:141]
	v_mfma_i32_16x16x64_i8 v[110:113], v[126:129], v[200:203], v[110:113]
	v_mfma_i32_16x16x64_i8 v[106:109], v[134:137], v[200:203], v[106:109]
	v_mfma_i32_16x16x64_i8 v[94:97], v[126:129], v[208:211], v[94:97]
	v_mfma_i32_16x16x64_i8 v[90:93], v[134:137], v[208:211], v[90:93]
	v_mfma_i32_16x16x64_i8 v[78:81], v[126:129], v[216:219], v[78:81]
	v_mfma_i32_16x16x64_i8 v[74:77], v[134:137], v[216:219], v[74:77]
	v_mfma_i32_16x16x64_i8 v[122:125], v[168:171], v[188:191], v[122:125]
	v_mfma_i32_16x16x64_i8 v[114:117], v[180:183], v[188:191], v[114:117]
	v_mfma_i32_16x16x64_i8 v[102:105], v[168:171], v[196:199], v[102:105]
	v_mfma_i32_16x16x64_i8 v[98:101], v[180:183], v[196:199], v[98:101]
	v_mfma_i32_16x16x64_i8 v[86:89], v[168:171], v[204:207], v[86:89]
	v_mfma_i32_16x16x64_i8 v[82:85], v[180:183], v[204:207], v[82:85]
	v_mfma_i32_16x16x64_i8 v[70:73], v[168:171], v[212:215], v[70:73]
	v_mfma_i32_16x16x64_i8 v[66:69], v[180:183], v[212:215], v[66:69]
	v_mfma_i32_16x16x64_i8 v[122:125], v[176:179], v[192:195], v[122:125]
	v_mfma_i32_16x16x64_i8 v[114:117], v[184:187], v[192:195], v[114:117]
	v_mfma_i32_16x16x64_i8 v[102:105], v[176:179], v[200:203], v[102:105]
	v_mfma_i32_16x16x64_i8 v[98:101], v[184:187], v[200:203], v[98:101]
	v_mfma_i32_16x16x64_i8 v[86:89], v[176:179], v[208:211], v[86:89]
	v_mfma_i32_16x16x64_i8 v[82:85], v[184:187], v[208:211], v[82:85]
	v_mfma_i32_16x16x64_i8 v[70:73], v[176:179], v[216:219], v[70:73]
	v_mfma_i32_16x16x64_i8 v[66:69], v[184:187], v[216:219], v[66:69]
	s_barrier
	s_add_i32 s66, s54, s46
	s_mov_b64 s[98:99], s[38:39]
	s_mov_b32 m0, s66
	ds_read_b128 v[188:191], v173 offset:16384
	ds_read_b128 v[192:195], v173 offset:17408
	ds_read_b128 v[196:199], v173 offset:18432
	ds_read_b128 v[200:203], v173 offset:19456
	ds_read_b128 v[204:207], v173 offset:20480
	ds_read_b128 v[208:211], v173 offset:21504
	ds_read_b128 v[212:215], v173 offset:22528
	ds_read_b128 v[216:219], v173 offset:23552
	global_load_lds_dwordx4 v148, s[38:39]
	s_add_i32 m0, s66, 0x2000
	s_add_u32 s66, s38, 0x80000
	s_mov_b64 s[98:99], s[38:39]
	s_addc_u32 s67, s39, 0
	s_add_i32 s68, s55, s46
	global_load_lds_dwordx4 v152, s[38:39]
	s_mov_b32 m0, s68
	s_mov_b64 s[100:101], s[40:41]
	global_load_lds_dwordx4 v148, s[66:67]
	s_add_i32 m0, s68, 0x2000
	s_nop 0
	global_load_lds_dwordx4 v152, s[66:67]
	s_mov_b64 s[100:101], s[40:41]
	s_mov_b32 m0, s35
	s_nop 0
	global_load_lds_dwordx4 v146, s[40:41]
	s_mov_b32 m0, s47
	s_nop 0
	global_load_lds_dwordx4 v150, s[40:41]
	s_waitcnt vmcnt(8)
	s_waitcnt lgkmcnt(0)
	s_barrier
	s_waitcnt lgkmcnt(0)
	v_mfma_i32_16x16x64_i8 v[62:65], v[118:121], v[188:191], v[62:65]
	v_mfma_i32_16x16x64_i8 v[58:61], v[130:133], v[188:191], v[58:61]
	v_mfma_i32_16x16x64_i8 v[46:49], v[118:121], v[196:199], v[46:49]
	v_mfma_i32_16x16x64_i8 v[42:45], v[130:133], v[196:199], v[42:45]
	v_mfma_i32_16x16x64_i8 v[30:33], v[118:121], v[204:207], v[30:33]
	v_mfma_i32_16x16x64_i8 v[26:29], v[130:133], v[204:207], v[26:29]
	v_mfma_i32_16x16x64_i8 v[14:17], v[118:121], v[212:215], v[14:17]
	v_mfma_i32_16x16x64_i8 v[10:13], v[130:133], v[212:215], v[10:13]
	v_mfma_i32_16x16x64_i8 v[62:65], v[126:129], v[192:195], v[62:65]
	v_mfma_i32_16x16x64_i8 v[58:61], v[134:137], v[192:195], v[58:61]
	v_mfma_i32_16x16x64_i8 v[46:49], v[126:129], v[200:203], v[46:49]
	v_mfma_i32_16x16x64_i8 v[42:45], v[134:137], v[200:203], v[42:45]
	v_mfma_i32_16x16x64_i8 v[30:33], v[126:129], v[208:211], v[30:33]
	v_mfma_i32_16x16x64_i8 v[26:29], v[134:137], v[208:211], v[26:29]
	v_mfma_i32_16x16x64_i8 v[14:17], v[126:129], v[216:219], v[14:17]
	v_mfma_i32_16x16x64_i8 v[10:13], v[134:137], v[216:219], v[10:13]
	v_mfma_i32_16x16x64_i8 v[54:57], v[168:171], v[188:191], v[54:57]
	v_mfma_i32_16x16x64_i8 v[50:53], v[180:183], v[188:191], v[50:53]
	v_mfma_i32_16x16x64_i8 v[38:41], v[168:171], v[196:199], v[38:41]
	v_mfma_i32_16x16x64_i8 v[34:37], v[180:183], v[196:199], v[34:37]
	v_mfma_i32_16x16x64_i8 v[22:25], v[168:171], v[204:207], v[22:25]
	v_mfma_i32_16x16x64_i8 v[18:21], v[180:183], v[204:207], v[18:21]
	v_mfma_i32_16x16x64_i8 v[6:9], v[168:171], v[212:215], v[6:9]
	v_mfma_i32_16x16x64_i8 v[2:5], v[180:183], v[212:215], v[2:5]
	v_mfma_i32_16x16x64_i8 v[54:57], v[176:179], v[192:195], v[54:57]
	v_mfma_i32_16x16x64_i8 v[50:53], v[184:187], v[192:195], v[50:53]
	v_mfma_i32_16x16x64_i8 v[38:41], v[176:179], v[200:203], v[38:41]
	v_mfma_i32_16x16x64_i8 v[34:37], v[184:187], v[200:203], v[34:37]
	v_mfma_i32_16x16x64_i8 v[22:25], v[176:179], v[208:211], v[22:25]
	v_mfma_i32_16x16x64_i8 v[18:21], v[184:187], v[208:211], v[18:21]
	v_mfma_i32_16x16x64_i8 v[6:9], v[176:179], v[216:219], v[6:9]
	v_mfma_i32_16x16x64_i8 v[2:5], v[184:187], v[216:219], v[2:5]
	s_barrier
; #define PG8_STAGE(bufoff, gbase, voff) do { _Pragma("unroll") for (int _i = 0; _i < 2; ++_i) \
;         __builtin_amdgcn_global_load_lds((const unsigned*)((const char*)(gbase) + (voff)[_i]), (PG8_LAS unsigned*)(lds + (bufoff) + ldsw + _i * 8192), 16, 0, 0); } while (0)
; #define PG8_LDA(dst, b, h) do { _Pragma("unroll") for (int m = 0; m < 4; ++m) _Pragma("unroll") for (int k = 0; k < 2; ++k) dst[m][k] = *(const PG8_LAS bf16x8*)(lds + PG8_SA(b, h) + aoff + m * 2048 + k * 1024); } while (0)
; #define PG8_WAIT_V(n) asm volatile("s_waitcnt vmcnt(" #n ")" ::: "memory")
; #define PG8_WAIT_L(n) asm volatile("s_waitcnt lgkmcnt(" #n ")" ::: "memory")
; #define PG8_BAR __builtin_amdgcn_s_barrier()
; template <class Epi, class Sched, bool ALIGN_EPI = false, bool SP2 = false, bool I8 = false>
; __device__ __forceinline__ void gemm_phase(PG8_LAS unsigned char* lds, const Gemm g, const Sched& S, const Epi& E) {
;     ...
;         for (int t = 0; t < nt; t += 2) {
;             const bool last = (t == nt - 2);
;             const char* a1 = cA + (size_t)(t + 1) * kstep;
;             const char* a2 = last ? nA : cA + (size_t)(t + 2) * kstep; const char* b2 = last ? nB : cB + (size_t)(t + 2) * kstep;
;             const char* a3 = a2 + kstep; const char* b3 = b2 + kstep;
;             if (last && has_next) S.a_ready(nxt);
;             if constexpr (SP2) {
;             PG8_LDB(B0, 0, 0); PG8_LDB(B1, 0, 1); PG8_SCHED; PG8_LDA(At, 0, 0); PG8_STAGE(PG8_SA(1, 1), a1 + hstepA, voffA);
;             PG8_WAIT_V(8); PG8_WAIT_L(0); PG8_BAR; PG8_MMA(0, 0, At, B0); PG8_MMA(0, 1, At, B1); PG8_BAR; PG8_SCHED;
;             PG8_LDA(At, 0, 1); PG8_STAGE(PG8_SB(0, 0), b2, voffB); PG8_STAGE(PG8_SB(0, 1), b2 + hstepB, voffB); PG8_STAGE(PG8_SA(0, 0), a2, voffA);
;             PG8_WAIT_V(8); PG8_WAIT_L(0); PG8_BAR; PG8_MMA(1, 0, At, B0); PG8_MMA(1, 1, At, B1); PG8_BAR; PG8_SCHED;
;             PG8_LDB(B0, 1, 0); PG8_LDB(B1, 1, 1); PG8_SCHED; PG8_LDA(At, 1, 0); PG8_STAGE(PG8_SA(0, 1), a2 + hstepA, voffA);
;             PG8_WAIT_V(8); PG8_WAIT_L(0); PG8_BAR; PG8_MMA(0, 0, At, B0); PG8_MMA(0, 1, At, B1); PG8_BAR; PG8_SCHED;
;             PG8_LDA(At, 1, 1); PG8_STAGE(PG8_SB(1, 0), b3, voffB); PG8_STAGE(PG8_SB(1, 1), b3 + hstepB, voffB); PG8_STAGE(PG8_SA(1, 0), a3, voffA);
;             PG8_WAIT_V(8); PG8_WAIT_L(0); PG8_BAR; PG8_MMA(1, 0, At, B0); PG8_MMA(1, 1, At, B1); PG8_BAR; PG8_SCHED;
	s_add_i32 s66, 0, 0x18000
	s_add_i32 s67, 0, 0x1c000
	v_add_u32_e32 v134, s66, v1
	v_add_u32_e32 v162, s67, v1
	ds_read_b128 v[118:121], v134
	ds_read_b128 v[126:129], v134 offset:1024
	ds_read_b128 v[130:133], v134 offset:2048
	ds_read_b128 v[134:137], v134 offset:3072
	ds_read_b128 v[168:171], v162
	ds_read_b128 v[176:179], v162 offset:1024
	ds_read_b128 v[180:183], v162 offset:2048
	ds_read_b128 v[184:187], v162 offset:3072
	s_add_u32 s40, s40, 0x80000
	s_addc_u32 s41, s41, 0
	s_mov_b32 m0, s48
	ds_read_b128 v[188:191], v173 offset:32768
	ds_read_b128 v[192:195], v173 offset:33792
	ds_read_b128 v[196:199], v173 offset:34816
	ds_read_b128 v[200:203], v173 offset:35840
	ds_read_b128 v[204:207], v173 offset:36864
	ds_read_b128 v[208:211], v173 offset:37888
	ds_read_b128 v[212:215], v173 offset:38912
	ds_read_b128 v[216:219], v173 offset:39936
	global_load_lds_dwordx4 v146, s[40:41]
	s_mov_b32 m0, s49
	s_nop 0
	global_load_lds_dwordx4 v150, s[40:41]
	s_waitcnt vmcnt(8)
	s_waitcnt lgkmcnt(0)
	s_barrier
	s_waitcnt lgkmcnt(0)
	v_mfma_i32_16x16x64_i8 v[142:145], v[118:121], v[188:191], v[142:145]
	v_mfma_i32_16x16x64_i8 v[138:141], v[130:133], v[188:191], v[138:141]
	v_mfma_i32_16x16x64_i8 v[110:113], v[118:121], v[196:199], v[110:113]
	v_mfma_i32_16x16x64_i8 v[106:109], v[130:133], v[196:199], v[106:109]
	v_mfma_i32_16x16x64_i8 v[94:97], v[118:121], v[204:207], v[94:97]
	v_mfma_i32_16x16x64_i8 v[90:93], v[130:133], v[204:207], v[90:93]
	v_mfma_i32_16x16x64_i8 v[78:81], v[118:121], v[212:215], v[78:81]
	v_mfma_i32_16x16x64_i8 v[74:77], v[130:133], v[212:215], v[74:77]
	v_mfma_i32_16x16x64_i8 v[142:145], v[126:129], v[192:195], v[142:145]
	v_mfma_i32_16x16x64_i8 v[138:141], v[134:137], v[192:195], v[138:141]
	v_mfma_i32_16x16x64_i8 v[110:113], v[126:129], v[200:203], v[110:113]
	v_mfma_i32_16x16x64_i8 v[106:109], v[134:137], v[200:203], v[106:109]
	v_mfma_i32_16x16x64_i8 v[94:97], v[126:129], v[208:211], v[94:97]
	v_mfma_i32_16x16x64_i8 v[90:93], v[134:137], v[208:211], v[90:93]
	v_mfma_i32_16x16x64_i8 v[78:81], v[126:129], v[216:219], v[78:81]
	v_mfma_i32_16x16x64_i8 v[74:77], v[134:137], v[216:219], v[74:77]
	v_mfma_i32_16x16x64_i8 v[122:125], v[168:171], v[188:191], v[122:125]
	v_mfma_i32_16x16x64_i8 v[114:117], v[180:183], v[188:191], v[114:117]
	v_mfma_i32_16x16x64_i8 v[102:105], v[168:171], v[196:199], v[102:105]
	v_mfma_i32_16x16x64_i8 v[98:101], v[180:183], v[196:199], v[98:101]
	v_mfma_i32_16x16x64_i8 v[86:89], v[168:171], v[204:207], v[86:89]
	v_mfma_i32_16x16x64_i8 v[82:85], v[180:183], v[204:207], v[82:85]
	v_mfma_i32_16x16x64_i8 v[70:73], v[168:171], v[212:215], v[70:73]
	v_mfma_i32_16x16x64_i8 v[66:69], v[180:183], v[212:215], v[66:69]
	v_mfma_i32_16x16x64_i8 v[122:125], v[176:179], v[192:195], v[122:125]
	v_mfma_i32_16x16x64_i8 v[114:117], v[184:187], v[192:195], v[114:117]
	v_mfma_i32_16x16x64_i8 v[102:105], v[176:179], v[200:203], v[102:105]
	v_mfma_i32_16x16x64_i8 v[98:101], v[184:187], v[200:203], v[98:101]
	v_mfma_i32_16x16x64_i8 v[86:89], v[176:179], v[208:211], v[86:89]
	v_mfma_i32_16x16x64_i8 v[82:85], v[184:187], v[208:211], v[82:85]
	v_mfma_i32_16x16x64_i8 v[70:73], v[176:179], v[216:219], v[70:73]
	v_mfma_i32_16x16x64_i8 v[66:69], v[184:187], v[216:219], v[66:69]
	s_barrier
	s_add_i32 s40, s66, s46
	s_add_i32 m0, s40, 0xffffff80
	ds_read_b128 v[188:191], v173 offset:49152
	ds_read_b128 v[192:195], v173 offset:50176
	ds_read_b128 v[196:199], v173 offset:51200
	ds_read_b128 v[200:203], v173 offset:52224
	ds_read_b128 v[204:207], v173 offset:53248
	ds_read_b128 v[208:211], v173 offset:54272
	ds_read_b128 v[212:215], v173 offset:55296
	ds_read_b128 v[216:219], v173 offset:56320
	global_load_lds_dwordx4 v148, s[98:99] offset:128
	s_add_i32 m0, s40, 0x1f80
	s_add_u32 s38, s38, 0x80080
	s_addc_u32 s39, s39, 0
	s_add_i32 s40, s67, s46
	global_load_lds_dwordx4 v152, s[98:99] offset:128
	s_mov_b32 m0, s40
	s_nop 0
	global_load_lds_dwordx4 v148, s[38:39]
	s_add_i32 m0, s40, 0x2000
	s_nop 0
	global_load_lds_dwordx4 v152, s[38:39]
	s_add_i32 m0, s51, 0xffffff80
	s_nop 0
	global_load_lds_dwordx4 v146, s[100:101] offset:128
	s_add_i32 m0, s52, 0xffffff80
	s_nop 0
	global_load_lds_dwordx4 v150, s[100:101] offset:128
	s_waitcnt vmcnt(8)
	s_waitcnt lgkmcnt(0)
	s_barrier
	s_waitcnt lgkmcnt(0)
	v_mfma_i32_16x16x64_i8 v[62:65], v[118:121], v[188:191], v[62:65]
	v_mfma_i32_16x16x64_i8 v[58:61], v[130:133], v[188:191], v[58:61]
	v_mfma_i32_16x16x64_i8 v[46:49], v[118:121], v[196:199], v[46:49]
	v_mfma_i32_16x16x64_i8 v[42:45], v[130:133], v[196:199], v[42:45]
	v_mfma_i32_16x16x64_i8 v[30:33], v[118:121], v[204:207], v[30:33]
	v_mfma_i32_16x16x64_i8 v[26:29], v[130:133], v[204:207], v[26:29]
	v_mfma_i32_16x16x64_i8 v[14:17], v[118:121], v[212:215], v[14:17]
	v_mfma_i32_16x16x64_i8 v[10:13], v[130:133], v[212:215], v[10:13]
	v_mfma_i32_16x16x64_i8 v[62:65], v[126:129], v[192:195], v[62:65]
	v_mfma_i32_16x16x64_i8 v[58:61], v[134:137], v[192:195], v[58:61]
	v_mfma_i32_16x16x64_i8 v[46:49], v[126:129], v[200:203], v[46:49]
	v_mfma_i32_16x16x64_i8 v[42:45], v[134:137], v[200:203], v[42:45]
	v_mfma_i32_16x16x64_i8 v[30:33], v[126:129], v[208:211], v[30:33]
	v_mfma_i32_16x16x64_i8 v[26:29], v[134:137], v[208:211], v[26:29]
	v_mfma_i32_16x16x64_i8 v[14:17], v[126:129], v[216:219], v[14:17]
	v_mfma_i32_16x16x64_i8 v[10:13], v[134:137], v[216:219], v[10:13]
	v_mfma_i32_16x16x64_i8 v[54:57], v[168:171], v[188:191], v[54:57]
	v_mfma_i32_16x16x64_i8 v[50:53], v[180:183], v[188:191], v[50:53]
	v_mfma_i32_16x16x64_i8 v[38:41], v[168:171], v[196:199], v[38:41]
	v_mfma_i32_16x16x64_i8 v[34:37], v[180:183], v[196:199], v[34:37]
	v_mfma_i32_16x16x64_i8 v[22:25], v[168:171], v[204:207], v[22:25]
	v_mfma_i32_16x16x64_i8 v[18:21], v[180:183], v[204:207], v[18:21]
	v_mfma_i32_16x16x64_i8 v[6:9], v[168:171], v[212:215], v[6:9]
	v_mfma_i32_16x16x64_i8 v[2:5], v[180:183], v[212:215], v[2:5]
	v_mfma_i32_16x16x64_i8 v[54:57], v[176:179], v[192:195], v[54:57]
	v_mfma_i32_16x16x64_i8 v[50:53], v[184:187], v[192:195], v[50:53]
	v_mfma_i32_16x16x64_i8 v[38:41], v[176:179], v[200:203], v[38:41]
	v_mfma_i32_16x16x64_i8 v[34:37], v[184:187], v[200:203], v[34:37]
	v_mfma_i32_16x16x64_i8 v[22:25], v[176:179], v[208:211], v[22:25]
	v_mfma_i32_16x16x64_i8 v[18:21], v[184:187], v[208:211], v[18:21]
	v_mfma_i32_16x16x64_i8 v[6:9], v[176:179], v[216:219], v[6:9]
	v_mfma_i32_16x16x64_i8 v[2:5], v[184:187], v[216:219], v[2:5]
	s_barrier
	s_add_i32 s65, s65, 2
	s_add_u32 s36, s36, 0x100
	s_addc_u32 s37, s37, 0
	s_add_u32 s63, s63, 0x100
	s_addc_u32 s64, s64, 0
	s_cmp_gt_u32 s65, 29
	s_cbranch_scc0 .LBB0_2014
	s_and_b64 vcc, exec, s[14:15]
	s_cbranch_vccz .LBB0_2017
	s_barrier

; #define PG8_STAGE(bufoff, gbase, voff) do { _Pragma("unroll") for (int _i = 0; _i < 2; ++_i) \
;         __builtin_amdgcn_global_load_lds((const unsigned*)((const char*)(gbase) + (voff)[_i]), (PG8_LAS unsigned*)(lds + (bufoff) + ldsw + _i * 8192), 16, 0, 0); } while (0)
; #define PG8_LDA(dst, b, h) do { _Pragma("unroll") for (int m = 0; m < 4; ++m) _Pragma("unroll") for (int k = 0; k < 2; ++k) dst[m][k] = *(const PG8_LAS bf16x8*)(lds + PG8_SA(b, h) + aoff + m * 2048 + k * 1024); } while (0)
; #define PG8_LDB(dst, b, h) do { _Pragma("unroll") for (int n = 0; n < 2; ++n) _Pragma("unroll") for (int k = 0; k < 2; ++k) dst[n][k] = *(const PG8_LAS bf16x8*)(lds + PG8_SB(b, h) + boff + n * 2048 + k * 1024); } while (0)
; #define PG8_MMA(ai, bj, At, Bt) do { __builtin_amdgcn_s_setprio(1); _Pragma("unroll") for (int m = 0; m < 4; ++m) _Pragma("unroll") for (int n = 0; n < 2; ++n) _Pragma("unroll") for (int k = 0; k < 2; ++k) \
;         acc[ai][bj][m][n] = mma_<I8>(Bt[n][k], At[m][k], acc[ai][bj][m][n]); __builtin_amdgcn_s_setprio(0); } while (0)
; #define PG8_WAIT_V(n) asm volatile("s_waitcnt vmcnt(" #n ")" ::: "memory")
; #define PG8_WAIT_L(n) asm volatile("s_waitcnt lgkmcnt(" #n ")" ::: "memory")
; #define PG8_BAR __builtin_amdgcn_s_barrier()
; template <class Epi, class Sched, bool ALIGN_EPI = false, bool SP2 = false, bool I8 = false>
; __device__ __forceinline__ void gemm_phase(PG8_LAS unsigned char* lds, const Gemm g, const Sched& S, const Epi& E) {
;     ...
;             const bool last = (t == nt - 2);
;             const char* a1 = cA + (size_t)(t + 1) * kstep;
;             const char* a2 = last ? nA : cA + (size_t)(t + 2) * kstep; const char* b2 = last ? nB : cB + (size_t)(t + 2) * kstep;
;             const char* a3 = a2 + kstep; const char* b3 = b2 + kstep;
;             if (last && has_next) S.a_ready(nxt);
;             if constexpr (SP2) {
;             PG8_LDB(B0, 0, 0); PG8_LDB(B1, 0, 1); PG8_SCHED; PG8_LDA(At, 0, 0); PG8_STAGE(PG8_SA(1, 1), a1 + hstepA, voffA);
;             PG8_WAIT_V(8); PG8_WAIT_L(0); PG8_BAR; PG8_MMA(0, 0, At, B0); PG8_MMA(0, 1, At, B1); PG8_BAR; PG8_SCHED;
;             PG8_LDA(At, 0, 1); PG8_STAGE(PG8_SB(0, 0), b2, voffB); PG8_STAGE(PG8_SB(0, 1), b2 + hstepB, voffB); PG8_STAGE(PG8_SA(0, 0), a2, voffA);
;             PG8_WAIT_V(8); PG8_WAIT_L(0); PG8_BAR; PG8_MMA(1, 0, At, B0); PG8_MMA(1, 1, At, B1); PG8_BAR; PG8_SCHED;
.LBB0_2092:
	ds_read_b128 v[130:133], v192
	ds_read_b128 v[134:137], v192 offset:1024
	ds_read_b128 v[138:141], v192 offset:2048
	ds_read_b128 v[142:145], v192 offset:3072
	ds_read_b128 v[146:149], v193
	ds_read_b128 v[150:153], v193 offset:1024
	ds_read_b128 v[154:157], v193 offset:2048
	ds_read_b128 v[158:161], v193 offset:3072
	s_add_u32 s28, s8, 0xffc00080
	s_addc_u32 s29, s9, -1
	s_cmpk_eq_i32 s51, 0xfc
	s_cselect_b32 s31, s3, s29
	s_cselect_b32 s30, s7, s28
	s_cselect_b32 s29, s21, s50
	s_cselect_b32 s28, s23, s49
	s_add_i32 m0, s38, 0xc000
	ds_read_b128 v[162:165], v194
	ds_read_b128 v[166:169], v194 offset:1024
	ds_read_b128 v[182:185], v194 offset:2048
	ds_read_b128 v[186:189], v194 offset:3072
	ds_read_b128 v[196:199], v194 offset:4096
	ds_read_b128 v[200:203], v194 offset:5120
	ds_read_b128 v[204:207], v194 offset:6144
	ds_read_b128 v[208:211], v194 offset:7168
	global_load_lds_dwordx4 v174, s[8:9]
	s_add_i32 m0, s38, 0xe000
	s_nop 0
	global_load_lds_dwordx4 v176, s[8:9]
	s_waitcnt vmcnt(8)
	s_waitcnt lgkmcnt(0)
	s_barrier
	s_waitcnt lgkmcnt(0)
	v_mfma_f32_16x16x32_bf16 v[126:129], v[130:133], v[162:165], v[126:129]
	v_mfma_f32_16x16x32_bf16 v[122:125], v[138:141], v[162:165], v[122:125]
	v_mfma_f32_16x16x32_bf16 v[110:113], v[130:133], v[182:185], v[110:113]
	v_mfma_f32_16x16x32_bf16 v[106:109], v[138:141], v[182:185], v[106:109]
	v_mfma_f32_16x16x32_bf16 v[94:97], v[130:133], v[196:199], v[94:97]
	v_mfma_f32_16x16x32_bf16 v[90:93], v[138:141], v[196:199], v[90:93]
	v_mfma_f32_16x16x32_bf16 v[78:81], v[130:133], v[204:207], v[78:81]
	v_mfma_f32_16x16x32_bf16 v[74:77], v[138:141], v[204:207], v[74:77]
	v_mfma_f32_16x16x32_bf16 v[126:129], v[134:137], v[166:169], v[126:129]
	v_mfma_f32_16x16x32_bf16 v[122:125], v[142:145], v[166:169], v[122:125]
	v_mfma_f32_16x16x32_bf16 v[110:113], v[134:137], v[186:189], v[110:113]
	v_mfma_f32_16x16x32_bf16 v[106:109], v[142:145], v[186:189], v[106:109]
	v_mfma_f32_16x16x32_bf16 v[94:97], v[134:137], v[200:203], v[94:97]
	v_mfma_f32_16x16x32_bf16 v[90:93], v[142:145], v[200:203], v[90:93]
	v_mfma_f32_16x16x32_bf16 v[78:81], v[134:137], v[208:211], v[78:81]
	v_mfma_f32_16x16x32_bf16 v[74:77], v[142:145], v[208:211], v[74:77]
	v_mfma_f32_16x16x32_bf16 v[118:121], v[146:149], v[162:165], v[118:121]
	v_mfma_f32_16x16x32_bf16 v[114:117], v[154:157], v[162:165], v[114:117]
	v_mfma_f32_16x16x32_bf16 v[102:105], v[146:149], v[182:185], v[102:105]
	v_mfma_f32_16x16x32_bf16 v[98:101], v[154:157], v[182:185], v[98:101]
	v_mfma_f32_16x16x32_bf16 v[86:89], v[146:149], v[196:199], v[86:89]
	v_mfma_f32_16x16x32_bf16 v[82:85], v[154:157], v[196:199], v[82:85]
	v_mfma_f32_16x16x32_bf16 v[70:73], v[146:149], v[204:207], v[70:73]
	v_mfma_f32_16x16x32_bf16 v[66:69], v[154:157], v[204:207], v[66:69]
	v_mfma_f32_16x16x32_bf16 v[118:121], v[150:153], v[166:169], v[118:121]
	v_mfma_f32_16x16x32_bf16 v[114:117], v[158:161], v[166:169], v[114:117]
	v_mfma_f32_16x16x32_bf16 v[102:105], v[150:153], v[186:189], v[102:105]
	v_mfma_f32_16x16x32_bf16 v[98:101], v[158:161], v[186:189], v[98:101]
	v_mfma_f32_16x16x32_bf16 v[86:89], v[150:153], v[200:203], v[86:89]
	v_mfma_f32_16x16x32_bf16 v[82:85], v[158:161], v[200:203], v[82:85]
	v_mfma_f32_16x16x32_bf16 v[70:73], v[150:153], v[208:211], v[70:73]
	v_mfma_f32_16x16x32_bf16 v[66:69], v[158:161], v[208:211], v[66:69]
	s_barrier
	s_add_i32 s52, s47, s33
	s_mov_b64 s[98:99], s[28:29]
	s_mov_b32 m0, s52
	ds_read_b128 v[162:165], v194 offset:16384
	ds_read_b128 v[166:169], v194 offset:17408
	ds_read_b128 v[182:185], v194 offset:18432
	ds_read_b128 v[186:189], v194 offset:19456
	ds_read_b128 v[196:199], v194 offset:20480
	ds_read_b128 v[200:203], v194 offset:21504
	ds_read_b128 v[204:207], v194 offset:22528
	ds_read_b128 v[208:211], v194 offset:23552
	global_load_lds_dwordx4 v170, s[28:29]
	s_add_i32 m0, s52, 0x2000
	s_add_u32 s52, s28, 0x400000
	s_mov_b64 s[98:99], s[28:29]
	s_addc_u32 s53, s29, 0
	s_add_i32 s54, s48, s33
	global_load_lds_dwordx4 v172, s[28:29]
	s_mov_b32 m0, s54
	s_mov_b64 s[100:101], s[30:31]
	global_load_lds_dwordx4 v170, s[52:53]
	s_add_i32 m0, s54, 0x2000
	s_nop 0
	global_load_lds_dwordx4 v172, s[52:53]
	s_mov_b64 s[100:101], s[30:31]
	s_mov_b32 m0, s38
	s_nop 0
	global_load_lds_dwordx4 v170, s[30:31]
	s_mov_b32 m0, s39
	s_nop 0
	global_load_lds_dwordx4 v172, s[30:31]
	s_waitcnt vmcnt(8)
	s_waitcnt lgkmcnt(0)
	s_barrier
	s_waitcnt lgkmcnt(0)
	v_mfma_f32_16x16x32_bf16 v[62:65], v[130:133], v[162:165], v[62:65]
	v_mfma_f32_16x16x32_bf16 v[58:61], v[138:141], v[162:165], v[58:61]
	v_mfma_f32_16x16x32_bf16 v[46:49], v[130:133], v[182:185], v[46:49]
	v_mfma_f32_16x16x32_bf16 v[42:45], v[138:141], v[182:185], v[42:45]
	v_mfma_f32_16x16x32_bf16 v[30:33], v[130:133], v[196:199], v[30:33]
	v_mfma_f32_16x16x32_bf16 v[26:29], v[138:141], v[196:199], v[26:29]
	v_mfma_f32_16x16x32_bf16 v[22:25], v[130:133], v[204:207], v[22:25]
	v_mfma_f32_16x16x32_bf16 v[10:13], v[138:141], v[204:207], v[10:13]
	v_mfma_f32_16x16x32_bf16 v[62:65], v[134:137], v[166:169], v[62:65]
	v_mfma_f32_16x16x32_bf16 v[58:61], v[142:145], v[166:169], v[58:61]
	v_mfma_f32_16x16x32_bf16 v[46:49], v[134:137], v[186:189], v[46:49]
	v_mfma_f32_16x16x32_bf16 v[42:45], v[142:145], v[186:189], v[42:45]
	v_mfma_f32_16x16x32_bf16 v[30:33], v[134:137], v[200:203], v[30:33]
	v_mfma_f32_16x16x32_bf16 v[26:29], v[142:145], v[200:203], v[26:29]
	v_mfma_f32_16x16x32_bf16 v[22:25], v[134:137], v[208:211], v[22:25]
	v_mfma_f32_16x16x32_bf16 v[10:13], v[142:145], v[208:211], v[10:13]
	v_mfma_f32_16x16x32_bf16 v[54:57], v[146:149], v[162:165], v[54:57]
	v_mfma_f32_16x16x32_bf16 v[50:53], v[154:157], v[162:165], v[50:53]
	v_mfma_f32_16x16x32_bf16 v[38:41], v[146:149], v[182:185], v[38:41]
	v_mfma_f32_16x16x32_bf16 v[34:37], v[154:157], v[182:185], v[34:37]
	v_mfma_f32_16x16x32_bf16 v[18:21], v[146:149], v[196:199], v[18:21]
	v_mfma_f32_16x16x32_bf16 v[14:17], v[154:157], v[196:199], v[14:17]
	v_mfma_f32_16x16x32_bf16 v[6:9], v[146:149], v[204:207], v[6:9]
	v_mfma_f32_16x16x32_bf16 v[2:5], v[154:157], v[204:207], v[2:5]
	v_mfma_f32_16x16x32_bf16 v[54:57], v[150:153], v[166:169], v[54:57]
	v_mfma_f32_16x16x32_bf16 v[50:53], v[158:161], v[166:169], v[50:53]
	v_mfma_f32_16x16x32_bf16 v[38:41], v[150:153], v[186:189], v[38:41]
	v_mfma_f32_16x16x32_bf16 v[34:37], v[158:161], v[186:189], v[34:37]
	v_mfma_f32_16x16x32_bf16 v[18:21], v[150:153], v[200:203], v[18:21]
	v_mfma_f32_16x16x32_bf16 v[14:17], v[158:161], v[200:203], v[14:17]
	v_mfma_f32_16x16x32_bf16 v[6:9], v[150:153], v[208:211], v[6:9]
	v_mfma_f32_16x16x32_bf16 v[2:5], v[158:161], v[208:211], v[2:5]
	s_barrier
; #define PG8_STAGE(bufoff, gbase, voff) do { _Pragma("unroll") for (int _i = 0; _i < 2; ++_i) \
;         __builtin_amdgcn_global_load_lds((const unsigned*)((const char*)(gbase) + (voff)[_i]), (PG8_LAS unsigned*)(lds + (bufoff) + ldsw + _i * 8192), 16, 0, 0); } while (0)
; #define PG8_LDA(dst, b, h) do { _Pragma("unroll") for (int m = 0; m < 4; ++m) _Pragma("unroll") for (int k = 0; k < 2; ++k) dst[m][k] = *(const PG8_LAS bf16x8*)(lds + PG8_SA(b, h) + aoff + m * 2048 + k * 1024); } while (0)
; #define PG8_WAIT_V(n) asm volatile("s_waitcnt vmcnt(" #n ")" ::: "memory")
; #define PG8_WAIT_L(n) asm volatile("s_waitcnt lgkmcnt(" #n ")" ::: "memory")
; #define PG8_BAR __builtin_amdgcn_s_barrier()
; template <class Epi, class Sched, bool ALIGN_EPI = false, bool SP2 = false, bool I8 = false>
; __device__ __forceinline__ void gemm_phase(PG8_LAS unsigned char* lds, const Gemm g, const Sched& S, const Epi& E) {
;     ...
;         for (int t = 0; t < nt; t += 2) {
;             const bool last = (t == nt - 2);
;             const char* a1 = cA + (size_t)(t + 1) * kstep;
;             const char* a2 = last ? nA : cA + (size_t)(t + 2) * kstep; const char* b2 = last ? nB : cB + (size_t)(t + 2) * kstep;
;             const char* a3 = a2 + kstep; const char* b3 = b2 + kstep;
;             if (last && has_next) S.a_ready(nxt);
;             if constexpr (SP2) {
;             PG8_LDB(B0, 0, 0); PG8_LDB(B1, 0, 1); PG8_SCHED; PG8_LDA(At, 0, 0); PG8_STAGE(PG8_SA(1, 1), a1 + hstepA, voffA);
;             PG8_WAIT_V(8); PG8_WAIT_L(0); PG8_BAR; PG8_MMA(0, 0, At, B0); PG8_MMA(0, 1, At, B1); PG8_BAR; PG8_SCHED;
;             PG8_LDA(At, 0, 1); PG8_STAGE(PG8_SB(0, 0), b2, voffB); PG8_STAGE(PG8_SB(0, 1), b2 + hstepB, voffB); PG8_STAGE(PG8_SA(0, 0), a2, voffA);
;             PG8_WAIT_V(8); PG8_WAIT_L(0); PG8_BAR; PG8_MMA(1, 0, At, B0); PG8_MMA(1, 1, At, B1); PG8_BAR; PG8_SCHED;
;             PG8_LDB(B0, 1, 0); PG8_LDB(B1, 1, 1); PG8_SCHED; PG8_LDA(At, 1, 0); PG8_STAGE(PG8_SA(0, 1), a2 + hstepA, voffA);
;             PG8_WAIT_V(8); PG8_WAIT_L(0); PG8_BAR; PG8_MMA(0, 0, At, B0); PG8_MMA(0, 1, At, B1); PG8_BAR; PG8_SCHED;
;             PG8_LDA(At, 1, 1); PG8_STAGE(PG8_SB(1, 0), b3, voffB); PG8_STAGE(PG8_SB(1, 1), b3 + hstepB, voffB); PG8_STAGE(PG8_SA(1, 0), a3, voffA);
;             PG8_WAIT_V(8); PG8_WAIT_L(0); PG8_BAR; PG8_MMA(1, 0, At, B0); PG8_MMA(1, 1, At, B1); PG8_BAR; PG8_SCHED;
	s_add_i32 s52, 0, 0x18000
	s_add_i32 s53, 0, 0x1c000
	v_add_u32_e32 v142, s52, v1
	v_add_u32_e32 v158, s53, v1
	ds_read_b128 v[130:133], v142
	ds_read_b128 v[134:137], v142 offset:1024
	ds_read_b128 v[138:141], v142 offset:2048
	ds_read_b128 v[142:145], v142 offset:3072
	ds_read_b128 v[146:149], v158
	ds_read_b128 v[150:153], v158 offset:1024
	ds_read_b128 v[154:157], v158 offset:2048
	ds_read_b128 v[158:161], v158 offset:3072
	s_add_u32 s30, s30, 0x400000
	s_addc_u32 s31, s31, 0
	s_mov_b32 m0, s40
	ds_read_b128 v[162:165], v194 offset:32768
	ds_read_b128 v[166:169], v194 offset:33792
	ds_read_b128 v[182:185], v194 offset:34816
	ds_read_b128 v[186:189], v194 offset:35840
	ds_read_b128 v[196:199], v194 offset:36864
	ds_read_b128 v[200:203], v194 offset:37888
	ds_read_b128 v[204:207], v194 offset:38912
	ds_read_b128 v[208:211], v194 offset:39936
	global_load_lds_dwordx4 v170, s[30:31]
	s_mov_b32 m0, s41
	s_nop 0
	global_load_lds_dwordx4 v172, s[30:31]
	s_waitcnt vmcnt(8)
	s_waitcnt lgkmcnt(0)
	s_barrier
	s_waitcnt lgkmcnt(0)
	v_mfma_f32_16x16x32_bf16 v[126:129], v[130:133], v[162:165], v[126:129]
	v_mfma_f32_16x16x32_bf16 v[122:125], v[138:141], v[162:165], v[122:125]
	v_mfma_f32_16x16x32_bf16 v[110:113], v[130:133], v[182:185], v[110:113]
	v_mfma_f32_16x16x32_bf16 v[106:109], v[138:141], v[182:185], v[106:109]
	v_mfma_f32_16x16x32_bf16 v[94:97], v[130:133], v[196:199], v[94:97]
	v_mfma_f32_16x16x32_bf16 v[90:93], v[138:141], v[196:199], v[90:93]
	v_mfma_f32_16x16x32_bf16 v[78:81], v[130:133], v[204:207], v[78:81]
	v_mfma_f32_16x16x32_bf16 v[74:77], v[138:141], v[204:207], v[74:77]
	v_mfma_f32_16x16x32_bf16 v[126:129], v[134:137], v[166:169], v[126:129]
	v_mfma_f32_16x16x32_bf16 v[122:125], v[142:145], v[166:169], v[122:125]
	v_mfma_f32_16x16x32_bf16 v[110:113], v[134:137], v[186:189], v[110:113]
	v_mfma_f32_16x16x32_bf16 v[106:109], v[142:145], v[186:189], v[106:109]
	v_mfma_f32_16x16x32_bf16 v[94:97], v[134:137], v[200:203], v[94:97]
	v_mfma_f32_16x16x32_bf16 v[90:93], v[142:145], v[200:203], v[90:93]
	v_mfma_f32_16x16x32_bf16 v[78:81], v[134:137], v[208:211], v[78:81]
	v_mfma_f32_16x16x32_bf16 v[74:77], v[142:145], v[208:211], v[74:77]
	v_mfma_f32_16x16x32_bf16 v[118:121], v[146:149], v[162:165], v[118:121]
	v_mfma_f32_16x16x32_bf16 v[114:117], v[154:157], v[162:165], v[114:117]
	v_mfma_f32_16x16x32_bf16 v[102:105], v[146:149], v[182:185], v[102:105]
	v_mfma_f32_16x16x32_bf16 v[98:101], v[154:157], v[182:185], v[98:101]
	v_mfma_f32_16x16x32_bf16 v[86:89], v[146:149], v[196:199], v[86:89]
	v_mfma_f32_16x16x32_bf16 v[82:85], v[154:157], v[196:199], v[82:85]
	v_mfma_f32_16x16x32_bf16 v[70:73], v[146:149], v[204:207], v[70:73]
	v_mfma_f32_16x16x32_bf16 v[66:69], v[154:157], v[204:207], v[66:69]
	v_mfma_f32_16x16x32_bf16 v[118:121], v[150:153], v[166:169], v[118:121]
	v_mfma_f32_16x16x32_bf16 v[114:117], v[158:161], v[166:169], v[114:117]
	v_mfma_f32_16x16x32_bf16 v[102:105], v[150:153], v[186:189], v[102:105]
	v_mfma_f32_16x16x32_bf16 v[98:101], v[158:161], v[186:189], v[98:101]
	v_mfma_f32_16x16x32_bf16 v[86:89], v[150:153], v[200:203], v[86:89]
	v_mfma_f32_16x16x32_bf16 v[82:85], v[158:161], v[200:203], v[82:85]
	v_mfma_f32_16x16x32_bf16 v[70:73], v[150:153], v[208:211], v[70:73]
	v_mfma_f32_16x16x32_bf16 v[66:69], v[158:161], v[208:211], v[66:69]
	s_barrier
	s_add_i32 s30, s52, s33
	s_add_i32 m0, s30, 0xffffff80
	ds_read_b128 v[162:165], v194 offset:49152
	ds_read_b128 v[166:169], v194 offset:50176
	ds_read_b128 v[182:185], v194 offset:51200
	ds_read_b128 v[186:189], v194 offset:52224
	ds_read_b128 v[196:199], v194 offset:53248
	ds_read_b128 v[200:203], v194 offset:54272
	ds_read_b128 v[204:207], v194 offset:55296
	ds_read_b128 v[208:211], v194 offset:56320
	global_load_lds_dwordx4 v170, s[98:99] offset:128
	s_add_i32 m0, s30, 0x1f80
	s_add_u32 s28, s28, 0x400080
	s_addc_u32 s29, s29, 0
	s_add_i32 s30, s53, s33
	global_load_lds_dwordx4 v172, s[98:99] offset:128
	s_mov_b32 m0, s30
	s_nop 0
	global_load_lds_dwordx4 v170, s[28:29]
	s_add_i32 m0, s30, 0x2000
	s_nop 0
	global_load_lds_dwordx4 v172, s[28:29]
	s_add_i32 m0, s43, 0xffffff80
	s_nop 0
	global_load_lds_dwordx4 v170, s[100:101] offset:128
	s_add_i32 m0, s44, 0xffffff80
	s_nop 0
	global_load_lds_dwordx4 v172, s[100:101] offset:128
	s_waitcnt vmcnt(8)
	s_waitcnt lgkmcnt(0)
	s_barrier
	s_waitcnt lgkmcnt(0)
	v_mfma_f32_16x16x32_bf16 v[62:65], v[130:133], v[162:165], v[62:65]
	v_mfma_f32_16x16x32_bf16 v[58:61], v[138:141], v[162:165], v[58:61]
	v_mfma_f32_16x16x32_bf16 v[46:49], v[130:133], v[182:185], v[46:49]
	v_mfma_f32_16x16x32_bf16 v[42:45], v[138:141], v[182:185], v[42:45]
	v_mfma_f32_16x16x32_bf16 v[30:33], v[130:133], v[196:199], v[30:33]
	v_mfma_f32_16x16x32_bf16 v[26:29], v[138:141], v[196:199], v[26:29]
	v_mfma_f32_16x16x32_bf16 v[22:25], v[130:133], v[204:207], v[22:25]
	v_mfma_f32_16x16x32_bf16 v[10:13], v[138:141], v[204:207], v[10:13]
	v_mfma_f32_16x16x32_bf16 v[62:65], v[134:137], v[166:169], v[62:65]
	v_mfma_f32_16x16x32_bf16 v[58:61], v[142:145], v[166:169], v[58:61]
	v_mfma_f32_16x16x32_bf16 v[46:49], v[134:137], v[186:189], v[46:49]
	v_mfma_f32_16x16x32_bf16 v[42:45], v[142:145], v[186:189], v[42:45]
	v_mfma_f32_16x16x32_bf16 v[30:33], v[134:137], v[200:203], v[30:33]
	v_mfma_f32_16x16x32_bf16 v[26:29], v[142:145], v[200:203], v[26:29]
	v_mfma_f32_16x16x32_bf16 v[22:25], v[134:137], v[208:211], v[22:25]
	v_mfma_f32_16x16x32_bf16 v[10:13], v[142:145], v[208:211], v[10:13]
	v_mfma_f32_16x16x32_bf16 v[54:57], v[146:149], v[162:165], v[54:57]
	v_mfma_f32_16x16x32_bf16 v[50:53], v[154:157], v[162:165], v[50:53]
	v_mfma_f32_16x16x32_bf16 v[38:41], v[146:149], v[182:185], v[38:41]
	v_mfma_f32_16x16x32_bf16 v[34:37], v[154:157], v[182:185], v[34:37]
	v_mfma_f32_16x16x32_bf16 v[18:21], v[146:149], v[196:199], v[18:21]
	v_mfma_f32_16x16x32_bf16 v[14:17], v[154:157], v[196:199], v[14:17]
	v_mfma_f32_16x16x32_bf16 v[6:9], v[146:149], v[204:207], v[6:9]
	v_mfma_f32_16x16x32_bf16 v[2:5], v[154:157], v[204:207], v[2:5]
	v_mfma_f32_16x16x32_bf16 v[54:57], v[150:153], v[166:169], v[54:57]
	v_mfma_f32_16x16x32_bf16 v[50:53], v[158:161], v[166:169], v[50:53]
	v_mfma_f32_16x16x32_bf16 v[38:41], v[150:153], v[186:189], v[38:41]
	v_mfma_f32_16x16x32_bf16 v[34:37], v[158:161], v[186:189], v[34:37]
	v_mfma_f32_16x16x32_bf16 v[18:21], v[150:153], v[200:203], v[18:21]
	v_mfma_f32_16x16x32_bf16 v[14:17], v[158:161], v[200:203], v[14:17]
	v_mfma_f32_16x16x32_bf16 v[6:9], v[150:153], v[208:211], v[6:9]
	v_mfma_f32_16x16x32_bf16 v[2:5], v[158:161], v[208:211], v[2:5]
	s_barrier
	s_add_i32 s51, s51, 2
	s_add_u32 s8, s8, 0x100
	s_addc_u32 s9, s9, 0
	s_add_u32 s49, s49, 0x100
	s_addc_u32 s50, s50, 0
	s_cmpk_gt_u32 s51, 0xfd
	s_cbranch_scc0 .LBB0_2092
	s_and_b64 vcc, exec, s[16:17]
	s_cbranch_vccz .LBB0_2095
	s_barrier

; #define PG8_STAGE(bufoff, gbase, voff) do { _Pragma("unroll") for (int _i = 0; _i < 2; ++_i) \
;         __builtin_amdgcn_global_load_lds((const unsigned*)((const char*)(gbase) + (voff)[_i]), (PG8_LAS unsigned*)(lds + (bufoff) + ldsw + _i * 8192), 16, 0, 0); } while (0)
; #define PG8_LDA(dst, b, h) do { _Pragma("unroll") for (int m = 0; m < 4; ++m) _Pragma("unroll") for (int k = 0; k < 2; ++k) dst[m][k] = *(const PG8_LAS bf16x8*)(lds + PG8_SA(b, h) + aoff + m * 2048 + k * 1024); } while (0)
; #define PG8_LDB(dst, b, h) do { _Pragma("unroll") for (int n = 0; n < 2; ++n) _Pragma("unroll") for (int k = 0; k < 2; ++k) dst[n][k] = *(const PG8_LAS bf16x8*)(lds + PG8_SB(b, h) + boff + n * 2048 + k * 1024); } while (0)
; #define PG8_MMA(ai, bj, At, Bt) do { __builtin_amdgcn_s_setprio(1); _Pragma("unroll") for (int m = 0; m < 4; ++m) _Pragma("unroll") for (int n = 0; n < 2; ++n) _Pragma("unroll") for (int k = 0; k < 2; ++k) \
;         acc[ai][bj][m][n] = mma_<I8>(Bt[n][k], At[m][k], acc[ai][bj][m][n]); __builtin_amdgcn_s_setprio(0); } while (0)
; #define PG8_WAIT_V(n) asm volatile("s_waitcnt vmcnt(" #n ")" ::: "memory")
; #define PG8_WAIT_L(n) asm volatile("s_waitcnt lgkmcnt(" #n ")" ::: "memory")
; #define PG8_BAR __builtin_amdgcn_s_barrier()
; template <class Epi, class Sched, bool ALIGN_EPI = false, bool SP2 = false, bool I8 = false>
; __device__ __forceinline__ void gemm_phase(PG8_LAS unsigned char* lds, const Gemm g, const Sched& S, const Epi& E) {
;     ...
;             const bool last = (t == nt - 2);
;             const char* a1 = cA + (size_t)(t + 1) * kstep;
;             const char* a2 = last ? nA : cA + (size_t)(t + 2) * kstep; const char* b2 = last ? nB : cB + (size_t)(t + 2) * kstep;
;             const char* a3 = a2 + kstep; const char* b3 = b2 + kstep;
;             if (last && has_next) S.a_ready(nxt);
;             if constexpr (SP2) {
;             PG8_LDB(B0, 0, 0); PG8_LDB(B1, 0, 1); PG8_SCHED; PG8_LDA(At, 0, 0); PG8_STAGE(PG8_SA(1, 1), a1 + hstepA, voffA);
;             PG8_WAIT_V(8); PG8_WAIT_L(0); PG8_BAR; PG8_MMA(0, 0, At, B0); PG8_MMA(0, 1, At, B1); PG8_BAR; PG8_SCHED;
;             PG8_LDA(At, 0, 1); PG8_STAGE(PG8_SB(0, 0), b2, voffB); PG8_STAGE(PG8_SB(0, 1), b2 + hstepB, voffB); PG8_STAGE(PG8_SA(0, 0), a2, voffA);
;             PG8_WAIT_V(8); PG8_WAIT_L(0); PG8_BAR; PG8_MMA(1, 0, At, B0); PG8_MMA(1, 1, At, B1); PG8_BAR; PG8_SCHED;
.LBB0_2322:
	ds_read_b128 v[58:61], v183
	ds_read_b128 v[66:69], v183 offset:1024
	ds_read_b128 v[74:77], v183 offset:2048
	ds_read_b128 v[78:81], v183 offset:3072
	ds_read_b128 v[146:149], v189
	ds_read_b128 v[150:153], v189 offset:1024
	ds_read_b128 v[154:157], v189 offset:2048
	ds_read_b128 v[158:161], v189 offset:3072
	s_add_u32 s28, s26, 0xfff80080
	s_addc_u32 s29, s27, -1
	s_cmp_eq_u32 s53, 28
	s_cselect_b32 s31, s21, s29
	s_cselect_b32 s30, s49, s28
	s_cselect_b32 s29, s19, s52
	s_cselect_b32 s28, s50, s51
	s_add_i32 m0, s3, 0xc000
	ds_read_b128 v[162:165], v193
	ds_read_b128 v[178:181], v193 offset:1024
	ds_read_b128 v[184:187], v193 offset:2048
	ds_read_b128 v[198:201], v193 offset:3072
	ds_read_b128 v[202:205], v193 offset:4096
	ds_read_b128 v[206:209], v193 offset:5120
	ds_read_b128 v[210:213], v193 offset:6144
	ds_read_b128 v[214:217], v193 offset:7168
	global_load_lds_dwordx4 v170, s[26:27]
	s_add_i32 m0, s3, 0xe000
	s_nop 0
	global_load_lds_dwordx4 v172, s[26:27]
	s_waitcnt vmcnt(8)
	s_waitcnt lgkmcnt(0)
	s_barrier
	s_waitcnt lgkmcnt(0)
	v_mfma_i32_16x16x64_i8 v[142:145], v[58:61], v[162:165], v[142:145]
	v_mfma_i32_16x16x64_i8 v[138:141], v[74:77], v[162:165], v[138:141]
	v_mfma_i32_16x16x64_i8 v[126:129], v[58:61], v[184:187], v[126:129]
	v_mfma_i32_16x16x64_i8 v[122:125], v[74:77], v[184:187], v[122:125]
	v_mfma_i32_16x16x64_i8 v[110:113], v[58:61], v[202:205], v[110:113]
	v_mfma_i32_16x16x64_i8 v[106:109], v[74:77], v[202:205], v[106:109]
	v_mfma_i32_16x16x64_i8 v[94:97], v[58:61], v[210:213], v[94:97]
	v_mfma_i32_16x16x64_i8 v[90:93], v[74:77], v[210:213], v[90:93]
	v_mfma_i32_16x16x64_i8 v[142:145], v[66:69], v[178:181], v[142:145]
	v_mfma_i32_16x16x64_i8 v[138:141], v[78:81], v[178:181], v[138:141]
	v_mfma_i32_16x16x64_i8 v[126:129], v[66:69], v[198:201], v[126:129]
	v_mfma_i32_16x16x64_i8 v[122:125], v[78:81], v[198:201], v[122:125]
	v_mfma_i32_16x16x64_i8 v[110:113], v[66:69], v[206:209], v[110:113]
	v_mfma_i32_16x16x64_i8 v[106:109], v[78:81], v[206:209], v[106:109]
	v_mfma_i32_16x16x64_i8 v[94:97], v[66:69], v[214:217], v[94:97]
	v_mfma_i32_16x16x64_i8 v[90:93], v[78:81], v[214:217], v[90:93]
	v_mfma_i32_16x16x64_i8 v[134:137], v[146:149], v[162:165], v[134:137]
	v_mfma_i32_16x16x64_i8 v[130:133], v[154:157], v[162:165], v[130:133]
	v_mfma_i32_16x16x64_i8 v[118:121], v[146:149], v[184:187], v[118:121]
	v_mfma_i32_16x16x64_i8 v[114:117], v[154:157], v[184:187], v[114:117]
	v_mfma_i32_16x16x64_i8 v[102:105], v[146:149], v[202:205], v[102:105]
	v_mfma_i32_16x16x64_i8 v[98:101], v[154:157], v[202:205], v[98:101]
	v_mfma_i32_16x16x64_i8 v[86:89], v[146:149], v[210:213], v[86:89]
	v_mfma_i32_16x16x64_i8 v[82:85], v[154:157], v[210:213], v[82:85]
	v_mfma_i32_16x16x64_i8 v[134:137], v[150:153], v[178:181], v[134:137]
	v_mfma_i32_16x16x64_i8 v[130:133], v[158:161], v[178:181], v[130:133]
	v_mfma_i32_16x16x64_i8 v[118:121], v[150:153], v[198:201], v[118:121]
	v_mfma_i32_16x16x64_i8 v[114:117], v[158:161], v[198:201], v[114:117]
	v_mfma_i32_16x16x64_i8 v[102:105], v[150:153], v[206:209], v[102:105]
	v_mfma_i32_16x16x64_i8 v[98:101], v[158:161], v[206:209], v[98:101]
	v_mfma_i32_16x16x64_i8 v[86:89], v[150:153], v[214:217], v[86:89]
	v_mfma_i32_16x16x64_i8 v[82:85], v[158:161], v[214:217], v[82:85]
	s_barrier
	s_add_i32 s54, s46, s38
	s_mov_b64 s[98:99], s[28:29]
	s_mov_b32 m0, s54
	ds_read_b128 v[162:165], v193 offset:16384
	ds_read_b128 v[178:181], v193 offset:17408
	ds_read_b128 v[184:187], v193 offset:18432
	ds_read_b128 v[198:201], v193 offset:19456
	ds_read_b128 v[202:205], v193 offset:20480
	ds_read_b128 v[206:209], v193 offset:21504
	ds_read_b128 v[210:213], v193 offset:22528
	ds_read_b128 v[214:217], v193 offset:23552
	global_load_lds_dwordx4 v166, s[28:29]
	s_add_i32 m0, s54, 0x2000
	s_add_u32 s54, s28, 0x80000
	s_mov_b64 s[98:99], s[28:29]
	s_addc_u32 s55, s29, 0
	s_add_i32 s56, s47, s38
	global_load_lds_dwordx4 v168, s[28:29]
	s_mov_b32 m0, s56
	s_mov_b64 s[100:101], s[30:31]
	global_load_lds_dwordx4 v166, s[54:55]
	s_add_i32 m0, s56, 0x2000
	s_nop 0
	global_load_lds_dwordx4 v168, s[54:55]
	s_mov_b64 s[100:101], s[30:31]
	s_mov_b32 m0, s3
	s_nop 0
	global_load_lds_dwordx4 v166, s[30:31]
	s_mov_b32 m0, s39
	s_nop 0
	global_load_lds_dwordx4 v168, s[30:31]
	s_waitcnt vmcnt(8)
	s_waitcnt lgkmcnt(0)
	s_barrier
	s_waitcnt lgkmcnt(0)
	v_mfma_i32_16x16x64_i8 v[70:73], v[58:61], v[162:165], v[70:73]
	v_mfma_i32_16x16x64_i8 v[62:65], v[74:77], v[162:165], v[62:65]
	v_mfma_i32_16x16x64_i8 v[46:49], v[58:61], v[184:187], v[46:49]
	v_mfma_i32_16x16x64_i8 v[42:45], v[74:77], v[184:187], v[42:45]
	v_mfma_i32_16x16x64_i8 v[30:33], v[58:61], v[202:205], v[30:33]
	v_mfma_i32_16x16x64_i8 v[26:29], v[74:77], v[202:205], v[26:29]
	v_mfma_i32_16x16x64_i8 v[14:17], v[58:61], v[210:213], v[14:17]
	v_mfma_i32_16x16x64_i8 v[10:13], v[74:77], v[210:213], v[10:13]
	v_mfma_i32_16x16x64_i8 v[70:73], v[66:69], v[178:181], v[70:73]
	v_mfma_i32_16x16x64_i8 v[62:65], v[78:81], v[178:181], v[62:65]
	v_mfma_i32_16x16x64_i8 v[46:49], v[66:69], v[198:201], v[46:49]
	v_mfma_i32_16x16x64_i8 v[42:45], v[78:81], v[198:201], v[42:45]
	v_mfma_i32_16x16x64_i8 v[30:33], v[66:69], v[206:209], v[30:33]
	v_mfma_i32_16x16x64_i8 v[26:29], v[78:81], v[206:209], v[26:29]
	v_mfma_i32_16x16x64_i8 v[14:17], v[66:69], v[214:217], v[14:17]
	v_mfma_i32_16x16x64_i8 v[10:13], v[78:81], v[214:217], v[10:13]
	v_mfma_i32_16x16x64_i8 v[54:57], v[146:149], v[162:165], v[54:57]
	v_mfma_i32_16x16x64_i8 v[50:53], v[154:157], v[162:165], v[50:53]
	v_mfma_i32_16x16x64_i8 v[38:41], v[146:149], v[184:187], v[38:41]
	v_mfma_i32_16x16x64_i8 v[34:37], v[154:157], v[184:187], v[34:37]
	v_mfma_i32_16x16x64_i8 v[22:25], v[146:149], v[202:205], v[22:25]
	v_mfma_i32_16x16x64_i8 v[18:21], v[154:157], v[202:205], v[18:21]
	v_mfma_i32_16x16x64_i8 v[6:9], v[146:149], v[210:213], v[6:9]
	v_mfma_i32_16x16x64_i8 v[2:5], v[154:157], v[210:213], v[2:5]
	v_mfma_i32_16x16x64_i8 v[54:57], v[150:153], v[178:181], v[54:57]
	v_mfma_i32_16x16x64_i8 v[50:53], v[158:161], v[178:181], v[50:53]
	v_mfma_i32_16x16x64_i8 v[38:41], v[150:153], v[198:201], v[38:41]
	v_mfma_i32_16x16x64_i8 v[34:37], v[158:161], v[198:201], v[34:37]
	v_mfma_i32_16x16x64_i8 v[22:25], v[150:153], v[206:209], v[22:25]
	v_mfma_i32_16x16x64_i8 v[18:21], v[158:161], v[206:209], v[18:21]
	v_mfma_i32_16x16x64_i8 v[6:9], v[150:153], v[214:217], v[6:9]
	v_mfma_i32_16x16x64_i8 v[2:5], v[158:161], v[214:217], v[2:5]
	s_barrier
; #define PG8_STAGE(bufoff, gbase, voff) do { _Pragma("unroll") for (int _i = 0; _i < 2; ++_i) \
;         __builtin_amdgcn_global_load_lds((const unsigned*)((const char*)(gbase) + (voff)[_i]), (PG8_LAS unsigned*)(lds + (bufoff) + ldsw + _i * 8192), 16, 0, 0); } while (0)
; #define PG8_LDA(dst, b, h) do { _Pragma("unroll") for (int m = 0; m < 4; ++m) _Pragma("unroll") for (int k = 0; k < 2; ++k) dst[m][k] = *(const PG8_LAS bf16x8*)(lds + PG8_SA(b, h) + aoff + m * 2048 + k * 1024); } while (0)
; #define PG8_WAIT_V(n) asm volatile("s_waitcnt vmcnt(" #n ")" ::: "memory")
; #define PG8_WAIT_L(n) asm volatile("s_waitcnt lgkmcnt(" #n ")" ::: "memory")
; #define PG8_BAR __builtin_amdgcn_s_barrier()
; template <class Epi, class Sched, bool ALIGN_EPI = false, bool SP2 = false, bool I8 = false>
; __device__ __forceinline__ void gemm_phase(PG8_LAS unsigned char* lds, const Gemm g, const Sched& S, const Epi& E) {
;     ...
;         for (int t = 0; t < nt; t += 2) {
;             const bool last = (t == nt - 2);
;             const char* a1 = cA + (size_t)(t + 1) * kstep;
;             const char* a2 = last ? nA : cA + (size_t)(t + 2) * kstep; const char* b2 = last ? nB : cB + (size_t)(t + 2) * kstep;
;             const char* a3 = a2 + kstep; const char* b3 = b2 + kstep;
;             if (last && has_next) S.a_ready(nxt);
;             if constexpr (SP2) {
;             PG8_LDB(B0, 0, 0); PG8_LDB(B1, 0, 1); PG8_SCHED; PG8_LDA(At, 0, 0); PG8_STAGE(PG8_SA(1, 1), a1 + hstepA, voffA);
;             PG8_WAIT_V(8); PG8_WAIT_L(0); PG8_BAR; PG8_MMA(0, 0, At, B0); PG8_MMA(0, 1, At, B1); PG8_BAR; PG8_SCHED;
;             PG8_LDA(At, 0, 1); PG8_STAGE(PG8_SB(0, 0), b2, voffB); PG8_STAGE(PG8_SB(0, 1), b2 + hstepB, voffB); PG8_STAGE(PG8_SA(0, 0), a2, voffA);
;             PG8_WAIT_V(8); PG8_WAIT_L(0); PG8_BAR; PG8_MMA(1, 0, At, B0); PG8_MMA(1, 1, At, B1); PG8_BAR; PG8_SCHED;
;             PG8_LDB(B0, 1, 0); PG8_LDB(B1, 1, 1); PG8_SCHED; PG8_LDA(At, 1, 0); PG8_STAGE(PG8_SA(0, 1), a2 + hstepA, voffA);
;             PG8_WAIT_V(8); PG8_WAIT_L(0); PG8_BAR; PG8_MMA(0, 0, At, B0); PG8_MMA(0, 1, At, B1); PG8_BAR; PG8_SCHED;
;             PG8_LDA(At, 1, 1); PG8_STAGE(PG8_SB(1, 0), b3, voffB); PG8_STAGE(PG8_SB(1, 1), b3 + hstepB, voffB); PG8_STAGE(PG8_SA(1, 0), a3, voffA);
;             PG8_WAIT_V(8); PG8_WAIT_L(0); PG8_BAR; PG8_MMA(1, 0, At, B0); PG8_MMA(1, 1, At, B1); PG8_BAR; PG8_SCHED;
	s_add_i32 s54, 0, 0x18000
	s_add_i32 s55, 0, 0x1c000
	v_add_u32_e32 v78, s54, v1
	v_add_u32_e32 v158, s55, v1
	ds_read_b128 v[58:61], v78
	ds_read_b128 v[66:69], v78 offset:1024
	ds_read_b128 v[74:77], v78 offset:2048
	ds_read_b128 v[78:81], v78 offset:3072
	ds_read_b128 v[146:149], v158
	ds_read_b128 v[150:153], v158 offset:1024
	ds_read_b128 v[154:157], v158 offset:2048
	ds_read_b128 v[158:161], v158 offset:3072
	s_add_u32 s30, s30, 0x80000
	s_addc_u32 s31, s31, 0
	s_mov_b32 m0, s40
	ds_read_b128 v[162:165], v193 offset:32768
	ds_read_b128 v[178:181], v193 offset:33792
	ds_read_b128 v[184:187], v193 offset:34816
	ds_read_b128 v[198:201], v193 offset:35840
	ds_read_b128 v[202:205], v193 offset:36864
	ds_read_b128 v[206:209], v193 offset:37888
	ds_read_b128 v[210:213], v193 offset:38912
	ds_read_b128 v[214:217], v193 offset:39936
	global_load_lds_dwordx4 v166, s[30:31]
	s_mov_b32 m0, s41
	s_nop 0
	global_load_lds_dwordx4 v168, s[30:31]
	s_waitcnt vmcnt(8)
	s_waitcnt lgkmcnt(0)
	s_barrier
	s_waitcnt lgkmcnt(0)
	v_mfma_i32_16x16x64_i8 v[142:145], v[58:61], v[162:165], v[142:145]
	v_mfma_i32_16x16x64_i8 v[138:141], v[74:77], v[162:165], v[138:141]
	v_mfma_i32_16x16x64_i8 v[126:129], v[58:61], v[184:187], v[126:129]
	v_mfma_i32_16x16x64_i8 v[122:125], v[74:77], v[184:187], v[122:125]
	v_mfma_i32_16x16x64_i8 v[110:113], v[58:61], v[202:205], v[110:113]
	v_mfma_i32_16x16x64_i8 v[106:109], v[74:77], v[202:205], v[106:109]
	v_mfma_i32_16x16x64_i8 v[94:97], v[58:61], v[210:213], v[94:97]
	v_mfma_i32_16x16x64_i8 v[90:93], v[74:77], v[210:213], v[90:93]
	v_mfma_i32_16x16x64_i8 v[142:145], v[66:69], v[178:181], v[142:145]
	v_mfma_i32_16x16x64_i8 v[138:141], v[78:81], v[178:181], v[138:141]
	v_mfma_i32_16x16x64_i8 v[126:129], v[66:69], v[198:201], v[126:129]
	v_mfma_i32_16x16x64_i8 v[122:125], v[78:81], v[198:201], v[122:125]
	v_mfma_i32_16x16x64_i8 v[110:113], v[66:69], v[206:209], v[110:113]
	v_mfma_i32_16x16x64_i8 v[106:109], v[78:81], v[206:209], v[106:109]
	v_mfma_i32_16x16x64_i8 v[94:97], v[66:69], v[214:217], v[94:97]
	v_mfma_i32_16x16x64_i8 v[90:93], v[78:81], v[214:217], v[90:93]
	v_mfma_i32_16x16x64_i8 v[134:137], v[146:149], v[162:165], v[134:137]
	v_mfma_i32_16x16x64_i8 v[130:133], v[154:157], v[162:165], v[130:133]
	v_mfma_i32_16x16x64_i8 v[118:121], v[146:149], v[184:187], v[118:121]
	v_mfma_i32_16x16x64_i8 v[114:117], v[154:157], v[184:187], v[114:117]
	v_mfma_i32_16x16x64_i8 v[102:105], v[146:149], v[202:205], v[102:105]
	v_mfma_i32_16x16x64_i8 v[98:101], v[154:157], v[202:205], v[98:101]
	v_mfma_i32_16x16x64_i8 v[86:89], v[146:149], v[210:213], v[86:89]
	v_mfma_i32_16x16x64_i8 v[82:85], v[154:157], v[210:213], v[82:85]
	v_mfma_i32_16x16x64_i8 v[134:137], v[150:153], v[178:181], v[134:137]
	v_mfma_i32_16x16x64_i8 v[130:133], v[158:161], v[178:181], v[130:133]
	v_mfma_i32_16x16x64_i8 v[118:121], v[150:153], v[198:201], v[118:121]
	v_mfma_i32_16x16x64_i8 v[114:117], v[158:161], v[198:201], v[114:117]
	v_mfma_i32_16x16x64_i8 v[102:105], v[150:153], v[206:209], v[102:105]
	v_mfma_i32_16x16x64_i8 v[98:101], v[158:161], v[206:209], v[98:101]
	v_mfma_i32_16x16x64_i8 v[86:89], v[150:153], v[214:217], v[86:89]
	v_mfma_i32_16x16x64_i8 v[82:85], v[158:161], v[214:217], v[82:85]
	s_barrier
	s_add_i32 s30, s54, s38
	s_add_i32 m0, s30, 0xffffff80
	ds_read_b128 v[162:165], v193 offset:49152
	ds_read_b128 v[178:181], v193 offset:50176
	ds_read_b128 v[184:187], v193 offset:51200
	ds_read_b128 v[198:201], v193 offset:52224
	ds_read_b128 v[202:205], v193 offset:53248
	ds_read_b128 v[206:209], v193 offset:54272
	ds_read_b128 v[210:213], v193 offset:55296
	ds_read_b128 v[214:217], v193 offset:56320
	global_load_lds_dwordx4 v166, s[98:99] offset:128
	s_add_i32 m0, s30, 0x1f80
	s_add_u32 s28, s28, 0x80080
	s_addc_u32 s29, s29, 0
	s_add_i32 s30, s55, s38
	global_load_lds_dwordx4 v168, s[98:99] offset:128
	s_mov_b32 m0, s30
	s_nop 0
	global_load_lds_dwordx4 v166, s[28:29]
	s_add_i32 m0, s30, 0x2000
	s_nop 0
	global_load_lds_dwordx4 v168, s[28:29]
	s_add_i32 m0, s43, 0xffffff80
	s_nop 0
	global_load_lds_dwordx4 v166, s[100:101] offset:128
	s_add_i32 m0, s44, 0xffffff80
	s_nop 0
	global_load_lds_dwordx4 v168, s[100:101] offset:128
	s_waitcnt vmcnt(8)
	s_waitcnt lgkmcnt(0)
	s_barrier
	s_waitcnt lgkmcnt(0)
	v_mfma_i32_16x16x64_i8 v[70:73], v[58:61], v[162:165], v[70:73]
	v_mfma_i32_16x16x64_i8 v[62:65], v[74:77], v[162:165], v[62:65]
	v_mfma_i32_16x16x64_i8 v[46:49], v[58:61], v[184:187], v[46:49]
	v_mfma_i32_16x16x64_i8 v[42:45], v[74:77], v[184:187], v[42:45]
	v_mfma_i32_16x16x64_i8 v[30:33], v[58:61], v[202:205], v[30:33]
	v_mfma_i32_16x16x64_i8 v[26:29], v[74:77], v[202:205], v[26:29]
	v_mfma_i32_16x16x64_i8 v[14:17], v[58:61], v[210:213], v[14:17]
	v_mfma_i32_16x16x64_i8 v[10:13], v[74:77], v[210:213], v[10:13]
	v_mfma_i32_16x16x64_i8 v[70:73], v[66:69], v[178:181], v[70:73]
	v_mfma_i32_16x16x64_i8 v[62:65], v[78:81], v[178:181], v[62:65]
	v_mfma_i32_16x16x64_i8 v[46:49], v[66:69], v[198:201], v[46:49]
	v_mfma_i32_16x16x64_i8 v[42:45], v[78:81], v[198:201], v[42:45]
	v_mfma_i32_16x16x64_i8 v[30:33], v[66:69], v[206:209], v[30:33]
	v_mfma_i32_16x16x64_i8 v[26:29], v[78:81], v[206:209], v[26:29]
	v_mfma_i32_16x16x64_i8 v[14:17], v[66:69], v[214:217], v[14:17]
	v_mfma_i32_16x16x64_i8 v[10:13], v[78:81], v[214:217], v[10:13]
	v_mfma_i32_16x16x64_i8 v[54:57], v[146:149], v[162:165], v[54:57]
	v_mfma_i32_16x16x64_i8 v[50:53], v[154:157], v[162:165], v[50:53]
	v_mfma_i32_16x16x64_i8 v[38:41], v[146:149], v[184:187], v[38:41]
	v_mfma_i32_16x16x64_i8 v[34:37], v[154:157], v[184:187], v[34:37]
	v_mfma_i32_16x16x64_i8 v[22:25], v[146:149], v[202:205], v[22:25]
	v_mfma_i32_16x16x64_i8 v[18:21], v[154:157], v[202:205], v[18:21]
	v_mfma_i32_16x16x64_i8 v[6:9], v[146:149], v[210:213], v[6:9]
	v_mfma_i32_16x16x64_i8 v[2:5], v[154:157], v[210:213], v[2:5]
	v_mfma_i32_16x16x64_i8 v[54:57], v[150:153], v[178:181], v[54:57]
	v_mfma_i32_16x16x64_i8 v[50:53], v[158:161], v[178:181], v[50:53]
	v_mfma_i32_16x16x64_i8 v[38:41], v[150:153], v[198:201], v[38:41]
	v_mfma_i32_16x16x64_i8 v[34:37], v[158:161], v[198:201], v[34:37]
	v_mfma_i32_16x16x64_i8 v[22:25], v[150:153], v[206:209], v[22:25]
	v_mfma_i32_16x16x64_i8 v[18:21], v[158:161], v[206:209], v[18:21]
	v_mfma_i32_16x16x64_i8 v[6:9], v[150:153], v[214:217], v[6:9]
	v_mfma_i32_16x16x64_i8 v[2:5], v[158:161], v[214:217], v[2:5]
	s_barrier
	s_add_i32 s53, s53, 2
	s_add_u32 s26, s26, 0x100
	s_addc_u32 s27, s27, 0
	s_add_u32 s51, s51, 0x100
	s_addc_u32 s52, s52, 0
	s_cmp_gt_u32 s53, 29
	s_cbranch_scc0 .LBB0_2322
	s_and_b64 vcc, exec, s[16:17]
	s_cbranch_vccz .LBB0_2325
	s_barrier
